# plus: redundant accumulator zeroing removed, first K-tile peeled with SrcC=0, incremental next-unit index math in UP0/IN/UP1 headers
# speedup vs baseline: 1.0401x; 1.0241x over previous
;     __device__ __forceinline__ size_t a_off(const Unit& u) const { return (size_t)u.pm * atile; }
;     __device__ __forceinline__ size_t b_off(const Unit& u) const { return (size_t)u.pn * btile; }
;     __device__ __forceinline__ bool next(int i, Unit& u) const { const long L = (long)i * G + c; if (L >= NG * 8) return false; u.g = (int)(L >> 3); u.pm = (int)(L & 7); u.pn = 0; return true; }
;     __device__ __forceinline__ size_t a_off(const Unit& u) const { return ((size_t)u.g * NROW + (size_t)u.pm * BM) * KA * 2; }
;     __device__ __forceinline__ size_t b_off(const Unit& u) const { return (size_t)u.g * btile; }
;     __device__ __forceinline__ bool next(int i, Unit& u) const { if (i >= 2) return false; u.g = g; u.pm = 2 * b + i; u.pn = 0; return true; }
;     __device__ __forceinline__ size_t a_off(const Unit& u) const { return ((size_t)u.g * NROW + (size_t)u.pm * BM) * KA * 2; }
;     ...
;     f32x4 acc[2][2][4][2];
; #pragma unroll
;     for (int a = 0; a < 2; ++a)
; #pragma unroll
;         for (int b = 0; b < 2; ++b)
; #pragma unroll
;             for (int m = 0; m < 4; ++m)
; #pragma unroll
;                 for (int n = 0; n < 2; ++n) acc[a][b][m][n] = (f32x4){0.f, 0.f, 0.f, 0.f};
;     ...
;     for (;;) {
;         const bool has_next = S.next(ui + 1, nxt);
;         const char* nA = has_next ? (const char*)Ap + S.a_off(nxt) : cA; const char* nB = has_next ? (const char*)Btp + S.b_off(nxt) : cB;
;         for (int t = 0; t < nt; t += 2) {
;             const bool last = (t == nt - 2);
;             const char* a1 = cA + (size_t)(t + 1) * kstep;
;             const char* a2 = last ? nA : cA + (size_t)(t + 2) * kstep; const char* b2 = last ? nB : cB + (size_t)(t + 2) * kstep;
;             const char* a3 = a2 + kstep; const char* b3 = b2 + kstep;
;             PG8_LDB(B0, 0, 0); PG8_SCHED; PG8_LDA(At, 0, 0); PG8_STAGE(PG8_SA(1, 1), a1 + hstepA, voffA);
;             PG8_WAIT_L(8); PG8_BAR; PG8_WAIT_L(0); PG8_MMA(0, 0, At, B0); PG8_BAR; PG8_SCHED;
;             PG8_LDB(B1, 0, 1); PG8_STAGE(PG8_SB(0, 0), b2, voffB);
;             PG8_BAR; PG8_WAIT_L(0); PG8_MMA(0, 1, At, B1); PG8_BAR;
;             PG8_LDA(At, 0, 1); PG8_STAGE(PG8_SA(0, 0), a2, voffA);
;             PG8_BAR; PG8_WAIT_L(0); PG8_MMA(1, 0, At, B0); PG8_BAR; PG8_SCHED;
;             PG8_STAGE(PG8_SB(0, 1), b2 + hstepB, voffB);
;             PG8_WAIT_V(6); PG8_BAR; PG8_MMA(1, 1, At, B1); PG8_BAR;
.LBB0_505:
	s_andn2_b64 vcc, exec, s[52:53]
	s_cbranch_vccnz .Lkzero_507
	s_add_u32 s17, s36, 0x100
	s_addc_u32 s22, s37, 0
	s_add_u32 s8, s36, s6
	s_addc_u32 s9, s37, s7
	s_add_u32 s23, s8, 0x80
	s_addc_u32 s24, s9, 0
	s_mov_b32 s26, 0
	s_mov_b64 s[8:9], 0
	s_add_i32 s25, s26, 2
	s_add_u32 s72, s8, 0x100
	s_addc_u32 s73, s9, 0
	s_add_u32 s27, s17, s8
	ds_read_b128 v[76:79], v73
	ds_read_b128 v[80:83], v73 offset:1024
	ds_read_b128 v[84:87], v73 offset:2048
	ds_read_b128 v[88:91], v73 offset:3072
	s_addc_u32 s28, s22, s9
	s_cmp_eq_u32 s93, s26
	s_cselect_b32 s64, s58, s27
	s_cselect_b32 s26, s59, s28
	s_cselect_b32 s27, 0, s73
	s_cselect_b32 s28, 0, s72
	s_add_u32 s36, s64, 0x80
	s_addc_u32 s29, s26, 0
	s_add_u32 s44, s4, s28
	s_addc_u32 s27, s82, s27
	s_add_u32 s8, s23, s8
	s_addc_u32 s9, s24, s9
	s_and_b32 s9, s9, 0xffff
	s_mov_b32 m0, s31
	ds_read_b128 v[92:95], v74
	ds_read_b128 v[96:99], v74 offset:1024
	ds_read_b128 v[100:103], v74 offset:2048
	ds_read_b128 v[104:107], v74 offset:3072
	ds_read_b128 v[108:111], v74 offset:4096
	ds_read_b128 v[112:115], v74 offset:5120
	ds_read_b128 v[116:119], v74 offset:6144
	ds_read_b128 v[120:123], v74 offset:7168
	buffer_load_dwordx4 v67, s[8:11], 0 offen lds
	s_mov_b32 m0, s74
	s_nop 0
	buffer_load_dwordx4 v71, s[8:11], 0 offen lds
	s_waitcnt lgkmcnt(8)
	s_barrier
	s_waitcnt lgkmcnt(0)
	s_setprio 1
	s_waitcnt lgkmcnt(7)
	v_mfma_f32_16x16x32_bf16 v[60:63], v[76:79], v[92:95], 0
	v_mfma_f32_16x16x32_bf16 v[56:59], v[84:87], v[92:95], 0
	s_waitcnt lgkmcnt(5)
	v_mfma_f32_16x16x32_bf16 v[52:55], v[76:79], v[100:103], 0
	v_mfma_f32_16x16x32_bf16 v[48:51], v[84:87], v[100:103], 0
	s_waitcnt lgkmcnt(3)
	v_mfma_f32_16x16x32_bf16 v[44:47], v[76:79], v[108:111], 0
	v_mfma_f32_16x16x32_bf16 v[40:43], v[84:87], v[108:111], 0
	s_waitcnt lgkmcnt(1)
	v_mfma_f32_16x16x32_bf16 v[36:39], v[76:79], v[116:119], 0
	v_mfma_f32_16x16x32_bf16 v[32:35], v[84:87], v[116:119], 0
	v_mfma_f32_16x16x32_bf16 v[60:63], v[80:83], v[96:99], v[60:63]
	v_mfma_f32_16x16x32_bf16 v[56:59], v[88:91], v[96:99], v[56:59]
	v_mfma_f32_16x16x32_bf16 v[52:55], v[80:83], v[104:107], v[52:55]
	v_mfma_f32_16x16x32_bf16 v[48:51], v[88:91], v[104:107], v[48:51]
	v_mfma_f32_16x16x32_bf16 v[44:47], v[80:83], v[112:115], v[44:47]
	v_mfma_f32_16x16x32_bf16 v[40:43], v[88:91], v[112:115], v[40:43]
	s_waitcnt lgkmcnt(0)
	v_mfma_f32_16x16x32_bf16 v[36:39], v[80:83], v[120:123], v[36:39]
	v_mfma_f32_16x16x32_bf16 v[32:35], v[88:91], v[120:123], v[32:35]
	s_setprio 0
	s_barrier
	s_and_b32 s45, s27, 0xffff
	s_mov_b32 s46, s10
	s_mov_b32 s47, s11
	s_mov_b32 m0, s84
	s_nop 0
	buffer_load_dwordx4 v70, s[44:47], 0 offen lds
	s_mov_b32 m0, s86
	s_nop 0
	buffer_load_dwordx4 v72, s[44:47], 0 offen lds
	s_barrier
	s_waitcnt lgkmcnt(0)
	s_setprio 1
	s_setprio 0
	s_and_b32 s65, s26, 0xffff
	s_mov_b32 s66, s10
	s_mov_b32 s67, s11
	s_mov_b32 m0, s75
	s_barrier
	ds_read_b128 v[92:95], v74 offset:16384
	ds_read_b128 v[96:99], v74 offset:17408
	ds_read_b128 v[100:103], v74 offset:18432
	ds_read_b128 v[104:107], v74 offset:19456
	ds_read_b128 v[108:111], v74 offset:20480
	ds_read_b128 v[112:115], v74 offset:21504
	ds_read_b128 v[116:119], v74 offset:22528
	ds_read_b128 v[120:123], v74 offset:23552
	buffer_load_dwordx4 v67, s[64:67], 0 offen lds
	s_mov_b32 m0, s5
	s_nop 0
	buffer_load_dwordx4 v71, s[64:67], 0 offen lds
	s_barrier
	s_waitcnt lgkmcnt(0)
	s_setprio 1
	s_waitcnt lgkmcnt(7)
	v_mfma_f32_16x16x32_bf16 v[28:31], v[76:79], v[92:95], 0
	v_mfma_f32_16x16x32_bf16 v[24:27], v[84:87], v[92:95], 0
	s_waitcnt lgkmcnt(5)
	v_mfma_f32_16x16x32_bf16 v[20:23], v[76:79], v[100:103], 0
	v_mfma_f32_16x16x32_bf16 v[16:19], v[84:87], v[100:103], 0
	s_waitcnt lgkmcnt(3)
	v_mfma_f32_16x16x32_bf16 v[12:15], v[76:79], v[108:111], 0
	v_mfma_f32_16x16x32_bf16 v[8:11], v[84:87], v[108:111], 0
	s_waitcnt lgkmcnt(1)
	v_mfma_f32_16x16x32_bf16 v[4:7], v[76:79], v[116:119], 0
	v_mfma_f32_16x16x32_bf16 v[0:3], v[84:87], v[116:119], 0
	v_mfma_f32_16x16x32_bf16 v[28:31], v[80:83], v[96:99], v[28:31]
	v_mfma_f32_16x16x32_bf16 v[24:27], v[88:91], v[96:99], v[24:27]
	v_mfma_f32_16x16x32_bf16 v[20:23], v[80:83], v[104:107], v[20:23]
	v_mfma_f32_16x16x32_bf16 v[16:19], v[88:91], v[104:107], v[16:19]
	v_mfma_f32_16x16x32_bf16 v[12:15], v[80:83], v[112:115], v[12:15]
	v_mfma_f32_16x16x32_bf16 v[8:11], v[88:91], v[112:115], v[8:11]
	s_waitcnt lgkmcnt(0)
	v_mfma_f32_16x16x32_bf16 v[4:7], v[80:83], v[120:123], v[4:7]
	v_mfma_f32_16x16x32_bf16 v[0:3], v[88:91], v[120:123], v[0:3]
	s_setprio 0
	s_barrier
	s_add_u32 s8, s44, s50
	s_addc_u32 s28, s27, s51
	s_and_b32 s9, s28, 0xffff
	s_mov_b32 m0, s87
	s_nop 0
	buffer_load_dwordx4 v70, s[8:11], 0 offen lds
	s_mov_b32 m0, s89
	s_nop 0
	buffer_load_dwordx4 v72, s[8:11], 0 offen lds
	s_waitcnt vmcnt(6)
	s_barrier
	s_setprio 1
	s_setprio 0
	s_barrier
	s_branch .Lkmid_507

; #define PG8_STAGE(bufoff, gbase, voff) do { const __amdgpu_buffer_rsrc_t _r = __builtin_amdgcn_make_buffer_rsrc((void*)(gbase), (short)0, 0x7fffffff, 0x00020000); _Pragma("unroll") for (int _i = 0; _i < 2; ++_i) \
;         __builtin_amdgcn_raw_ptr_buffer_load_lds(_r, (LAS unsigned*)(lds + (bufoff) + ldsw + _i * 8192), 16, (int)(voff)[_i], 0, 0, 0); } while (0)
; #define PG8_LDA(dst, b, h) do { _Pragma("unroll") for (int m = 0; m < 4; ++m) _Pragma("unroll") for (int k = 0; k < 2; ++k) dst[m][k] = *(const LAS bf16x8*)(lds + PG8_SA(b, h) + aoff + m * 2048 + k * 1024); } while (0)
; #define PG8_LDB(dst, b, h) do { _Pragma("unroll") for (int n = 0; n < 2; ++n) _Pragma("unroll") for (int k = 0; k < 2; ++k) dst[n][k] = *(const LAS bf16x8*)(lds + PG8_SB(b, h) + boff + n * 2048 + k * 1024); } while (0)
; #define PG8_MMA(ai, bj, At, Bt) do { __builtin_amdgcn_s_setprio(1); _Pragma("unroll") for (int k = 0; k < 2; ++k) _Pragma("unroll") for (int m = 0; m < 4; ++m) _Pragma("unroll") for (int n = 0; n < ((bj) == 1 ? NB1 : 2); ++n) \
;         acc[ai][bj][m][n] = __builtin_amdgcn_mfma_f32_16x16x32_bf16(Bt[n][k], At[m][k], acc[ai][bj][m][n], 0, 0, 0); __builtin_amdgcn_s_setprio(0); } while (0)
; #define PG8_WAIT_V(n) asm volatile("s_waitcnt vmcnt(" #n ")" ::: "memory")
; #define PG8_WAIT_L(n) asm volatile("s_waitcnt lgkmcnt(" #n ")" ::: "memory")
; #define PG8_BAR __builtin_amdgcn_s_barrier()
; #define PG8_SCHED __builtin_amdgcn_sched_barrier(0)
;     ...
;             PG8_LDB(B0, 1, 0); PG8_SCHED; PG8_LDA(At, 1, 0); PG8_STAGE(PG8_SA(0, 1), a2 + hstepA, voffA);
;             PG8_WAIT_L(8); PG8_BAR; PG8_WAIT_L(0); PG8_MMA(0, 0, At, B0); PG8_BAR; PG8_SCHED;
;             PG8_LDB(B1, 1, 1); PG8_STAGE(PG8_SB(1, 0), b3, voffB);
;             PG8_BAR; PG8_WAIT_L(0); PG8_MMA(0, 1, At, B1); PG8_BAR;
;             PG8_LDA(At, 1, 1); PG8_STAGE(PG8_SA(1, 0), a3, voffA);
;             PG8_BAR; PG8_WAIT_L(0); PG8_MMA(1, 0, At, B0); PG8_BAR; PG8_SCHED;
;             PG8_STAGE(PG8_SB(1, 1), b3 + hstepB, voffB);
;             PG8_WAIT_V(6); PG8_BAR; PG8_MMA(1, 1, At, B1); PG8_BAR;
;         }
.Lkmid_507:
	ds_read_b128 v[76:79], v75
	ds_read_b128 v[80:83], v75 offset:1024
	ds_read_b128 v[84:87], v75 offset:2048
	ds_read_b128 v[88:91], v75 offset:3072
	s_add_u32 s64, s64, s6
	s_addc_u32 s9, s26, s7
	s_and_b32 s65, s9, 0xffff
	s_mov_b32 m0, s83
	ds_read_b128 v[92:95], v74 offset:32768
	ds_read_b128 v[96:99], v74 offset:33792
	ds_read_b128 v[100:103], v74 offset:34816
	ds_read_b128 v[104:107], v74 offset:35840
	ds_read_b128 v[108:111], v74 offset:36864
	ds_read_b128 v[112:115], v74 offset:37888
	ds_read_b128 v[116:119], v74 offset:38912
	ds_read_b128 v[120:123], v74 offset:39936
	buffer_load_dwordx4 v67, s[64:67], 0 offen lds
	s_mov_b32 m0, s90
	s_nop 0
	buffer_load_dwordx4 v71, s[64:67], 0 offen lds
	s_waitcnt lgkmcnt(8)
	s_barrier
	s_waitcnt lgkmcnt(0)
	s_setprio 1
	s_waitcnt lgkmcnt(7)
	v_mfma_f32_16x16x32_bf16 v[60:63], v[76:79], v[92:95], v[60:63]
	v_mfma_f32_16x16x32_bf16 v[56:59], v[84:87], v[92:95], v[56:59]
	s_waitcnt lgkmcnt(5)
	v_mfma_f32_16x16x32_bf16 v[52:55], v[76:79], v[100:103], v[52:55]
	v_mfma_f32_16x16x32_bf16 v[48:51], v[84:87], v[100:103], v[48:51]
	s_waitcnt lgkmcnt(3)
	v_mfma_f32_16x16x32_bf16 v[44:47], v[76:79], v[108:111], v[44:47]
	v_mfma_f32_16x16x32_bf16 v[40:43], v[84:87], v[108:111], v[40:43]
	s_waitcnt lgkmcnt(1)
	v_mfma_f32_16x16x32_bf16 v[36:39], v[76:79], v[116:119], v[36:39]
	v_mfma_f32_16x16x32_bf16 v[32:35], v[84:87], v[116:119], v[32:35]
	v_mfma_f32_16x16x32_bf16 v[60:63], v[80:83], v[96:99], v[60:63]
	v_mfma_f32_16x16x32_bf16 v[56:59], v[88:91], v[96:99], v[56:59]
	v_mfma_f32_16x16x32_bf16 v[52:55], v[80:83], v[104:107], v[52:55]
	v_mfma_f32_16x16x32_bf16 v[48:51], v[88:91], v[104:107], v[48:51]
	v_mfma_f32_16x16x32_bf16 v[44:47], v[80:83], v[112:115], v[44:47]
	v_mfma_f32_16x16x32_bf16 v[40:43], v[88:91], v[112:115], v[40:43]
	s_waitcnt lgkmcnt(0)
	v_mfma_f32_16x16x32_bf16 v[36:39], v[80:83], v[120:123], v[36:39]
	v_mfma_f32_16x16x32_bf16 v[32:35], v[88:91], v[120:123], v[32:35]
	s_setprio 0
	s_barrier
	s_add_u32 s44, s44, 0x80
	s_addc_u32 s9, s27, 0
	s_and_b32 s45, s9, 0xffff
	s_mov_b32 m0, s92
	s_nop 0
	buffer_load_dwordx4 v70, s[44:47], 0 offen lds
	s_mov_b32 m0, s97
	s_nop 0
	buffer_load_dwordx4 v72, s[44:47], 0 offen lds
	s_barrier
	s_waitcnt lgkmcnt(0)
	s_setprio 1
	s_setprio 0
	s_and_b32 s37, s29, 0xffff
	s_mov_b32 s38, s10
	s_mov_b32 s39, s11
	s_mov_b32 m0, s94
	s_barrier
	ds_read_b128 v[92:95], v74 offset:49152
	ds_read_b128 v[96:99], v74 offset:50176
	ds_read_b128 v[100:103], v74 offset:51200
	ds_read_b128 v[104:107], v74 offset:52224
	ds_read_b128 v[108:111], v74 offset:53248
	ds_read_b128 v[112:115], v74 offset:54272
	ds_read_b128 v[116:119], v74 offset:55296
	ds_read_b128 v[120:123], v74 offset:56320
	buffer_load_dwordx4 v67, s[36:39], 0 offen lds
	s_mov_b32 m0, s3
	s_nop 0
	buffer_load_dwordx4 v71, s[36:39], 0 offen lds
	s_barrier
	s_waitcnt lgkmcnt(0)
	s_setprio 1
	s_waitcnt lgkmcnt(7)
	v_mfma_f32_16x16x32_bf16 v[28:31], v[76:79], v[92:95], v[28:31]
	v_mfma_f32_16x16x32_bf16 v[24:27], v[84:87], v[92:95], v[24:27]
	s_waitcnt lgkmcnt(5)
	v_mfma_f32_16x16x32_bf16 v[20:23], v[76:79], v[100:103], v[20:23]
	v_mfma_f32_16x16x32_bf16 v[16:19], v[84:87], v[100:103], v[16:19]
	s_waitcnt lgkmcnt(3)
	v_mfma_f32_16x16x32_bf16 v[12:15], v[76:79], v[108:111], v[12:15]
	v_mfma_f32_16x16x32_bf16 v[8:11], v[84:87], v[108:111], v[8:11]
	s_waitcnt lgkmcnt(1)
	v_mfma_f32_16x16x32_bf16 v[4:7], v[76:79], v[116:119], v[4:7]
	v_mfma_f32_16x16x32_bf16 v[0:3], v[84:87], v[116:119], v[0:3]
	v_mfma_f32_16x16x32_bf16 v[28:31], v[80:83], v[96:99], v[28:31]
	v_mfma_f32_16x16x32_bf16 v[24:27], v[88:91], v[96:99], v[24:27]
	v_mfma_f32_16x16x32_bf16 v[20:23], v[80:83], v[104:107], v[20:23]
	v_mfma_f32_16x16x32_bf16 v[16:19], v[88:91], v[104:107], v[16:19]
	v_mfma_f32_16x16x32_bf16 v[12:15], v[80:83], v[112:115], v[12:15]
	v_mfma_f32_16x16x32_bf16 v[8:11], v[88:91], v[112:115], v[8:11]
	s_waitcnt lgkmcnt(0)
	v_mfma_f32_16x16x32_bf16 v[4:7], v[80:83], v[120:123], v[4:7]
	v_mfma_f32_16x16x32_bf16 v[0:3], v[88:91], v[120:123], v[0:3]
	s_setprio 0
	s_barrier
	s_add_u32 s8, s8, 0x80
	s_addc_u32 s9, s28, 0
	s_and_b32 s9, s9, 0xffff
	s_mov_b32 m0, s13
	s_nop 0
	buffer_load_dwordx4 v70, s[8:11], 0 offen lds
	s_mov_b32 m0, s14
	s_nop 0
	buffer_load_dwordx4 v72, s[8:11], 0 offen lds
	s_waitcnt vmcnt(6)
	s_barrier
	s_setprio 1
	s_setprio 0
	s_cmp_ge_i32 s25, s33
	s_mov_b64 s[8:9], s[72:73]
	s_mov_b32 s26, s25
	s_barrier
	s_cbranch_scc0 .LBB0_507
	s_branch .LBB0_502

;     __device__ __forceinline__ size_t a_off(const Unit& u) const { return (size_t)u.pm * atile; }
;     __device__ __forceinline__ size_t b_off(const Unit& u) const { return (size_t)u.pn * btile; }
;     __device__ __forceinline__ bool next(int i, Unit& u) const { const long L = (long)i * G + c; if (L >= NG * 8) return false; u.g = (int)(L >> 3); u.pm = (int)(L & 7); u.pn = 0; return true; }
;     __device__ __forceinline__ size_t a_off(const Unit& u) const { return ((size_t)u.g * NROW + (size_t)u.pm * BM) * KA * 2; }
;     __device__ __forceinline__ size_t b_off(const Unit& u) const { return (size_t)u.g * btile; }
;     __device__ __forceinline__ bool next(int i, Unit& u) const { if (i >= 2) return false; u.g = g; u.pm = 2 * b + i; u.pn = 0; return true; }
;     __device__ __forceinline__ size_t a_off(const Unit& u) const { return ((size_t)u.g * NROW + (size_t)u.pm * BM) * KA * 2; }
;     __device__ __forceinline__ size_t b_off(const Unit& u) const { return (size_t)u.g * btile; }
; #define PG8_LDA(dst, b, h) do { _Pragma("unroll") for (int m = 0; m < 4; ++m) _Pragma("unroll") for (int k = 0; k < 2; ++k) dst[m][k] = *(const LAS bf16x8*)(lds + PG8_SA(b, h) + aoff + m * 2048 + k * 1024); } while (0)
; #define PG8_WAIT_L(n) asm volatile("s_waitcnt lgkmcnt(" #n ")" ::: "memory")
;     ...
;     for (;;) {
;         const bool has_next = S.next(ui + 1, nxt);
;         const char* nA = has_next ? (const char*)Ap + S.a_off(nxt) : cA; const char* nB = has_next ? (const char*)Btp + S.b_off(nxt) : cB;
;         for (int t = 0; t < nt; t += 2) {
;             const bool last = (t == nt - 2);
;             const char* a1 = cA + (size_t)(t + 1) * kstep;
;             const char* a2 = last ? nA : cA + (size_t)(t + 2) * kstep; const char* b2 = last ? nB : cB + (size_t)(t + 2) * kstep;
;             const char* a3 = a2 + kstep; const char* b3 = b2 + kstep;
;             PG8_LDB(B0, 0, 0); PG8_SCHED; PG8_LDA(At, 0, 0); PG8_STAGE(PG8_SA(1, 1), a1 + hstepA, voffA);
;             PG8_WAIT_L(8); PG8_BAR; PG8_WAIT_L(0); PG8_MMA(0, 0, At, B0); PG8_BAR; PG8_SCHED;
;             PG8_LDB(B1, 0, 1); PG8_STAGE(PG8_SB(0, 0), b2, voffB);
;             PG8_BAR; PG8_WAIT_L(0); PG8_MMA(0, 1, At, B1); PG8_BAR;
;             PG8_LDA(At, 0, 1); PG8_STAGE(PG8_SA(0, 0), a2, voffA);
;             PG8_BAR; PG8_WAIT_L(0); PG8_MMA(1, 0, At, B0); PG8_BAR; PG8_SCHED;
.LBB0_573:
	s_andn2_b64 vcc, exec, s[20:21]
	s_cbranch_vccnz .Lkzero_575
	s_add_u32 s45, s26, 0x100
	s_addc_u32 s47, s27, 0
	s_add_u32 s51, s24, 0x100
	s_addc_u32 s81, s25, 0
	s_mov_b32 s8, 0
	ds_read_b128 v[96:99], v215
	ds_read_b128 v[100:103], v215 offset:1024
	ds_read_b128 v[136:139], v215 offset:2048
	ds_read_b128 v[140:143], v215 offset:3072
	s_add_i32 s16, s8, 2
	s_cmp_eq_u32 s90, s8
	s_cselect_b32 s36, s42, s45
	s_cselect_b32 s23, s43, s47
	s_cselect_b32 s22, s1, s81
	s_cselect_b32 s28, s0, s51
	s_add_u32 s24, s36, 0x80
	s_addc_u32 s17, s23, 0
	s_add_u32 s8, s45, s6
	s_addc_u32 s9, s47, s7
	s_add_u32 s8, s8, 0xffffff80
	s_addc_u32 s9, s9, -1
	s_and_b32 s9, s9, 0xffff
	s_mov_b32 m0, s76
	ds_read_b128 v[144:147], v216
	ds_read_b128 v[148:151], v216 offset:1024
	ds_read_b128 v[152:155], v216 offset:2048
	ds_read_b128 v[156:159], v216 offset:3072
	ds_read_b128 v[160:163], v216 offset:4096
	ds_read_b128 v[164:167], v216 offset:5120
	ds_read_b128 v[168:171], v216 offset:6144
	ds_read_b128 v[172:175], v216 offset:7168
	buffer_load_dwordx4 v210, s[8:11], 0 offen lds
	s_mov_b32 m0, s77
	s_nop 0
	buffer_load_dwordx4 v212, s[8:11], 0 offen lds
	s_waitcnt lgkmcnt(8)
	s_barrier
	s_waitcnt lgkmcnt(0)
	s_setprio 1
	s_waitcnt lgkmcnt(7)
	v_mfma_f32_16x16x32_bf16 v[132:135], v[96:99], v[144:147], 0
	v_mfma_f32_16x16x32_bf16 v[120:123], v[136:139], v[144:147], 0
	s_waitcnt lgkmcnt(5)
	v_mfma_f32_16x16x32_bf16 v[116:119], v[96:99], v[152:155], 0
	v_mfma_f32_16x16x32_bf16 v[112:115], v[136:139], v[152:155], 0
	s_waitcnt lgkmcnt(3)
	v_mfma_f32_16x16x32_bf16 v[92:95], v[96:99], v[160:163], 0
	v_mfma_f32_16x16x32_bf16 v[88:91], v[136:139], v[160:163], 0
	s_waitcnt lgkmcnt(1)
	v_mfma_f32_16x16x32_bf16 v[76:79], v[96:99], v[168:171], 0
	v_mfma_f32_16x16x32_bf16 v[72:75], v[136:139], v[168:171], 0
	v_mfma_f32_16x16x32_bf16 v[132:135], v[100:103], v[148:151], v[132:135]
	v_mfma_f32_16x16x32_bf16 v[120:123], v[140:143], v[148:151], v[120:123]
	v_mfma_f32_16x16x32_bf16 v[116:119], v[100:103], v[156:159], v[116:119]
	v_mfma_f32_16x16x32_bf16 v[112:115], v[140:143], v[156:159], v[112:115]
	v_mfma_f32_16x16x32_bf16 v[92:95], v[100:103], v[164:167], v[92:95]
	v_mfma_f32_16x16x32_bf16 v[88:91], v[140:143], v[164:167], v[88:91]
	s_waitcnt lgkmcnt(0)
	v_mfma_f32_16x16x32_bf16 v[76:79], v[100:103], v[172:175], v[76:79]
	v_mfma_f32_16x16x32_bf16 v[72:75], v[140:143], v[172:175], v[72:75]
	s_setprio 0
	s_barrier
	s_and_b32 s29, s22, 0xffff
	s_mov_b32 s30, s10
	s_mov_b32 s31, s11
	s_mov_b32 m0, s15
	ds_read_b128 v[176:179], v217
	ds_read_b128 v[194:197], v217 offset:1024
	ds_read_b128 v[198:201], v217 offset:2048
	ds_read_b128 v[202:205], v217 offset:3072
	buffer_load_dwordx4 v211, s[28:31], 0 offen lds
	s_mov_b32 m0, s33
	s_nop 0
	buffer_load_dwordx4 v213, s[28:31], 0 offen lds
	s_barrier
	s_waitcnt lgkmcnt(0)
	s_setprio 1
	s_waitcnt lgkmcnt(3)
	v_mfma_f32_16x16x32_bf16 v[128:131], v[176:179], v[144:147], 0
	s_waitcnt lgkmcnt(1)
	v_mfma_f32_16x16x32_bf16 v[124:127], v[198:201], v[144:147], 0
	v_mfma_f32_16x16x32_bf16 v[108:111], v[176:179], v[152:155], 0
	v_mfma_f32_16x16x32_bf16 v[104:107], v[198:201], v[152:155], 0
	v_mfma_f32_16x16x32_bf16 v[84:87], v[176:179], v[160:163], 0
	v_mfma_f32_16x16x32_bf16 v[80:83], v[198:201], v[160:163], 0
	v_mfma_f32_16x16x32_bf16 v[68:71], v[176:179], v[168:171], 0
	v_mfma_f32_16x16x32_bf16 v[64:67], v[198:201], v[168:171], 0
	v_mfma_f32_16x16x32_bf16 v[128:131], v[194:197], v[148:151], v[128:131]
	s_waitcnt lgkmcnt(0)
	v_mfma_f32_16x16x32_bf16 v[124:127], v[202:205], v[148:151], v[124:127]
	v_mfma_f32_16x16x32_bf16 v[108:111], v[194:197], v[156:159], v[108:111]
	v_mfma_f32_16x16x32_bf16 v[104:107], v[202:205], v[156:159], v[104:107]
	v_mfma_f32_16x16x32_bf16 v[84:87], v[194:197], v[164:167], v[84:87]
	v_mfma_f32_16x16x32_bf16 v[80:83], v[202:205], v[164:167], v[80:83]
	v_mfma_f32_16x16x32_bf16 v[68:71], v[194:197], v[172:175], v[68:71]
	v_mfma_f32_16x16x32_bf16 v[64:67], v[202:205], v[172:175], v[64:67]
	s_setprio 0
	s_and_b32 s37, s23, 0xffff
	s_mov_b32 s38, s10
	s_mov_b32 s39, s11
	s_mov_b32 m0, s14
	s_barrier
; #define PG8_STAGE(bufoff, gbase, voff) do { const __amdgpu_buffer_rsrc_t _r = __builtin_amdgcn_make_buffer_rsrc((void*)(gbase), (short)0, 0x7fffffff, 0x00020000); _Pragma("unroll") for (int _i = 0; _i < 2; ++_i) \
;         __builtin_amdgcn_raw_ptr_buffer_load_lds(_r, (LAS unsigned*)(lds + (bufoff) + ldsw + _i * 8192), 16, (int)(voff)[_i], 0, 0, 0); } while (0)
; #define PG8_LDA(dst, b, h) do { _Pragma("unroll") for (int m = 0; m < 4; ++m) _Pragma("unroll") for (int k = 0; k < 2; ++k) dst[m][k] = *(const LAS bf16x8*)(lds + PG8_SA(b, h) + aoff + m * 2048 + k * 1024); } while (0)
; #define PG8_MMA(ai, bj, At, Bt) do { __builtin_amdgcn_s_setprio(1); _Pragma("unroll") for (int k = 0; k < 2; ++k) _Pragma("unroll") for (int m = 0; m < 4; ++m) _Pragma("unroll") for (int n = 0; n < ((bj) == 1 ? NB1 : 2); ++n) \
;         acc[ai][bj][m][n] = __builtin_amdgcn_mfma_f32_16x16x32_bf16(Bt[n][k], At[m][k], acc[ai][bj][m][n], 0, 0, 0); __builtin_amdgcn_s_setprio(0); } while (0)
; #define PG8_WAIT_V(n) asm volatile("s_waitcnt vmcnt(" #n ")" ::: "memory")
; #define PG8_WAIT_L(n) asm volatile("s_waitcnt lgkmcnt(" #n ")" ::: "memory")
; #define PG8_BAR __builtin_amdgcn_s_barrier()
; #define PG8_SCHED __builtin_amdgcn_sched_barrier(0)
;     ...
;             PG8_LDA(At, 0, 1); PG8_STAGE(PG8_SA(0, 0), a2, voffA);
;             PG8_BAR; PG8_WAIT_L(0); PG8_MMA(1, 0, At, B0); PG8_BAR; PG8_SCHED;
;             PG8_STAGE(PG8_SB(0, 1), b2 + hstepB, voffB);
;             PG8_WAIT_V(6); PG8_BAR; PG8_MMA(1, 1, At, B1); PG8_BAR;
	ds_read_b128 v[144:147], v216 offset:16384
	ds_read_b128 v[148:151], v216 offset:17408
	ds_read_b128 v[152:155], v216 offset:18432
	ds_read_b128 v[156:159], v216 offset:19456
	ds_read_b128 v[160:163], v216 offset:20480
	ds_read_b128 v[164:167], v216 offset:21504
	ds_read_b128 v[168:171], v216 offset:22528
	ds_read_b128 v[172:175], v216 offset:23552
	buffer_load_dwordx4 v210, s[36:39], 0 offen lds
	s_mov_b32 m0, s35
	s_nop 0
	buffer_load_dwordx4 v212, s[36:39], 0 offen lds
	s_barrier
	s_waitcnt lgkmcnt(0)
	s_setprio 1
	s_waitcnt lgkmcnt(7)
	v_mfma_f32_16x16x32_bf16 v[60:63], v[96:99], v[144:147], 0
	v_mfma_f32_16x16x32_bf16 v[56:59], v[136:139], v[144:147], 0
	s_waitcnt lgkmcnt(5)
	v_mfma_f32_16x16x32_bf16 v[44:47], v[96:99], v[152:155], 0
	v_mfma_f32_16x16x32_bf16 v[40:43], v[136:139], v[152:155], 0
	s_waitcnt lgkmcnt(3)
	v_mfma_f32_16x16x32_bf16 v[28:31], v[96:99], v[160:163], 0
	v_mfma_f32_16x16x32_bf16 v[24:27], v[136:139], v[160:163], 0
	s_waitcnt lgkmcnt(1)
	v_mfma_f32_16x16x32_bf16 v[12:15], v[96:99], v[168:171], 0
	v_mfma_f32_16x16x32_bf16 v[8:11], v[136:139], v[168:171], 0
	v_mfma_f32_16x16x32_bf16 v[60:63], v[100:103], v[148:151], v[60:63]
	v_mfma_f32_16x16x32_bf16 v[56:59], v[140:143], v[148:151], v[56:59]
	v_mfma_f32_16x16x32_bf16 v[44:47], v[100:103], v[156:159], v[44:47]
	v_mfma_f32_16x16x32_bf16 v[40:43], v[140:143], v[156:159], v[40:43]
	v_mfma_f32_16x16x32_bf16 v[28:31], v[100:103], v[164:167], v[28:31]
	v_mfma_f32_16x16x32_bf16 v[24:27], v[140:143], v[164:167], v[24:27]
	s_waitcnt lgkmcnt(0)
	v_mfma_f32_16x16x32_bf16 v[12:15], v[100:103], v[172:175], v[12:15]
	v_mfma_f32_16x16x32_bf16 v[8:11], v[140:143], v[172:175], v[8:11]
	s_setprio 0
	s_barrier
	s_add_u32 s8, s28, s18
	s_addc_u32 s82, s22, s19
	s_and_b32 s9, s82, 0xffff
	s_mov_b32 m0, s52
	s_nop 0
	buffer_load_dwordx4 v211, s[8:11], 0 offen lds
	s_mov_b32 m0, s53
	s_nop 0
	buffer_load_dwordx4 v213, s[8:11], 0 offen lds
	s_waitcnt vmcnt(6)
	s_barrier
	s_setprio 1
	v_mfma_f32_16x16x32_bf16 v[52:55], v[176:179], v[144:147], 0
	v_mfma_f32_16x16x32_bf16 v[48:51], v[198:201], v[144:147], 0
	v_mfma_f32_16x16x32_bf16 v[36:39], v[176:179], v[152:155], 0
	v_mfma_f32_16x16x32_bf16 v[32:35], v[198:201], v[152:155], 0
	v_mfma_f32_16x16x32_bf16 v[20:23], v[176:179], v[160:163], 0
	v_mfma_f32_16x16x32_bf16 v[16:19], v[198:201], v[160:163], 0
	v_mfma_f32_16x16x32_bf16 v[4:7], v[176:179], v[168:171], 0
	v_mfma_f32_16x16x32_bf16 v[0:3], v[198:201], v[168:171], 0
	v_mfma_f32_16x16x32_bf16 v[52:55], v[194:197], v[148:151], v[52:55]
	v_mfma_f32_16x16x32_bf16 v[48:51], v[202:205], v[148:151], v[48:51]
	v_mfma_f32_16x16x32_bf16 v[36:39], v[194:197], v[156:159], v[36:39]
	v_mfma_f32_16x16x32_bf16 v[32:35], v[202:205], v[156:159], v[32:35]
	v_mfma_f32_16x16x32_bf16 v[20:23], v[194:197], v[164:167], v[20:23]
	v_mfma_f32_16x16x32_bf16 v[16:19], v[202:205], v[164:167], v[16:19]
	v_mfma_f32_16x16x32_bf16 v[4:7], v[194:197], v[172:175], v[4:7]
	v_mfma_f32_16x16x32_bf16 v[0:3], v[202:205], v[172:175], v[0:3]
	s_setprio 0
	s_barrier
	s_branch .Lkmid_575

; #define PG8_STAGE(bufoff, gbase, voff) do { const __amdgpu_buffer_rsrc_t _r = __builtin_amdgcn_make_buffer_rsrc((void*)(gbase), (short)0, 0x7fffffff, 0x00020000); _Pragma("unroll") for (int _i = 0; _i < 2; ++_i) \
;         __builtin_amdgcn_raw_ptr_buffer_load_lds(_r, (LAS unsigned*)(lds + (bufoff) + ldsw + _i * 8192), 16, (int)(voff)[_i], 0, 0, 0); } while (0)
; #define PG8_LDA(dst, b, h) do { _Pragma("unroll") for (int m = 0; m < 4; ++m) _Pragma("unroll") for (int k = 0; k < 2; ++k) dst[m][k] = *(const LAS bf16x8*)(lds + PG8_SA(b, h) + aoff + m * 2048 + k * 1024); } while (0)
; #define PG8_LDB(dst, b, h) do { _Pragma("unroll") for (int n = 0; n < 2; ++n) _Pragma("unroll") for (int k = 0; k < 2; ++k) dst[n][k] = *(const LAS bf16x8*)(lds + PG8_SB(b, h) + boff + n * 2048 + k * 1024); } while (0)
; #define PG8_MMA(ai, bj, At, Bt) do { __builtin_amdgcn_s_setprio(1); _Pragma("unroll") for (int k = 0; k < 2; ++k) _Pragma("unroll") for (int m = 0; m < 4; ++m) _Pragma("unroll") for (int n = 0; n < ((bj) == 1 ? NB1 : 2); ++n) \
;         acc[ai][bj][m][n] = __builtin_amdgcn_mfma_f32_16x16x32_bf16(Bt[n][k], At[m][k], acc[ai][bj][m][n], 0, 0, 0); __builtin_amdgcn_s_setprio(0); } while (0)
; #define PG8_WAIT_L(n) asm volatile("s_waitcnt lgkmcnt(" #n ")" ::: "memory")
; #define PG8_BAR __builtin_amdgcn_s_barrier()
; #define PG8_SCHED __builtin_amdgcn_sched_barrier(0)
;     ...
;             PG8_LDB(B0, 1, 0); PG8_SCHED; PG8_LDA(At, 1, 0); PG8_STAGE(PG8_SA(0, 1), a2 + hstepA, voffA);
;             PG8_WAIT_L(8); PG8_BAR; PG8_WAIT_L(0); PG8_MMA(0, 0, At, B0); PG8_BAR; PG8_SCHED;
;             PG8_LDB(B1, 1, 1); PG8_STAGE(PG8_SB(1, 0), b3, voffB);
;             PG8_BAR; PG8_WAIT_L(0); PG8_MMA(0, 1, At, B1); PG8_BAR;
.Lkmid_575:
	ds_read_b128 v[96:99], v218
	ds_read_b128 v[100:103], v218 offset:1024
	ds_read_b128 v[136:139], v218 offset:2048
	ds_read_b128 v[140:143], v218 offset:3072
	s_add_u32 s36, s36, s6
	s_addc_u32 s9, s23, s7
	s_and_b32 s37, s9, 0xffff
	s_mov_b32 m0, s58
	ds_read_b128 v[144:147], v216 offset:32768
	ds_read_b128 v[148:151], v216 offset:33792
	ds_read_b128 v[152:155], v216 offset:34816
	ds_read_b128 v[156:159], v216 offset:35840
	ds_read_b128 v[160:163], v216 offset:36864
	ds_read_b128 v[164:167], v216 offset:37888
	ds_read_b128 v[168:171], v216 offset:38912
	ds_read_b128 v[172:175], v216 offset:39936
	buffer_load_dwordx4 v210, s[36:39], 0 offen lds
	s_mov_b32 m0, s59
	s_nop 0
	buffer_load_dwordx4 v212, s[36:39], 0 offen lds
	s_waitcnt lgkmcnt(8)
	s_barrier
	s_waitcnt lgkmcnt(0)
	s_setprio 1
	s_waitcnt lgkmcnt(7)
	v_mfma_f32_16x16x32_bf16 v[132:135], v[96:99], v[144:147], v[132:135]
	v_mfma_f32_16x16x32_bf16 v[120:123], v[136:139], v[144:147], v[120:123]
	s_waitcnt lgkmcnt(5)
	v_mfma_f32_16x16x32_bf16 v[116:119], v[96:99], v[152:155], v[116:119]
	v_mfma_f32_16x16x32_bf16 v[112:115], v[136:139], v[152:155], v[112:115]
	s_waitcnt lgkmcnt(3)
	v_mfma_f32_16x16x32_bf16 v[92:95], v[96:99], v[160:163], v[92:95]
	v_mfma_f32_16x16x32_bf16 v[88:91], v[136:139], v[160:163], v[88:91]
	s_waitcnt lgkmcnt(1)
	v_mfma_f32_16x16x32_bf16 v[76:79], v[96:99], v[168:171], v[76:79]
	v_mfma_f32_16x16x32_bf16 v[72:75], v[136:139], v[168:171], v[72:75]
	v_mfma_f32_16x16x32_bf16 v[132:135], v[100:103], v[148:151], v[132:135]
	v_mfma_f32_16x16x32_bf16 v[120:123], v[140:143], v[148:151], v[120:123]
	v_mfma_f32_16x16x32_bf16 v[116:119], v[100:103], v[156:159], v[116:119]
	v_mfma_f32_16x16x32_bf16 v[112:115], v[140:143], v[156:159], v[112:115]
	v_mfma_f32_16x16x32_bf16 v[92:95], v[100:103], v[164:167], v[92:95]
	v_mfma_f32_16x16x32_bf16 v[88:91], v[140:143], v[164:167], v[88:91]
	s_waitcnt lgkmcnt(0)
	v_mfma_f32_16x16x32_bf16 v[76:79], v[100:103], v[172:175], v[76:79]
	v_mfma_f32_16x16x32_bf16 v[72:75], v[140:143], v[172:175], v[72:75]
	s_setprio 0
	s_barrier
	s_add_u32 s28, s28, 0x80
	s_addc_u32 s9, s22, 0
	s_and_b32 s29, s9, 0xffff
	s_mov_b32 m0, s48
	ds_read_b128 v[176:179], v219
	ds_read_b128 v[194:197], v219 offset:1024
	ds_read_b128 v[198:201], v219 offset:2048
	ds_read_b128 v[202:205], v219 offset:3072
	buffer_load_dwordx4 v211, s[28:31], 0 offen lds
	s_mov_b32 m0, s49
	s_nop 0
	buffer_load_dwordx4 v213, s[28:31], 0 offen lds
	s_barrier
	s_waitcnt lgkmcnt(0)
	s_setprio 1
	s_waitcnt lgkmcnt(3)
	v_mfma_f32_16x16x32_bf16 v[128:131], v[176:179], v[144:147], v[128:131]
	s_waitcnt lgkmcnt(1)
	v_mfma_f32_16x16x32_bf16 v[124:127], v[198:201], v[144:147], v[124:127]
	v_mfma_f32_16x16x32_bf16 v[108:111], v[176:179], v[152:155], v[108:111]
	v_mfma_f32_16x16x32_bf16 v[104:107], v[198:201], v[152:155], v[104:107]
	v_mfma_f32_16x16x32_bf16 v[84:87], v[176:179], v[160:163], v[84:87]
	v_mfma_f32_16x16x32_bf16 v[80:83], v[198:201], v[160:163], v[80:83]
	v_mfma_f32_16x16x32_bf16 v[68:71], v[176:179], v[168:171], v[68:71]
	v_mfma_f32_16x16x32_bf16 v[64:67], v[198:201], v[168:171], v[64:67]
	v_mfma_f32_16x16x32_bf16 v[128:131], v[194:197], v[148:151], v[128:131]
	s_waitcnt lgkmcnt(0)
	v_mfma_f32_16x16x32_bf16 v[124:127], v[202:205], v[148:151], v[124:127]
	v_mfma_f32_16x16x32_bf16 v[108:111], v[194:197], v[156:159], v[108:111]
	v_mfma_f32_16x16x32_bf16 v[104:107], v[202:205], v[156:159], v[104:107]
	v_mfma_f32_16x16x32_bf16 v[84:87], v[194:197], v[164:167], v[84:87]
	v_mfma_f32_16x16x32_bf16 v[80:83], v[202:205], v[164:167], v[80:83]
	v_mfma_f32_16x16x32_bf16 v[68:71], v[194:197], v[172:175], v[68:71]
	v_mfma_f32_16x16x32_bf16 v[64:67], v[202:205], v[172:175], v[64:67]
	s_setprio 0
	s_and_b32 s25, s17, 0xffff
	s_mov_b32 s26, s10
	s_mov_b32 s27, s11
	s_mov_b32 m0, s83
	s_barrier
; #define PG8_STAGE(bufoff, gbase, voff) do { const __amdgpu_buffer_rsrc_t _r = __builtin_amdgcn_make_buffer_rsrc((void*)(gbase), (short)0, 0x7fffffff, 0x00020000); _Pragma("unroll") for (int _i = 0; _i < 2; ++_i) \
;         __builtin_amdgcn_raw_ptr_buffer_load_lds(_r, (LAS unsigned*)(lds + (bufoff) + ldsw + _i * 8192), 16, (int)(voff)[_i], 0, 0, 0); } while (0)
; #define PG8_LDA(dst, b, h) do { _Pragma("unroll") for (int m = 0; m < 4; ++m) _Pragma("unroll") for (int k = 0; k < 2; ++k) dst[m][k] = *(const LAS bf16x8*)(lds + PG8_SA(b, h) + aoff + m * 2048 + k * 1024); } while (0)
; #define PG8_MMA(ai, bj, At, Bt) do { __builtin_amdgcn_s_setprio(1); _Pragma("unroll") for (int k = 0; k < 2; ++k) _Pragma("unroll") for (int m = 0; m < 4; ++m) _Pragma("unroll") for (int n = 0; n < ((bj) == 1 ? NB1 : 2); ++n) \
;         acc[ai][bj][m][n] = __builtin_amdgcn_mfma_f32_16x16x32_bf16(Bt[n][k], At[m][k], acc[ai][bj][m][n], 0, 0, 0); __builtin_amdgcn_s_setprio(0); } while (0)
; #define PG8_WAIT_V(n) asm volatile("s_waitcnt vmcnt(" #n ")" ::: "memory")
; #define PG8_WAIT_L(n) asm volatile("s_waitcnt lgkmcnt(" #n ")" ::: "memory")
; #define PG8_BAR __builtin_amdgcn_s_barrier()
; #define PG8_SCHED __builtin_amdgcn_sched_barrier(0)
;     ...
;             PG8_LDA(At, 1, 1); PG8_STAGE(PG8_SA(1, 0), a3, voffA);
;             PG8_BAR; PG8_WAIT_L(0); PG8_MMA(1, 0, At, B0); PG8_BAR; PG8_SCHED;
;             PG8_STAGE(PG8_SB(1, 1), b3 + hstepB, voffB);
;             PG8_WAIT_V(6); PG8_BAR; PG8_MMA(1, 1, At, B1); PG8_BAR;
;         }
	ds_read_b128 v[144:147], v216 offset:49152
	ds_read_b128 v[148:151], v216 offset:50176
	ds_read_b128 v[152:155], v216 offset:51200
	ds_read_b128 v[156:159], v216 offset:52224
	ds_read_b128 v[160:163], v216 offset:53248
	ds_read_b128 v[164:167], v216 offset:54272
	ds_read_b128 v[168:171], v216 offset:55296
	ds_read_b128 v[172:175], v216 offset:56320
	buffer_load_dwordx4 v210, s[24:27], 0 offen lds
	s_mov_b32 m0, s84
	s_nop 0
	buffer_load_dwordx4 v212, s[24:27], 0 offen lds
	s_barrier
	s_waitcnt lgkmcnt(0)
	s_setprio 1
	s_waitcnt lgkmcnt(7)
	v_mfma_f32_16x16x32_bf16 v[60:63], v[96:99], v[144:147], v[60:63]
	v_mfma_f32_16x16x32_bf16 v[56:59], v[136:139], v[144:147], v[56:59]
	s_waitcnt lgkmcnt(5)
	v_mfma_f32_16x16x32_bf16 v[44:47], v[96:99], v[152:155], v[44:47]
	v_mfma_f32_16x16x32_bf16 v[40:43], v[136:139], v[152:155], v[40:43]
	s_waitcnt lgkmcnt(3)
	v_mfma_f32_16x16x32_bf16 v[28:31], v[96:99], v[160:163], v[28:31]
	v_mfma_f32_16x16x32_bf16 v[24:27], v[136:139], v[160:163], v[24:27]
	s_waitcnt lgkmcnt(1)
	v_mfma_f32_16x16x32_bf16 v[12:15], v[96:99], v[168:171], v[12:15]
	v_mfma_f32_16x16x32_bf16 v[8:11], v[136:139], v[168:171], v[8:11]
	v_mfma_f32_16x16x32_bf16 v[60:63], v[100:103], v[148:151], v[60:63]
	v_mfma_f32_16x16x32_bf16 v[56:59], v[140:143], v[148:151], v[56:59]
	v_mfma_f32_16x16x32_bf16 v[44:47], v[100:103], v[156:159], v[44:47]
	v_mfma_f32_16x16x32_bf16 v[40:43], v[140:143], v[156:159], v[40:43]
	v_mfma_f32_16x16x32_bf16 v[28:31], v[100:103], v[164:167], v[28:31]
	v_mfma_f32_16x16x32_bf16 v[24:27], v[140:143], v[164:167], v[24:27]
	s_waitcnt lgkmcnt(0)
	v_mfma_f32_16x16x32_bf16 v[12:15], v[100:103], v[172:175], v[12:15]
	v_mfma_f32_16x16x32_bf16 v[8:11], v[140:143], v[172:175], v[8:11]
	s_setprio 0
	s_barrier
	s_add_u32 s8, s8, 0x80
	s_addc_u32 s9, s82, 0
	s_and_b32 s9, s9, 0xffff
	s_mov_b32 m0, s85
	s_nop 0
	buffer_load_dwordx4 v211, s[8:11], 0 offen lds
	s_mov_b32 m0, s86
	s_nop 0
	buffer_load_dwordx4 v213, s[8:11], 0 offen lds
	s_waitcnt vmcnt(6)
	s_barrier
	s_setprio 1
	v_mfma_f32_16x16x32_bf16 v[52:55], v[176:179], v[144:147], v[52:55]
	v_mfma_f32_16x16x32_bf16 v[48:51], v[198:201], v[144:147], v[48:51]
	v_mfma_f32_16x16x32_bf16 v[36:39], v[176:179], v[152:155], v[36:39]
	v_mfma_f32_16x16x32_bf16 v[32:35], v[198:201], v[152:155], v[32:35]
	v_mfma_f32_16x16x32_bf16 v[20:23], v[176:179], v[160:163], v[20:23]
	v_mfma_f32_16x16x32_bf16 v[16:19], v[198:201], v[160:163], v[16:19]
	v_mfma_f32_16x16x32_bf16 v[4:7], v[176:179], v[168:171], v[4:7]
	v_mfma_f32_16x16x32_bf16 v[0:3], v[198:201], v[168:171], v[0:3]
	v_mfma_f32_16x16x32_bf16 v[52:55], v[194:197], v[148:151], v[52:55]
	v_mfma_f32_16x16x32_bf16 v[48:51], v[202:205], v[148:151], v[48:51]
	v_mfma_f32_16x16x32_bf16 v[36:39], v[194:197], v[156:159], v[36:39]
	v_mfma_f32_16x16x32_bf16 v[32:35], v[202:205], v[156:159], v[32:35]
	v_mfma_f32_16x16x32_bf16 v[20:23], v[194:197], v[164:167], v[20:23]
	v_mfma_f32_16x16x32_bf16 v[16:19], v[202:205], v[164:167], v[16:19]
	v_mfma_f32_16x16x32_bf16 v[4:7], v[194:197], v[172:175], v[4:7]
	v_mfma_f32_16x16x32_bf16 v[0:3], v[202:205], v[172:175], v[0:3]
	s_setprio 0
	s_add_u32 s45, s45, 0x100
	s_addc_u32 s47, s47, 0
	s_add_u32 s51, s51, 0x100
	s_addc_u32 s81, s81, 0
	s_cmp_ge_i32 s16, s89
	s_mov_b32 s8, s16
	s_barrier
	s_cbranch_scc0 .LBB0_575
	s_branch .LBB0_568

;     __device__ __forceinline__ bool next(int i, Unit& u) const { const long L = (long)i * G + c; if (L >= NG * 8) return false; u.g = (int)(L >> 3); u.pm = (int)(L & 7); u.pn = 0; return true; }
;     __device__ __forceinline__ size_t a_off(const Unit& u) const { return ((size_t)u.g * NROW + (size_t)u.pm * BM) * KA * 2; }
;     __device__ __forceinline__ size_t b_off(const Unit& u) const { return (size_t)u.g * btile; }
;     __device__ __forceinline__ bool next(int i, Unit& u) const { if (i >= 2) return false; u.g = g; u.pm = 2 * b + i; u.pn = 0; return true; }
;     __device__ __forceinline__ size_t a_off(const Unit& u) const { return ((size_t)u.g * NROW + (size_t)u.pm * BM) * KA * 2; }
;     __device__ __forceinline__ size_t b_off(const Unit& u) const { return (size_t)u.g * btile; }
; #define PG8_LDA(dst, b, h) do { _Pragma("unroll") for (int m = 0; m < 4; ++m) _Pragma("unroll") for (int k = 0; k < 2; ++k) dst[m][k] = *(const LAS bf16x8*)(lds + PG8_SA(b, h) + aoff + m * 2048 + k * 1024); } while (0)
; #define PG8_WAIT_L(n) asm volatile("s_waitcnt lgkmcnt(" #n ")" ::: "memory")
;     __device__ __forceinline__ size_t a_off(const Unit& u) const { return (size_t)u.pm * atile; }
;     __device__ __forceinline__ size_t b_off(const Unit& u) const { return (size_t)u.pn * btile; }
;     ...
;     for (;;) {
;         const bool has_next = S.next(ui + 1, nxt);
;         const char* nA = has_next ? (const char*)Ap + S.a_off(nxt) : cA; const char* nB = has_next ? (const char*)Btp + S.b_off(nxt) : cB;
;         for (int t = 0; t < nt; t += 2) {
;             const bool last = (t == nt - 2);
;             const char* a1 = cA + (size_t)(t + 1) * kstep;
;             const char* a2 = last ? nA : cA + (size_t)(t + 2) * kstep; const char* b2 = last ? nB : cB + (size_t)(t + 2) * kstep;
;             const char* a3 = a2 + kstep; const char* b3 = b2 + kstep;
;             PG8_LDB(B0, 0, 0); PG8_SCHED; PG8_LDA(At, 0, 0); PG8_STAGE(PG8_SA(1, 1), a1 + hstepA, voffA);
;             PG8_WAIT_L(8); PG8_BAR; PG8_WAIT_L(0); PG8_MMA(0, 0, At, B0); PG8_BAR; PG8_SCHED;
;             PG8_LDB(B1, 0, 1); PG8_STAGE(PG8_SB(0, 0), b2, voffB);
;             PG8_BAR; PG8_WAIT_L(0); PG8_MMA(0, 1, At, B1); PG8_BAR;
;             PG8_LDA(At, 0, 1); PG8_STAGE(PG8_SA(0, 0), a2, voffA);
;             PG8_BAR; PG8_WAIT_L(0); PG8_MMA(1, 0, At, B0); PG8_BAR; PG8_SCHED;
.LBB0_625:
	s_ashr_i32 s97, s96, 31
	s_lshl_b64 s[8:9], s[96:97], 19
	s_add_u32 s68, s40, s8
	s_addc_u32 s69, s41, s9
	s_ashr_i32 s95, s94, 31
	s_lshl_b64 s[8:9], s[94:95], 19
	s_add_u32 s12, s3, s8
	v_cmp_lt_i64_e64 s[0:1], s[0:1], v[184:185]
	s_addc_u32 s13, s87, s9
	s_andn2_b64 vcc, exec, s[36:37]
	s_waitcnt lgkmcnt(0)
	s_cbranch_vccnz .Lkzero_627
	s_and_b64 s[0:1], s[0:1], exec
	s_cselect_b32 s0, s69, s27
	s_cselect_b32 s1, s68, s26
	s_cselect_b32 s47, s13, s25
	s_cselect_b32 s51, s12, s24
	s_add_u32 s89, s26, 0x100
	s_addc_u32 s90, s27, 0
	s_add_u32 s91, s24, 0x100
	s_mov_b64 s[44:45], s[36:37]
	s_addc_u32 s92, s25, 0
	s_mov_b32 s8, 0
	ds_read_b128 v[128:131], v212
	ds_read_b128 v[132:135], v212 offset:1024
	ds_read_b128 v[136:139], v212 offset:2048
	ds_read_b128 v[140:143], v212 offset:3072
	s_add_i32 s16, s8, 2
	s_cmp_eq_u32 s82, s8
	s_cselect_b32 s36, s1, s89
	s_cselect_b32 s23, s0, s90
	s_cselect_b32 s22, s47, s92
	s_cselect_b32 s28, s51, s91
	s_add_u32 s24, s36, 0x80
	s_addc_u32 s17, s23, 0
	s_add_u32 s8, s89, s18
	s_addc_u32 s9, s90, s19
	s_add_u32 s8, s8, 0xffffff80
	s_addc_u32 s9, s9, -1
	s_and_b32 s9, s9, 0xffff
	s_mov_b32 m0, s83
	ds_read_b128 v[144:147], v213
	ds_read_b128 v[148:151], v213 offset:1024
	ds_read_b128 v[152:155], v213 offset:2048
	ds_read_b128 v[156:159], v213 offset:3072
	ds_read_b128 v[160:163], v213 offset:4096
	ds_read_b128 v[164:167], v213 offset:5120
	ds_read_b128 v[168:171], v213 offset:6144
	ds_read_b128 v[172:175], v213 offset:7168
	buffer_load_dwordx4 v206, s[8:11], 0 offen lds
	s_mov_b32 m0, s84
	s_nop 0
	buffer_load_dwordx4 v208, s[8:11], 0 offen lds
	s_waitcnt lgkmcnt(8)
	s_barrier
	s_waitcnt lgkmcnt(0)
	s_setprio 1
	s_waitcnt lgkmcnt(7)
	v_mfma_f32_16x16x32_bf16 v[112:115], v[128:131], v[144:147], 0
	v_mfma_f32_16x16x32_bf16 v[116:119], v[136:139], v[144:147], 0
	s_waitcnt lgkmcnt(5)
	v_mfma_f32_16x16x32_bf16 v[100:103], v[128:131], v[152:155], 0
	v_mfma_f32_16x16x32_bf16 v[96:99], v[136:139], v[152:155], 0
	s_waitcnt lgkmcnt(3)
	v_mfma_f32_16x16x32_bf16 v[84:87], v[128:131], v[160:163], 0
	v_mfma_f32_16x16x32_bf16 v[80:83], v[136:139], v[160:163], 0
	s_waitcnt lgkmcnt(1)
	v_mfma_f32_16x16x32_bf16 v[68:71], v[128:131], v[168:171], 0
	v_mfma_f32_16x16x32_bf16 v[64:67], v[136:139], v[168:171], 0
	v_mfma_f32_16x16x32_bf16 v[112:115], v[132:135], v[148:151], v[112:115]
	v_mfma_f32_16x16x32_bf16 v[116:119], v[140:143], v[148:151], v[116:119]
	v_mfma_f32_16x16x32_bf16 v[100:103], v[132:135], v[156:159], v[100:103]
	v_mfma_f32_16x16x32_bf16 v[96:99], v[140:143], v[156:159], v[96:99]
	v_mfma_f32_16x16x32_bf16 v[84:87], v[132:135], v[164:167], v[84:87]
	v_mfma_f32_16x16x32_bf16 v[80:83], v[140:143], v[164:167], v[80:83]
	s_waitcnt lgkmcnt(0)
	v_mfma_f32_16x16x32_bf16 v[68:71], v[132:135], v[172:175], v[68:71]
	v_mfma_f32_16x16x32_bf16 v[64:67], v[140:143], v[172:175], v[64:67]
	s_setprio 0
	s_barrier
	s_and_b32 s29, s22, 0xffff
	s_mov_b32 s30, s10
	s_mov_b32 s31, s11
	s_mov_b32 m0, s15
	ds_read_b128 v[176:179], v214
	ds_read_b128 v[180:183], v214 offset:1024
	ds_read_b128 v[188:191], v214 offset:2048
	ds_read_b128 v[192:195], v214 offset:3072
	buffer_load_dwordx4 v207, s[28:31], 0 offen lds
	s_mov_b32 m0, s33
	s_nop 0
	buffer_load_dwordx4 v209, s[28:31], 0 offen lds
	s_barrier
; #define PG8_STAGE(bufoff, gbase, voff) do { const __amdgpu_buffer_rsrc_t _r = __builtin_amdgcn_make_buffer_rsrc((void*)(gbase), (short)0, 0x7fffffff, 0x00020000); _Pragma("unroll") for (int _i = 0; _i < 2; ++_i) \
;         __builtin_amdgcn_raw_ptr_buffer_load_lds(_r, (LAS unsigned*)(lds + (bufoff) + ldsw + _i * 8192), 16, (int)(voff)[_i], 0, 0, 0); } while (0)
; #define PG8_LDA(dst, b, h) do { _Pragma("unroll") for (int m = 0; m < 4; ++m) _Pragma("unroll") for (int k = 0; k < 2; ++k) dst[m][k] = *(const LAS bf16x8*)(lds + PG8_SA(b, h) + aoff + m * 2048 + k * 1024); } while (0)
; #define PG8_MMA(ai, bj, At, Bt) do { __builtin_amdgcn_s_setprio(1); _Pragma("unroll") for (int k = 0; k < 2; ++k) _Pragma("unroll") for (int m = 0; m < 4; ++m) _Pragma("unroll") for (int n = 0; n < ((bj) == 1 ? NB1 : 2); ++n) \
;         acc[ai][bj][m][n] = __builtin_amdgcn_mfma_f32_16x16x32_bf16(Bt[n][k], At[m][k], acc[ai][bj][m][n], 0, 0, 0); __builtin_amdgcn_s_setprio(0); } while (0)
; #define PG8_WAIT_V(n) asm volatile("s_waitcnt vmcnt(" #n ")" ::: "memory")
; #define PG8_WAIT_L(n) asm volatile("s_waitcnt lgkmcnt(" #n ")" ::: "memory")
; #define PG8_BAR __builtin_amdgcn_s_barrier()
; #define PG8_SCHED __builtin_amdgcn_sched_barrier(0)
;     ...
;             PG8_BAR; PG8_WAIT_L(0); PG8_MMA(0, 1, At, B1); PG8_BAR;
;             PG8_LDA(At, 0, 1); PG8_STAGE(PG8_SA(0, 0), a2, voffA);
;             PG8_BAR; PG8_WAIT_L(0); PG8_MMA(1, 0, At, B0); PG8_BAR; PG8_SCHED;
;             PG8_STAGE(PG8_SB(0, 1), b2 + hstepB, voffB);
;             PG8_WAIT_V(6); PG8_BAR; PG8_MMA(1, 1, At, B1); PG8_BAR;
	s_waitcnt lgkmcnt(0)
	s_setprio 1
	s_waitcnt lgkmcnt(3)
	v_mfma_f32_16x16x32_bf16 v[124:127], v[176:179], v[144:147], 0
	s_waitcnt lgkmcnt(1)
	v_mfma_f32_16x16x32_bf16 v[120:123], v[188:191], v[144:147], 0
	v_mfma_f32_16x16x32_bf16 v[108:111], v[176:179], v[152:155], 0
	v_mfma_f32_16x16x32_bf16 v[104:107], v[188:191], v[152:155], 0
	v_mfma_f32_16x16x32_bf16 v[92:95], v[176:179], v[160:163], 0
	v_mfma_f32_16x16x32_bf16 v[88:91], v[188:191], v[160:163], 0
	v_mfma_f32_16x16x32_bf16 v[76:79], v[176:179], v[168:171], 0
	v_mfma_f32_16x16x32_bf16 v[72:75], v[188:191], v[168:171], 0
	v_mfma_f32_16x16x32_bf16 v[124:127], v[180:183], v[148:151], v[124:127]
	s_waitcnt lgkmcnt(0)
	v_mfma_f32_16x16x32_bf16 v[120:123], v[192:195], v[148:151], v[120:123]
	v_mfma_f32_16x16x32_bf16 v[108:111], v[180:183], v[156:159], v[108:111]
	v_mfma_f32_16x16x32_bf16 v[104:107], v[192:195], v[156:159], v[104:107]
	v_mfma_f32_16x16x32_bf16 v[92:95], v[180:183], v[164:167], v[92:95]
	v_mfma_f32_16x16x32_bf16 v[88:91], v[192:195], v[164:167], v[88:91]
	v_mfma_f32_16x16x32_bf16 v[76:79], v[180:183], v[172:175], v[76:79]
	v_mfma_f32_16x16x32_bf16 v[72:75], v[192:195], v[172:175], v[72:75]
	s_setprio 0
	s_and_b32 s37, s23, 0xffff
	s_mov_b32 s38, s10
	s_mov_b32 s39, s11
	s_mov_b32 m0, s14
	s_barrier
	ds_read_b128 v[144:147], v213 offset:16384
	ds_read_b128 v[148:151], v213 offset:17408
	ds_read_b128 v[152:155], v213 offset:18432
	ds_read_b128 v[156:159], v213 offset:19456
	ds_read_b128 v[160:163], v213 offset:20480
	ds_read_b128 v[164:167], v213 offset:21504
	ds_read_b128 v[168:171], v213 offset:22528
	ds_read_b128 v[172:175], v213 offset:23552
	buffer_load_dwordx4 v206, s[36:39], 0 offen lds
	s_mov_b32 m0, s35
	s_nop 0
	buffer_load_dwordx4 v208, s[36:39], 0 offen lds
	s_barrier
	s_waitcnt lgkmcnt(0)
	s_setprio 1
	s_waitcnt lgkmcnt(7)
	v_mfma_f32_16x16x32_bf16 v[52:55], v[128:131], v[144:147], 0
	v_mfma_f32_16x16x32_bf16 v[48:51], v[136:139], v[144:147], 0
	s_waitcnt lgkmcnt(5)
	v_mfma_f32_16x16x32_bf16 v[36:39], v[128:131], v[152:155], 0
	v_mfma_f32_16x16x32_bf16 v[32:35], v[136:139], v[152:155], 0
	s_waitcnt lgkmcnt(3)
	v_mfma_f32_16x16x32_bf16 v[20:23], v[128:131], v[160:163], 0
	v_mfma_f32_16x16x32_bf16 v[16:19], v[136:139], v[160:163], 0
	s_waitcnt lgkmcnt(1)
	v_mfma_f32_16x16x32_bf16 v[4:7], v[128:131], v[168:171], 0
	v_mfma_f32_16x16x32_bf16 v[0:3], v[136:139], v[168:171], 0
	v_mfma_f32_16x16x32_bf16 v[52:55], v[132:135], v[148:151], v[52:55]
	v_mfma_f32_16x16x32_bf16 v[48:51], v[140:143], v[148:151], v[48:51]
	v_mfma_f32_16x16x32_bf16 v[36:39], v[132:135], v[156:159], v[36:39]
	v_mfma_f32_16x16x32_bf16 v[32:35], v[140:143], v[156:159], v[32:35]
	v_mfma_f32_16x16x32_bf16 v[20:23], v[132:135], v[164:167], v[20:23]
	v_mfma_f32_16x16x32_bf16 v[16:19], v[140:143], v[164:167], v[16:19]
	s_waitcnt lgkmcnt(0)
	v_mfma_f32_16x16x32_bf16 v[4:7], v[132:135], v[172:175], v[4:7]
	v_mfma_f32_16x16x32_bf16 v[0:3], v[140:143], v[172:175], v[0:3]
	s_setprio 0
	s_barrier
	s_add_u32 s8, s28, s42
	s_addc_u32 s93, s22, s43
	s_and_b32 s9, s93, 0xffff
	s_mov_b32 m0, s65
	s_nop 0
	buffer_load_dwordx4 v207, s[8:11], 0 offen lds
	s_mov_b32 m0, s67
	s_nop 0
	buffer_load_dwordx4 v209, s[8:11], 0 offen lds
	s_waitcnt vmcnt(6)
	s_barrier
	s_setprio 1
	v_mfma_f32_16x16x32_bf16 v[60:63], v[176:179], v[144:147], 0
	v_mfma_f32_16x16x32_bf16 v[56:59], v[188:191], v[144:147], 0
	v_mfma_f32_16x16x32_bf16 v[44:47], v[176:179], v[152:155], 0
	v_mfma_f32_16x16x32_bf16 v[40:43], v[188:191], v[152:155], 0
	v_mfma_f32_16x16x32_bf16 v[28:31], v[176:179], v[160:163], 0
	v_mfma_f32_16x16x32_bf16 v[24:27], v[188:191], v[160:163], 0
	v_mfma_f32_16x16x32_bf16 v[12:15], v[176:179], v[168:171], 0
	v_mfma_f32_16x16x32_bf16 v[8:11], v[188:191], v[168:171], 0
	v_mfma_f32_16x16x32_bf16 v[60:63], v[180:183], v[148:151], v[60:63]
	v_mfma_f32_16x16x32_bf16 v[56:59], v[192:195], v[148:151], v[56:59]
	v_mfma_f32_16x16x32_bf16 v[44:47], v[180:183], v[156:159], v[44:47]
	v_mfma_f32_16x16x32_bf16 v[40:43], v[192:195], v[156:159], v[40:43]
	v_mfma_f32_16x16x32_bf16 v[28:31], v[180:183], v[164:167], v[28:31]
	v_mfma_f32_16x16x32_bf16 v[24:27], v[192:195], v[164:167], v[24:27]
	v_mfma_f32_16x16x32_bf16 v[12:15], v[180:183], v[172:175], v[12:15]
	v_mfma_f32_16x16x32_bf16 v[8:11], v[192:195], v[172:175], v[8:11]
	s_setprio 0
	s_barrier
	s_branch .Lkmid_627

; #define PG8_STAGE(bufoff, gbase, voff) do { const __amdgpu_buffer_rsrc_t _r = __builtin_amdgcn_make_buffer_rsrc((void*)(gbase), (short)0, 0x7fffffff, 0x00020000); _Pragma("unroll") for (int _i = 0; _i < 2; ++_i) \
;         __builtin_amdgcn_raw_ptr_buffer_load_lds(_r, (LAS unsigned*)(lds + (bufoff) + ldsw + _i * 8192), 16, (int)(voff)[_i], 0, 0, 0); } while (0)
; #define PG8_LDA(dst, b, h) do { _Pragma("unroll") for (int m = 0; m < 4; ++m) _Pragma("unroll") for (int k = 0; k < 2; ++k) dst[m][k] = *(const LAS bf16x8*)(lds + PG8_SA(b, h) + aoff + m * 2048 + k * 1024); } while (0)
; #define PG8_LDB(dst, b, h) do { _Pragma("unroll") for (int n = 0; n < 2; ++n) _Pragma("unroll") for (int k = 0; k < 2; ++k) dst[n][k] = *(const LAS bf16x8*)(lds + PG8_SB(b, h) + boff + n * 2048 + k * 1024); } while (0)
; #define PG8_MMA(ai, bj, At, Bt) do { __builtin_amdgcn_s_setprio(1); _Pragma("unroll") for (int k = 0; k < 2; ++k) _Pragma("unroll") for (int m = 0; m < 4; ++m) _Pragma("unroll") for (int n = 0; n < ((bj) == 1 ? NB1 : 2); ++n) \
;         acc[ai][bj][m][n] = __builtin_amdgcn_mfma_f32_16x16x32_bf16(Bt[n][k], At[m][k], acc[ai][bj][m][n], 0, 0, 0); __builtin_amdgcn_s_setprio(0); } while (0)
; #define PG8_WAIT_L(n) asm volatile("s_waitcnt lgkmcnt(" #n ")" ::: "memory")
; #define PG8_BAR __builtin_amdgcn_s_barrier()
; #define PG8_SCHED __builtin_amdgcn_sched_barrier(0)
;     ...
;             PG8_LDB(B0, 1, 0); PG8_SCHED; PG8_LDA(At, 1, 0); PG8_STAGE(PG8_SA(0, 1), a2 + hstepA, voffA);
;             PG8_WAIT_L(8); PG8_BAR; PG8_WAIT_L(0); PG8_MMA(0, 0, At, B0); PG8_BAR; PG8_SCHED;
;             PG8_LDB(B1, 1, 1); PG8_STAGE(PG8_SB(1, 0), b3, voffB);
;             PG8_BAR; PG8_WAIT_L(0); PG8_MMA(0, 1, At, B1); PG8_BAR;
.Lkmid_627:
	ds_read_b128 v[128:131], v215
	ds_read_b128 v[132:135], v215 offset:1024
	ds_read_b128 v[136:139], v215 offset:2048
	ds_read_b128 v[140:143], v215 offset:3072
	s_add_u32 s36, s36, s18
	s_addc_u32 s9, s23, s19
	s_and_b32 s37, s9, 0xffff
	s_mov_b32 m0, s70
	ds_read_b128 v[144:147], v213 offset:32768
	ds_read_b128 v[148:151], v213 offset:33792
	ds_read_b128 v[152:155], v213 offset:34816
	ds_read_b128 v[156:159], v213 offset:35840
	ds_read_b128 v[160:163], v213 offset:36864
	ds_read_b128 v[164:167], v213 offset:37888
	ds_read_b128 v[168:171], v213 offset:38912
	ds_read_b128 v[172:175], v213 offset:39936
	buffer_load_dwordx4 v206, s[36:39], 0 offen lds
	s_mov_b32 m0, s71
	s_nop 0
	buffer_load_dwordx4 v208, s[36:39], 0 offen lds
	s_waitcnt lgkmcnt(8)
	s_barrier
	s_waitcnt lgkmcnt(0)
	s_setprio 1
	s_waitcnt lgkmcnt(7)
	v_mfma_f32_16x16x32_bf16 v[112:115], v[128:131], v[144:147], v[112:115]
	v_mfma_f32_16x16x32_bf16 v[116:119], v[136:139], v[144:147], v[116:119]
	s_waitcnt lgkmcnt(5)
	v_mfma_f32_16x16x32_bf16 v[100:103], v[128:131], v[152:155], v[100:103]
	v_mfma_f32_16x16x32_bf16 v[96:99], v[136:139], v[152:155], v[96:99]
	s_waitcnt lgkmcnt(3)
	v_mfma_f32_16x16x32_bf16 v[84:87], v[128:131], v[160:163], v[84:87]
	v_mfma_f32_16x16x32_bf16 v[80:83], v[136:139], v[160:163], v[80:83]
	s_waitcnt lgkmcnt(1)
	v_mfma_f32_16x16x32_bf16 v[68:71], v[128:131], v[168:171], v[68:71]
	v_mfma_f32_16x16x32_bf16 v[64:67], v[136:139], v[168:171], v[64:67]
	v_mfma_f32_16x16x32_bf16 v[112:115], v[132:135], v[148:151], v[112:115]
	v_mfma_f32_16x16x32_bf16 v[116:119], v[140:143], v[148:151], v[116:119]
	v_mfma_f32_16x16x32_bf16 v[100:103], v[132:135], v[156:159], v[100:103]
	v_mfma_f32_16x16x32_bf16 v[96:99], v[140:143], v[156:159], v[96:99]
	v_mfma_f32_16x16x32_bf16 v[84:87], v[132:135], v[164:167], v[84:87]
	v_mfma_f32_16x16x32_bf16 v[80:83], v[140:143], v[164:167], v[80:83]
	s_waitcnt lgkmcnt(0)
	v_mfma_f32_16x16x32_bf16 v[68:71], v[132:135], v[172:175], v[68:71]
	v_mfma_f32_16x16x32_bf16 v[64:67], v[140:143], v[172:175], v[64:67]
	s_setprio 0
	s_barrier
	s_add_u32 s28, s28, 0x80
	s_addc_u32 s9, s22, 0
	s_and_b32 s29, s9, 0xffff
	s_mov_b32 m0, s74
	ds_read_b128 v[176:179], v216
	ds_read_b128 v[180:183], v216 offset:1024
	ds_read_b128 v[188:191], v216 offset:2048
	ds_read_b128 v[192:195], v216 offset:3072
	buffer_load_dwordx4 v207, s[28:31], 0 offen lds
	s_mov_b32 m0, s75
	s_nop 0
	buffer_load_dwordx4 v209, s[28:31], 0 offen lds
	s_barrier
	s_waitcnt lgkmcnt(0)
	s_setprio 1
	s_waitcnt lgkmcnt(3)
	v_mfma_f32_16x16x32_bf16 v[124:127], v[176:179], v[144:147], v[124:127]
	s_waitcnt lgkmcnt(1)
	v_mfma_f32_16x16x32_bf16 v[120:123], v[188:191], v[144:147], v[120:123]
	v_mfma_f32_16x16x32_bf16 v[108:111], v[176:179], v[152:155], v[108:111]
	v_mfma_f32_16x16x32_bf16 v[104:107], v[188:191], v[152:155], v[104:107]
	v_mfma_f32_16x16x32_bf16 v[92:95], v[176:179], v[160:163], v[92:95]
	v_mfma_f32_16x16x32_bf16 v[88:91], v[188:191], v[160:163], v[88:91]
	v_mfma_f32_16x16x32_bf16 v[76:79], v[176:179], v[168:171], v[76:79]
	v_mfma_f32_16x16x32_bf16 v[72:75], v[188:191], v[168:171], v[72:75]
	v_mfma_f32_16x16x32_bf16 v[124:127], v[180:183], v[148:151], v[124:127]
	s_waitcnt lgkmcnt(0)
	v_mfma_f32_16x16x32_bf16 v[120:123], v[192:195], v[148:151], v[120:123]
	v_mfma_f32_16x16x32_bf16 v[108:111], v[180:183], v[156:159], v[108:111]
	v_mfma_f32_16x16x32_bf16 v[104:107], v[192:195], v[156:159], v[104:107]
	v_mfma_f32_16x16x32_bf16 v[92:95], v[180:183], v[164:167], v[92:95]
	v_mfma_f32_16x16x32_bf16 v[88:91], v[192:195], v[164:167], v[88:91]
	v_mfma_f32_16x16x32_bf16 v[76:79], v[180:183], v[172:175], v[76:79]
	v_mfma_f32_16x16x32_bf16 v[72:75], v[192:195], v[172:175], v[72:75]
	s_setprio 0
	s_and_b32 s25, s17, 0xffff
	s_mov_b32 s26, s10
	s_mov_b32 s27, s11
	s_mov_b32 m0, s76
	s_barrier
; #define PG8_STAGE(bufoff, gbase, voff) do { const __amdgpu_buffer_rsrc_t _r = __builtin_amdgcn_make_buffer_rsrc((void*)(gbase), (short)0, 0x7fffffff, 0x00020000); _Pragma("unroll") for (int _i = 0; _i < 2; ++_i) \
;         __builtin_amdgcn_raw_ptr_buffer_load_lds(_r, (LAS unsigned*)(lds + (bufoff) + ldsw + _i * 8192), 16, (int)(voff)[_i], 0, 0, 0); } while (0)
; #define PG8_LDA(dst, b, h) do { _Pragma("unroll") for (int m = 0; m < 4; ++m) _Pragma("unroll") for (int k = 0; k < 2; ++k) dst[m][k] = *(const LAS bf16x8*)(lds + PG8_SA(b, h) + aoff + m * 2048 + k * 1024); } while (0)
; #define PG8_MMA(ai, bj, At, Bt) do { __builtin_amdgcn_s_setprio(1); _Pragma("unroll") for (int k = 0; k < 2; ++k) _Pragma("unroll") for (int m = 0; m < 4; ++m) _Pragma("unroll") for (int n = 0; n < ((bj) == 1 ? NB1 : 2); ++n) \
;         acc[ai][bj][m][n] = __builtin_amdgcn_mfma_f32_16x16x32_bf16(Bt[n][k], At[m][k], acc[ai][bj][m][n], 0, 0, 0); __builtin_amdgcn_s_setprio(0); } while (0)
; #define PG8_WAIT_V(n) asm volatile("s_waitcnt vmcnt(" #n ")" ::: "memory")
; #define PG8_WAIT_L(n) asm volatile("s_waitcnt lgkmcnt(" #n ")" ::: "memory")
; #define PG8_BAR __builtin_amdgcn_s_barrier()
; #define PG8_SCHED __builtin_amdgcn_sched_barrier(0)
;     ...
;             PG8_LDA(At, 1, 1); PG8_STAGE(PG8_SA(1, 0), a3, voffA);
;             PG8_BAR; PG8_WAIT_L(0); PG8_MMA(1, 0, At, B0); PG8_BAR; PG8_SCHED;
;             PG8_STAGE(PG8_SB(1, 1), b3 + hstepB, voffB);
;             PG8_WAIT_V(6); PG8_BAR; PG8_MMA(1, 1, At, B1); PG8_BAR;
;         }
	ds_read_b128 v[144:147], v213 offset:49152
	ds_read_b128 v[148:151], v213 offset:50176
	ds_read_b128 v[152:155], v213 offset:51200
	ds_read_b128 v[156:159], v213 offset:52224
	ds_read_b128 v[160:163], v213 offset:53248
	ds_read_b128 v[164:167], v213 offset:54272
	ds_read_b128 v[168:171], v213 offset:55296
	ds_read_b128 v[172:175], v213 offset:56320
	buffer_load_dwordx4 v206, s[24:27], 0 offen lds
	s_mov_b32 m0, s77
	s_nop 0
	buffer_load_dwordx4 v208, s[24:27], 0 offen lds
	s_barrier
	s_waitcnt lgkmcnt(0)
	s_setprio 1
	s_waitcnt lgkmcnt(7)
	v_mfma_f32_16x16x32_bf16 v[52:55], v[128:131], v[144:147], v[52:55]
	v_mfma_f32_16x16x32_bf16 v[48:51], v[136:139], v[144:147], v[48:51]
	s_waitcnt lgkmcnt(5)
	v_mfma_f32_16x16x32_bf16 v[36:39], v[128:131], v[152:155], v[36:39]
	v_mfma_f32_16x16x32_bf16 v[32:35], v[136:139], v[152:155], v[32:35]
	s_waitcnt lgkmcnt(3)
	v_mfma_f32_16x16x32_bf16 v[20:23], v[128:131], v[160:163], v[20:23]
	v_mfma_f32_16x16x32_bf16 v[16:19], v[136:139], v[160:163], v[16:19]
	s_waitcnt lgkmcnt(1)
	v_mfma_f32_16x16x32_bf16 v[4:7], v[128:131], v[168:171], v[4:7]
	v_mfma_f32_16x16x32_bf16 v[0:3], v[136:139], v[168:171], v[0:3]
	v_mfma_f32_16x16x32_bf16 v[52:55], v[132:135], v[148:151], v[52:55]
	v_mfma_f32_16x16x32_bf16 v[48:51], v[140:143], v[148:151], v[48:51]
	v_mfma_f32_16x16x32_bf16 v[36:39], v[132:135], v[156:159], v[36:39]
	v_mfma_f32_16x16x32_bf16 v[32:35], v[140:143], v[156:159], v[32:35]
	v_mfma_f32_16x16x32_bf16 v[20:23], v[132:135], v[164:167], v[20:23]
	v_mfma_f32_16x16x32_bf16 v[16:19], v[140:143], v[164:167], v[16:19]
	s_waitcnt lgkmcnt(0)
	v_mfma_f32_16x16x32_bf16 v[4:7], v[132:135], v[172:175], v[4:7]
	v_mfma_f32_16x16x32_bf16 v[0:3], v[140:143], v[172:175], v[0:3]
	s_setprio 0
	s_barrier
	s_add_u32 s8, s8, 0x80
	s_addc_u32 s9, s93, 0
	s_and_b32 s9, s9, 0xffff
	s_mov_b32 m0, s78
	s_nop 0
	buffer_load_dwordx4 v207, s[8:11], 0 offen lds
	s_mov_b32 m0, s79
	s_nop 0
	buffer_load_dwordx4 v209, s[8:11], 0 offen lds
	s_waitcnt vmcnt(6)
	s_barrier
	s_setprio 1
	v_mfma_f32_16x16x32_bf16 v[60:63], v[176:179], v[144:147], v[60:63]
	v_mfma_f32_16x16x32_bf16 v[56:59], v[188:191], v[144:147], v[56:59]
	v_mfma_f32_16x16x32_bf16 v[44:47], v[176:179], v[152:155], v[44:47]
	v_mfma_f32_16x16x32_bf16 v[40:43], v[188:191], v[152:155], v[40:43]
	v_mfma_f32_16x16x32_bf16 v[28:31], v[176:179], v[160:163], v[28:31]
	v_mfma_f32_16x16x32_bf16 v[24:27], v[188:191], v[160:163], v[24:27]
	v_mfma_f32_16x16x32_bf16 v[12:15], v[176:179], v[168:171], v[12:15]
	v_mfma_f32_16x16x32_bf16 v[8:11], v[188:191], v[168:171], v[8:11]
	v_mfma_f32_16x16x32_bf16 v[60:63], v[180:183], v[148:151], v[60:63]
	v_mfma_f32_16x16x32_bf16 v[56:59], v[192:195], v[148:151], v[56:59]
	v_mfma_f32_16x16x32_bf16 v[44:47], v[180:183], v[156:159], v[44:47]
	v_mfma_f32_16x16x32_bf16 v[40:43], v[192:195], v[156:159], v[40:43]
	v_mfma_f32_16x16x32_bf16 v[28:31], v[180:183], v[164:167], v[28:31]
	v_mfma_f32_16x16x32_bf16 v[24:27], v[192:195], v[164:167], v[24:27]
	v_mfma_f32_16x16x32_bf16 v[12:15], v[180:183], v[172:175], v[12:15]
	v_mfma_f32_16x16x32_bf16 v[8:11], v[192:195], v[172:175], v[8:11]
	s_setprio 0
	s_add_u32 s89, s89, 0x100
	s_addc_u32 s90, s90, 0
	s_add_u32 s91, s91, 0x100
	s_addc_u32 s92, s92, 0
	s_cmp_ge_i32 s16, s73
	s_mov_b32 s8, s16
	s_barrier
	s_cbranch_scc0 .LBB0_627
	s_mov_b64 s[36:37], s[44:45]

;     __device__ __forceinline__ size_t a_off(const Unit& u) const { return (size_t)u.pm * atile; }
;     __device__ __forceinline__ size_t b_off(const Unit& u) const { return (size_t)u.pn * btile; }
;     __device__ __forceinline__ bool next(int i, Unit& u) const { const long L = (long)i * G + c; if (L >= NG * 8) return false; u.g = (int)(L >> 3); u.pm = (int)(L & 7); u.pn = 0; return true; }
;     __device__ __forceinline__ size_t a_off(const Unit& u) const { return ((size_t)u.g * NROW + (size_t)u.pm * BM) * KA * 2; }
;     __device__ __forceinline__ size_t b_off(const Unit& u) const { return (size_t)u.g * btile; }
;     __device__ __forceinline__ bool next(int i, Unit& u) const { if (i >= 2) return false; u.g = g; u.pm = 2 * b + i; u.pn = 0; return true; }
;     __device__ __forceinline__ size_t a_off(const Unit& u) const { return ((size_t)u.g * NROW + (size_t)u.pm * BM) * KA * 2; }
; #define PG8_WAIT_L(n) asm volatile("s_waitcnt lgkmcnt(" #n ")" ::: "memory")
;     __device__ __forceinline__ bool next(int i, Unit& u) const {
;         const long L = (long)i * G + c; if (L >= nwg) return false;
;         int wgid = (int)L; { const int q = nwg / NXCD, r = nwg % NXCD, xcd = wgid % NXCD, off = wgid / NXCD; wgid = (xcd < r ? xcd * (q + 1) : r * (q + 1) + (xcd - r) * q) + off; }
;         const int nig = WGM * nN, gid = wgid / nig, fm = gid * WGM, gsz = (nM - fm) < WGM ? (nM - fm) : WGM;
;         u.pm = __builtin_amdgcn_readfirstlane(fm + ((wgid % nig) % gsz)); u.pn = __builtin_amdgcn_readfirstlane((wgid % nig) / gsz); u.g = 0; return true;
;     ...
;         const bool has_next = S.next(ui + 1, nxt);
;         const char* nA = has_next ? (const char*)Ap + S.a_off(nxt) : cA; const char* nB = has_next ? (const char*)Btp + S.b_off(nxt) : cB;
;         for (int t = 0; t < nt; t += 2) {
;             const bool last = (t == nt - 2);
;             const char* a1 = cA + (size_t)(t + 1) * kstep;
;             const char* a2 = last ? nA : cA + (size_t)(t + 2) * kstep; const char* b2 = last ? nB : cB + (size_t)(t + 2) * kstep;
;             const char* a3 = a2 + kstep; const char* b3 = b2 + kstep;
;             PG8_LDB(B0, 0, 0); PG8_SCHED; PG8_LDA(At, 0, 0); PG8_STAGE(PG8_SA(1, 1), a1 + hstepA, voffA);
;             PG8_WAIT_L(8); PG8_BAR; PG8_WAIT_L(0); PG8_MMA(0, 0, At, B0); PG8_BAR; PG8_SCHED;
;             PG8_LDB(B1, 0, 1); PG8_STAGE(PG8_SB(0, 0), b2, voffB);
.LBB0_686:
	s_add_i32 s47, s47, 1
	s_mul_i32 s3, s47, s94
	s_mul_hi_u32 s12, s47, s34
	s_add_i32 s3, s12, s3
	s_mul_i32 s12, s47, s34
	s_add_u32 s12, s12, s2
	s_addc_u32 s13, s3, s15
	v_cmp_gt_i64_e32 vcc, s[12:13], v[172:173]
	s_cbranch_vccnz .LBB0_688
	s_add_i32 s52, s72, 4
	s_cmp_ge_i32 s52, 22
	s_cselect_b32 s16, 22, 0
	s_cselect_b32 s17, 8, 0
	s_sub_i32 s52, s52, s16
	s_add_i32 s58, s70, s17
.LBB0_688:
	s_ashr_i32 s59, s58, 31
	s_lshl_b64 s[16:17], s[58:59], 19
	s_add_u32 s64, s20, s16
	s_addc_u32 s65, s21, s17
	s_ashr_i32 s53, s52, 31
	s_lshl_b64 s[16:17], s[52:53], 19
	s_add_u32 s66, s76, s16
	v_cmp_lt_i64_e64 s[12:13], s[12:13], v[170:171]
	s_addc_u32 s67, s77, s17
	s_andn2_b64 vcc, exec, s[50:51]
	s_cbranch_vccnz .Lkzero_690
	s_and_b64 s[16:17], s[12:13], exec
	s_cselect_b32 s53, s65, s27
	s_cselect_b32 s59, s64, s26
	s_cselect_b32 s96, s67, s25
	s_cselect_b32 s97, s66, s24
	s_add_u32 vcc_lo, s26, 0x100
	s_addc_u32 vcc_hi, s27, 0
	s_add_u32 s3, s24, 0x100
	s_addc_u32 s46, s25, 0
	s_mov_b32 s16, 0
	ds_read_b128 v[76:79], v193
	ds_read_b128 v[88:91], v193 offset:1024
	ds_read_b128 v[92:95], v193 offset:2048
	ds_read_b128 v[128:131], v193 offset:3072
	s_add_i32 s22, s16, 2
	s_cmp_eq_u32 s91, s16
	s_cselect_b32 s36, s59, vcc_lo
	s_cselect_b32 s26, s53, vcc_hi
	s_cselect_b32 s25, s96, s46
	s_cselect_b32 s28, s97, s3
	s_add_u32 s24, s36, 0x80
	s_addc_u32 s23, s26, 0
	s_add_u32 s16, vcc_lo, s0
	s_addc_u32 s17, vcc_hi, s1
	s_add_u32 s16, s16, 0xffffff80
	s_addc_u32 s17, s17, -1
	s_and_b32 s17, s17, 0xffff
	s_mov_b32 m0, s92
	ds_read_b128 v[132:135], v194
	ds_read_b128 v[136:139], v194 offset:1024
	ds_read_b128 v[140:143], v194 offset:2048
	ds_read_b128 v[174:177], v194 offset:3072
	ds_read_b128 v[178:181], v194 offset:4096
	ds_read_b128 v[182:185], v194 offset:5120
	ds_read_b128 v[202:205], v194 offset:6144
	ds_read_b128 v[206:209], v194 offset:7168
	buffer_load_dwordx4 v186, s[16:19], 0 offen lds
	s_mov_b32 m0, s93
	s_nop 0
	buffer_load_dwordx4 v188, s[16:19], 0 offen lds
	s_waitcnt lgkmcnt(8)
	s_barrier
	s_waitcnt lgkmcnt(0)
	s_setprio 1
	s_waitcnt lgkmcnt(7)
	v_mfma_f32_16x16x32_bf16 v[152:155], v[76:79], v[132:135], 0
	v_mfma_f32_16x16x32_bf16 v[144:147], v[92:95], v[132:135], 0
	s_waitcnt lgkmcnt(5)
	v_mfma_f32_16x16x32_bf16 v[124:127], v[76:79], v[140:143], 0
	v_mfma_f32_16x16x32_bf16 v[120:123], v[92:95], v[140:143], 0
	s_waitcnt lgkmcnt(3)
	v_mfma_f32_16x16x32_bf16 v[108:111], v[76:79], v[178:181], 0
	v_mfma_f32_16x16x32_bf16 v[104:107], v[92:95], v[178:181], 0
	s_waitcnt lgkmcnt(1)
	v_mfma_f32_16x16x32_bf16 v[84:87], v[76:79], v[202:205], 0
	v_mfma_f32_16x16x32_bf16 v[80:83], v[92:95], v[202:205], 0
	v_mfma_f32_16x16x32_bf16 v[152:155], v[88:91], v[136:139], v[152:155]
	v_mfma_f32_16x16x32_bf16 v[144:147], v[128:131], v[136:139], v[144:147]
	v_mfma_f32_16x16x32_bf16 v[124:127], v[88:91], v[174:177], v[124:127]
	v_mfma_f32_16x16x32_bf16 v[120:123], v[128:131], v[174:177], v[120:123]
	v_mfma_f32_16x16x32_bf16 v[108:111], v[88:91], v[182:185], v[108:111]
	v_mfma_f32_16x16x32_bf16 v[104:107], v[128:131], v[182:185], v[104:107]
	s_waitcnt lgkmcnt(0)
	v_mfma_f32_16x16x32_bf16 v[84:87], v[88:91], v[206:209], v[84:87]
	v_mfma_f32_16x16x32_bf16 v[80:83], v[128:131], v[206:209], v[80:83]
	s_setprio 0
	s_barrier
	s_and_b32 s29, s25, 0xffff
	s_mov_b32 s30, s18
	s_mov_b32 s31, s19
	s_mov_b32 m0, s73
	ds_read_b128 v[210:213], v195
	ds_read_b128 v[214:217], v195 offset:1024
	ds_read_b128 v[218:221], v195 offset:2048
	ds_read_b128 v[222:225], v195 offset:3072
	buffer_load_dwordx4 v187, s[28:31], 0 offen lds
	s_mov_b32 m0, s78
	s_nop 0
	buffer_load_dwordx4 v189, s[28:31], 0 offen lds
	s_barrier
; #define PG8_STAGE(bufoff, gbase, voff) do { const __amdgpu_buffer_rsrc_t _r = __builtin_amdgcn_make_buffer_rsrc((void*)(gbase), (short)0, 0x7fffffff, 0x00020000); _Pragma("unroll") for (int _i = 0; _i < 2; ++_i) \
;         __builtin_amdgcn_raw_ptr_buffer_load_lds(_r, (LAS unsigned*)(lds + (bufoff) + ldsw + _i * 8192), 16, (int)(voff)[_i], 0, 0, 0); } while (0)
; #define PG8_LDA(dst, b, h) do { _Pragma("unroll") for (int m = 0; m < 4; ++m) _Pragma("unroll") for (int k = 0; k < 2; ++k) dst[m][k] = *(const LAS bf16x8*)(lds + PG8_SA(b, h) + aoff + m * 2048 + k * 1024); } while (0)
; #define PG8_LDB(dst, b, h) do { _Pragma("unroll") for (int n = 0; n < 2; ++n) _Pragma("unroll") for (int k = 0; k < 2; ++k) dst[n][k] = *(const LAS bf16x8*)(lds + PG8_SB(b, h) + boff + n * 2048 + k * 1024); } while (0)
; #define PG8_MMA(ai, bj, At, Bt) do { __builtin_amdgcn_s_setprio(1); _Pragma("unroll") for (int k = 0; k < 2; ++k) _Pragma("unroll") for (int m = 0; m < 4; ++m) _Pragma("unroll") for (int n = 0; n < ((bj) == 1 ? NB1 : 2); ++n) \
;         acc[ai][bj][m][n] = __builtin_amdgcn_mfma_f32_16x16x32_bf16(Bt[n][k], At[m][k], acc[ai][bj][m][n], 0, 0, 0); __builtin_amdgcn_s_setprio(0); } while (0)
; #define PG8_WAIT_V(n) asm volatile("s_waitcnt vmcnt(" #n ")" ::: "memory")
; #define PG8_WAIT_L(n) asm volatile("s_waitcnt lgkmcnt(" #n ")" ::: "memory")
; #define PG8_BAR __builtin_amdgcn_s_barrier()
; #define PG8_SCHED __builtin_amdgcn_sched_barrier(0)
;     ...
;             PG8_LDB(B0, 0, 0); PG8_SCHED; PG8_LDA(At, 0, 0); PG8_STAGE(PG8_SA(1, 1), a1 + hstepA, voffA);
;             PG8_WAIT_L(8); PG8_BAR; PG8_WAIT_L(0); PG8_MMA(0, 0, At, B0); PG8_BAR; PG8_SCHED;
;             PG8_LDB(B1, 0, 1); PG8_STAGE(PG8_SB(0, 0), b2, voffB);
;             PG8_BAR; PG8_WAIT_L(0); PG8_MMA(0, 1, At, B1); PG8_BAR;
;             PG8_LDA(At, 0, 1); PG8_STAGE(PG8_SA(0, 0), a2, voffA);
;             PG8_BAR; PG8_WAIT_L(0); PG8_MMA(1, 0, At, B0); PG8_BAR; PG8_SCHED;
;             PG8_STAGE(PG8_SB(0, 1), b2 + hstepB, voffB);
;             PG8_WAIT_V(6); PG8_BAR; PG8_MMA(1, 1, At, B1); PG8_BAR;
	s_waitcnt lgkmcnt(0)
	s_setprio 1
	s_waitcnt lgkmcnt(3)
	v_mfma_f32_16x16x32_bf16 v[116:119], v[210:213], v[140:143], 0
	s_waitcnt lgkmcnt(1)
	v_mfma_f32_16x16x32_bf16 v[112:115], v[218:221], v[140:143], 0
	v_mfma_f32_16x16x32_bf16 v[100:103], v[210:213], v[178:181], 0
	v_mfma_f32_16x16x32_bf16 v[96:99], v[218:221], v[178:181], 0
	v_mfma_f32_16x16x32_bf16 v[68:71], v[210:213], v[202:205], 0
	v_mfma_f32_16x16x32_bf16 v[64:67], v[218:221], v[202:205], 0
	v_mfma_f32_16x16x32_bf16 v[156:159], v[210:213], v[132:135], 0
	v_mfma_f32_16x16x32_bf16 v[132:135], v[218:221], v[132:135], 0
	v_mfma_f32_16x16x32_bf16 v[116:119], v[214:217], v[174:177], v[116:119]
	s_waitcnt lgkmcnt(0)
	v_mfma_f32_16x16x32_bf16 v[112:115], v[222:225], v[174:177], v[112:115]
	v_mfma_f32_16x16x32_bf16 v[100:103], v[214:217], v[182:185], v[100:103]
	v_mfma_f32_16x16x32_bf16 v[96:99], v[222:225], v[182:185], v[96:99]
	v_mfma_f32_16x16x32_bf16 v[68:71], v[214:217], v[206:209], v[68:71]
	v_mfma_f32_16x16x32_bf16 v[64:67], v[222:225], v[206:209], v[64:67]
	v_mfma_f32_16x16x32_bf16 v[140:143], v[214:217], v[136:139], v[156:159]
	v_mfma_f32_16x16x32_bf16 v[132:135], v[222:225], v[136:139], v[132:135]
	s_setprio 0
	s_and_b32 s37, s26, 0xffff
	s_mov_b32 s38, s18
	s_mov_b32 s39, s19
	s_mov_b32 m0, s71
	s_barrier
	ds_read_b128 v[136:139], v194 offset:16384
	ds_read_b128 v[148:151], v194 offset:17408
	ds_read_b128 v[156:159], v194 offset:18432
	ds_read_b128 v[174:177], v194 offset:19456
	ds_read_b128 v[178:181], v194 offset:20480
	ds_read_b128 v[182:185], v194 offset:21504
	ds_read_b128 v[202:205], v194 offset:22528
	ds_read_b128 v[206:209], v194 offset:23552
	buffer_load_dwordx4 v186, s[36:39], 0 offen lds
	s_mov_b32 m0, s79
	s_nop 0
	buffer_load_dwordx4 v188, s[36:39], 0 offen lds
	s_barrier
	s_waitcnt lgkmcnt(0)
	s_setprio 1
	s_waitcnt lgkmcnt(7)
	v_mfma_f32_16x16x32_bf16 v[60:63], v[76:79], v[136:139], 0
	v_mfma_f32_16x16x32_bf16 v[52:55], v[92:95], v[136:139], 0
	s_waitcnt lgkmcnt(5)
	v_mfma_f32_16x16x32_bf16 v[44:47], v[76:79], v[156:159], 0
	v_mfma_f32_16x16x32_bf16 v[40:43], v[92:95], v[156:159], 0
	s_waitcnt lgkmcnt(3)
	v_mfma_f32_16x16x32_bf16 v[28:31], v[76:79], v[178:181], 0
	v_mfma_f32_16x16x32_bf16 v[24:27], v[92:95], v[178:181], 0
	s_waitcnt lgkmcnt(1)
	v_mfma_f32_16x16x32_bf16 v[12:15], v[76:79], v[202:205], 0
	v_mfma_f32_16x16x32_bf16 v[8:11], v[92:95], v[202:205], 0
	v_mfma_f32_16x16x32_bf16 v[60:63], v[88:91], v[148:151], v[60:63]
	v_mfma_f32_16x16x32_bf16 v[52:55], v[128:131], v[148:151], v[52:55]
	v_mfma_f32_16x16x32_bf16 v[44:47], v[88:91], v[174:177], v[44:47]
	v_mfma_f32_16x16x32_bf16 v[40:43], v[128:131], v[174:177], v[40:43]
	v_mfma_f32_16x16x32_bf16 v[28:31], v[88:91], v[182:185], v[28:31]
	v_mfma_f32_16x16x32_bf16 v[24:27], v[128:131], v[182:185], v[24:27]
	s_waitcnt lgkmcnt(0)
	v_mfma_f32_16x16x32_bf16 v[12:15], v[88:91], v[206:209], v[12:15]
	v_mfma_f32_16x16x32_bf16 v[8:11], v[128:131], v[206:209], v[8:11]
	s_setprio 0
	s_barrier
	s_add_u32 s16, s28, s44
	s_addc_u32 s74, s25, s45
	s_and_b32 s17, s74, 0xffff
	s_mov_b32 m0, s80
	s_nop 0
	buffer_load_dwordx4 v187, s[16:19], 0 offen lds
	s_mov_b32 m0, s81
	s_nop 0
	buffer_load_dwordx4 v189, s[16:19], 0 offen lds
	s_waitcnt vmcnt(6)
	s_barrier
	s_setprio 1
	v_mfma_f32_16x16x32_bf16 v[56:59], v[210:213], v[136:139], 0
	v_mfma_f32_16x16x32_bf16 v[48:51], v[218:221], v[136:139], 0
	v_mfma_f32_16x16x32_bf16 v[36:39], v[210:213], v[156:159], 0
	v_mfma_f32_16x16x32_bf16 v[32:35], v[218:221], v[156:159], 0
	v_mfma_f32_16x16x32_bf16 v[20:23], v[210:213], v[178:181], 0
	v_mfma_f32_16x16x32_bf16 v[16:19], v[218:221], v[178:181], 0
	v_mfma_f32_16x16x32_bf16 v[4:7], v[210:213], v[202:205], 0
	v_mfma_f32_16x16x32_bf16 v[0:3], v[218:221], v[202:205], 0
	v_mfma_f32_16x16x32_bf16 v[56:59], v[214:217], v[148:151], v[56:59]
	v_mfma_f32_16x16x32_bf16 v[48:51], v[222:225], v[148:151], v[48:51]
	v_mfma_f32_16x16x32_bf16 v[36:39], v[214:217], v[174:177], v[36:39]
	v_mfma_f32_16x16x32_bf16 v[32:35], v[222:225], v[174:177], v[32:35]
	v_mfma_f32_16x16x32_bf16 v[20:23], v[214:217], v[182:185], v[20:23]
	v_mfma_f32_16x16x32_bf16 v[16:19], v[222:225], v[182:185], v[16:19]
	v_mfma_f32_16x16x32_bf16 v[4:7], v[214:217], v[206:209], v[4:7]
	v_mfma_f32_16x16x32_bf16 v[0:3], v[222:225], v[206:209], v[0:3]
	s_setprio 0
	s_barrier
	s_branch .Lkmid_690

; #define PG8_STAGE(bufoff, gbase, voff) do { const __amdgpu_buffer_rsrc_t _r = __builtin_amdgcn_make_buffer_rsrc((void*)(gbase), (short)0, 0x7fffffff, 0x00020000); _Pragma("unroll") for (int _i = 0; _i < 2; ++_i) \
;         __builtin_amdgcn_raw_ptr_buffer_load_lds(_r, (LAS unsigned*)(lds + (bufoff) + ldsw + _i * 8192), 16, (int)(voff)[_i], 0, 0, 0); } while (0)
; #define PG8_LDA(dst, b, h) do { _Pragma("unroll") for (int m = 0; m < 4; ++m) _Pragma("unroll") for (int k = 0; k < 2; ++k) dst[m][k] = *(const LAS bf16x8*)(lds + PG8_SA(b, h) + aoff + m * 2048 + k * 1024); } while (0)
; #define PG8_LDB(dst, b, h) do { _Pragma("unroll") for (int n = 0; n < 2; ++n) _Pragma("unroll") for (int k = 0; k < 2; ++k) dst[n][k] = *(const LAS bf16x8*)(lds + PG8_SB(b, h) + boff + n * 2048 + k * 1024); } while (0)
; #define PG8_MMA(ai, bj, At, Bt) do { __builtin_amdgcn_s_setprio(1); _Pragma("unroll") for (int k = 0; k < 2; ++k) _Pragma("unroll") for (int m = 0; m < 4; ++m) _Pragma("unroll") for (int n = 0; n < ((bj) == 1 ? NB1 : 2); ++n) \
;         acc[ai][bj][m][n] = __builtin_amdgcn_mfma_f32_16x16x32_bf16(Bt[n][k], At[m][k], acc[ai][bj][m][n], 0, 0, 0); __builtin_amdgcn_s_setprio(0); } while (0)
; #define PG8_WAIT_L(n) asm volatile("s_waitcnt lgkmcnt(" #n ")" ::: "memory")
; #define PG8_BAR __builtin_amdgcn_s_barrier()
; #define PG8_SCHED __builtin_amdgcn_sched_barrier(0)
;     ...
;             PG8_LDB(B0, 1, 0); PG8_SCHED; PG8_LDA(At, 1, 0); PG8_STAGE(PG8_SA(0, 1), a2 + hstepA, voffA);
;             PG8_WAIT_L(8); PG8_BAR; PG8_WAIT_L(0); PG8_MMA(0, 0, At, B0); PG8_BAR; PG8_SCHED;
;             PG8_LDB(B1, 1, 1); PG8_STAGE(PG8_SB(1, 0), b3, voffB);
;             PG8_BAR; PG8_WAIT_L(0); PG8_MMA(0, 1, At, B1); PG8_BAR;
;             PG8_LDA(At, 1, 1); PG8_STAGE(PG8_SA(1, 0), a3, voffA);
;             PG8_BAR; PG8_WAIT_L(0); PG8_MMA(1, 0, At, B0); PG8_BAR; PG8_SCHED;
.Lkmid_690:
	ds_read_b128 v[76:79], v196
	ds_read_b128 v[88:91], v196 offset:1024
	ds_read_b128 v[92:95], v196 offset:2048
	ds_read_b128 v[128:131], v196 offset:3072
	s_add_u32 s36, s36, s0
	s_addc_u32 s17, s26, s1
	s_and_b32 s37, s17, 0xffff
	s_mov_b32 m0, s82
	ds_read_b128 v[136:139], v194 offset:32768
	ds_read_b128 v[148:151], v194 offset:33792
	ds_read_b128 v[156:159], v194 offset:34816
	ds_read_b128 v[174:177], v194 offset:35840
	ds_read_b128 v[178:181], v194 offset:36864
	ds_read_b128 v[182:185], v194 offset:37888
	ds_read_b128 v[202:205], v194 offset:38912
	ds_read_b128 v[206:209], v194 offset:39936
	buffer_load_dwordx4 v186, s[36:39], 0 offen lds
	s_mov_b32 m0, s83
	s_nop 0
	buffer_load_dwordx4 v188, s[36:39], 0 offen lds
	s_waitcnt lgkmcnt(8)
	s_barrier
	s_waitcnt lgkmcnt(0)
	s_setprio 1
	s_waitcnt lgkmcnt(7)
	v_mfma_f32_16x16x32_bf16 v[152:155], v[76:79], v[136:139], v[152:155]
	v_mfma_f32_16x16x32_bf16 v[144:147], v[92:95], v[136:139], v[144:147]
	s_waitcnt lgkmcnt(5)
	v_mfma_f32_16x16x32_bf16 v[124:127], v[76:79], v[156:159], v[124:127]
	v_mfma_f32_16x16x32_bf16 v[120:123], v[92:95], v[156:159], v[120:123]
	s_waitcnt lgkmcnt(3)
	v_mfma_f32_16x16x32_bf16 v[108:111], v[76:79], v[178:181], v[108:111]
	v_mfma_f32_16x16x32_bf16 v[104:107], v[92:95], v[178:181], v[104:107]
	s_waitcnt lgkmcnt(1)
	v_mfma_f32_16x16x32_bf16 v[84:87], v[76:79], v[202:205], v[84:87]
	v_mfma_f32_16x16x32_bf16 v[80:83], v[92:95], v[202:205], v[80:83]
	v_mfma_f32_16x16x32_bf16 v[152:155], v[88:91], v[148:151], v[152:155]
	v_mfma_f32_16x16x32_bf16 v[144:147], v[128:131], v[148:151], v[144:147]
	v_mfma_f32_16x16x32_bf16 v[124:127], v[88:91], v[174:177], v[124:127]
	v_mfma_f32_16x16x32_bf16 v[120:123], v[128:131], v[174:177], v[120:123]
	v_mfma_f32_16x16x32_bf16 v[108:111], v[88:91], v[182:185], v[108:111]
	v_mfma_f32_16x16x32_bf16 v[104:107], v[128:131], v[182:185], v[104:107]
	s_waitcnt lgkmcnt(0)
	v_mfma_f32_16x16x32_bf16 v[84:87], v[88:91], v[206:209], v[84:87]
	v_mfma_f32_16x16x32_bf16 v[80:83], v[128:131], v[206:209], v[80:83]
	s_setprio 0
	s_barrier
	s_add_u32 s28, s28, 0x80
	s_addc_u32 s17, s25, 0
	s_and_b32 s29, s17, 0xffff
	s_mov_b32 m0, s85
	ds_read_b128 v[210:213], v197
	ds_read_b128 v[214:217], v197 offset:1024
	ds_read_b128 v[218:221], v197 offset:2048
	ds_read_b128 v[222:225], v197 offset:3072
	buffer_load_dwordx4 v187, s[28:31], 0 offen lds
	s_mov_b32 m0, s86
	s_nop 0
	buffer_load_dwordx4 v189, s[28:31], 0 offen lds
	s_barrier
	s_waitcnt lgkmcnt(0)
	s_setprio 1
	s_waitcnt lgkmcnt(3)
	v_mfma_f32_16x16x32_bf16 v[140:143], v[210:213], v[136:139], v[140:143]
	s_waitcnt lgkmcnt(1)
	v_mfma_f32_16x16x32_bf16 v[132:135], v[218:221], v[136:139], v[132:135]
	v_mfma_f32_16x16x32_bf16 v[116:119], v[210:213], v[156:159], v[116:119]
	v_mfma_f32_16x16x32_bf16 v[112:115], v[218:221], v[156:159], v[112:115]
	v_mfma_f32_16x16x32_bf16 v[100:103], v[210:213], v[178:181], v[100:103]
	v_mfma_f32_16x16x32_bf16 v[96:99], v[218:221], v[178:181], v[96:99]
	v_mfma_f32_16x16x32_bf16 v[68:71], v[210:213], v[202:205], v[68:71]
	v_mfma_f32_16x16x32_bf16 v[64:67], v[218:221], v[202:205], v[64:67]
	v_mfma_f32_16x16x32_bf16 v[156:159], v[214:217], v[148:151], v[140:143]
	s_waitcnt lgkmcnt(0)
	v_mfma_f32_16x16x32_bf16 v[148:151], v[222:225], v[148:151], v[132:135]
	v_mfma_f32_16x16x32_bf16 v[116:119], v[214:217], v[174:177], v[116:119]
	v_mfma_f32_16x16x32_bf16 v[112:115], v[222:225], v[174:177], v[112:115]
	v_mfma_f32_16x16x32_bf16 v[100:103], v[214:217], v[182:185], v[100:103]
	v_mfma_f32_16x16x32_bf16 v[96:99], v[222:225], v[182:185], v[96:99]
	v_mfma_f32_16x16x32_bf16 v[68:71], v[214:217], v[206:209], v[68:71]
	v_mfma_f32_16x16x32_bf16 v[64:67], v[222:225], v[206:209], v[64:67]
	s_setprio 0
	s_and_b32 s25, s23, 0xffff
	s_mov_b32 s26, s18
	s_mov_b32 s27, s19
	s_mov_b32 m0, s87
	s_barrier
; #define PG8_STAGE(bufoff, gbase, voff) do { const __amdgpu_buffer_rsrc_t _r = __builtin_amdgcn_make_buffer_rsrc((void*)(gbase), (short)0, 0x7fffffff, 0x00020000); _Pragma("unroll") for (int _i = 0; _i < 2; ++_i) \
;         __builtin_amdgcn_raw_ptr_buffer_load_lds(_r, (LAS unsigned*)(lds + (bufoff) + ldsw + _i * 8192), 16, (int)(voff)[_i], 0, 0, 0); } while (0)
; #define PG8_LDA(dst, b, h) do { _Pragma("unroll") for (int m = 0; m < 4; ++m) _Pragma("unroll") for (int k = 0; k < 2; ++k) dst[m][k] = *(const LAS bf16x8*)(lds + PG8_SA(b, h) + aoff + m * 2048 + k * 1024); } while (0)
; #define PG8_MMA(ai, bj, At, Bt) do { __builtin_amdgcn_s_setprio(1); _Pragma("unroll") for (int k = 0; k < 2; ++k) _Pragma("unroll") for (int m = 0; m < 4; ++m) _Pragma("unroll") for (int n = 0; n < ((bj) == 1 ? NB1 : 2); ++n) \
;         acc[ai][bj][m][n] = __builtin_amdgcn_mfma_f32_16x16x32_bf16(Bt[n][k], At[m][k], acc[ai][bj][m][n], 0, 0, 0); __builtin_amdgcn_s_setprio(0); } while (0)
; #define PG8_WAIT_V(n) asm volatile("s_waitcnt vmcnt(" #n ")" ::: "memory")
; #define PG8_WAIT_L(n) asm volatile("s_waitcnt lgkmcnt(" #n ")" ::: "memory")
; #define PG8_BAR __builtin_amdgcn_s_barrier()
; #define PG8_SCHED __builtin_amdgcn_sched_barrier(0)
;     ...
;             PG8_LDA(At, 1, 1); PG8_STAGE(PG8_SA(1, 0), a3, voffA);
;             PG8_BAR; PG8_WAIT_L(0); PG8_MMA(1, 0, At, B0); PG8_BAR; PG8_SCHED;
;             PG8_STAGE(PG8_SB(1, 1), b3 + hstepB, voffB);
;             PG8_WAIT_V(6); PG8_BAR; PG8_MMA(1, 1, At, B1); PG8_BAR;
;         }
	ds_read_b128 v[132:135], v194 offset:49152
	ds_read_b128 v[136:139], v194 offset:50176
	ds_read_b128 v[140:143], v194 offset:51200
	ds_read_b128 v[174:177], v194 offset:52224
	ds_read_b128 v[178:181], v194 offset:53248
	ds_read_b128 v[182:185], v194 offset:54272
	ds_read_b128 v[202:205], v194 offset:55296
	ds_read_b128 v[206:209], v194 offset:56320
	buffer_load_dwordx4 v186, s[24:27], 0 offen lds
	s_mov_b32 m0, s88
	s_nop 0
	buffer_load_dwordx4 v188, s[24:27], 0 offen lds
	s_barrier
	s_waitcnt lgkmcnt(0)
	s_setprio 1
	s_waitcnt lgkmcnt(7)
	v_mfma_f32_16x16x32_bf16 v[60:63], v[76:79], v[132:135], v[60:63]
	v_mfma_f32_16x16x32_bf16 v[52:55], v[92:95], v[132:135], v[52:55]
	s_waitcnt lgkmcnt(5)
	v_mfma_f32_16x16x32_bf16 v[44:47], v[76:79], v[140:143], v[44:47]
	v_mfma_f32_16x16x32_bf16 v[40:43], v[92:95], v[140:143], v[40:43]
	s_waitcnt lgkmcnt(3)
	v_mfma_f32_16x16x32_bf16 v[28:31], v[76:79], v[178:181], v[28:31]
	v_mfma_f32_16x16x32_bf16 v[24:27], v[92:95], v[178:181], v[24:27]
	s_waitcnt lgkmcnt(1)
	v_mfma_f32_16x16x32_bf16 v[12:15], v[76:79], v[202:205], v[12:15]
	v_mfma_f32_16x16x32_bf16 v[8:11], v[92:95], v[202:205], v[8:11]
	v_mfma_f32_16x16x32_bf16 v[60:63], v[88:91], v[136:139], v[60:63]
	v_mfma_f32_16x16x32_bf16 v[52:55], v[128:131], v[136:139], v[52:55]
	v_mfma_f32_16x16x32_bf16 v[44:47], v[88:91], v[174:177], v[44:47]
	v_mfma_f32_16x16x32_bf16 v[40:43], v[128:131], v[174:177], v[40:43]
	v_mfma_f32_16x16x32_bf16 v[28:31], v[88:91], v[182:185], v[28:31]
	v_mfma_f32_16x16x32_bf16 v[24:27], v[128:131], v[182:185], v[24:27]
	s_waitcnt lgkmcnt(0)
	v_mfma_f32_16x16x32_bf16 v[12:15], v[88:91], v[206:209], v[12:15]
	v_mfma_f32_16x16x32_bf16 v[8:11], v[128:131], v[206:209], v[8:11]
	s_setprio 0
	s_barrier
	s_add_u32 s16, s16, 0x80
	s_addc_u32 s17, s74, 0
	s_and_b32 s17, s17, 0xffff
	s_mov_b32 m0, s89
	s_nop 0
	buffer_load_dwordx4 v187, s[16:19], 0 offen lds
	s_mov_b32 m0, s90
	s_nop 0
	buffer_load_dwordx4 v189, s[16:19], 0 offen lds
	s_waitcnt vmcnt(6)
	s_barrier
	s_setprio 1
	v_mfma_f32_16x16x32_bf16 v[56:59], v[210:213], v[132:135], v[56:59]
	v_mfma_f32_16x16x32_bf16 v[48:51], v[218:221], v[132:135], v[48:51]
	v_mfma_f32_16x16x32_bf16 v[36:39], v[210:213], v[140:143], v[36:39]
	v_mfma_f32_16x16x32_bf16 v[32:35], v[218:221], v[140:143], v[32:35]
	v_mfma_f32_16x16x32_bf16 v[20:23], v[210:213], v[178:181], v[20:23]
	v_mfma_f32_16x16x32_bf16 v[16:19], v[218:221], v[178:181], v[16:19]
	v_mfma_f32_16x16x32_bf16 v[4:7], v[210:213], v[202:205], v[4:7]
	v_mfma_f32_16x16x32_bf16 v[0:3], v[218:221], v[202:205], v[0:3]
	v_mfma_f32_16x16x32_bf16 v[56:59], v[214:217], v[136:139], v[56:59]
	v_mfma_f32_16x16x32_bf16 v[48:51], v[222:225], v[136:139], v[48:51]
	v_mfma_f32_16x16x32_bf16 v[36:39], v[214:217], v[174:177], v[36:39]
	v_mfma_f32_16x16x32_bf16 v[32:35], v[222:225], v[174:177], v[32:35]
	v_mfma_f32_16x16x32_bf16 v[20:23], v[214:217], v[182:185], v[20:23]
	v_mfma_f32_16x16x32_bf16 v[16:19], v[222:225], v[182:185], v[16:19]
	v_mfma_f32_16x16x32_bf16 v[4:7], v[214:217], v[206:209], v[4:7]
	v_mfma_f32_16x16x32_bf16 v[0:3], v[222:225], v[206:209], v[0:3]
	s_setprio 0
	s_add_u32 vcc_lo, vcc_lo, 0x100
	s_addc_u32 vcc_hi, vcc_hi, 0
	s_add_u32 s3, s3, 0x100
	s_addc_u32 s46, s46, 0
	s_cmp_ge_i32 s22, s84
	s_mov_b32 s16, s22
	s_barrier
	s_cbranch_scc0 .LBB0_690
	v_readlane_b32 s96, v252, 38
	v_readlane_b32 s97, v252, 39

;     __device__ __forceinline__ size_t a_off(const Unit& u) const { return (size_t)u.pm * atile; }
;     __device__ __forceinline__ size_t b_off(const Unit& u) const { return (size_t)u.pn * btile; }
;     __device__ __forceinline__ bool next(int i, Unit& u) const { const long L = (long)i * G + c; if (L >= NG * 8) return false; u.g = (int)(L >> 3); u.pm = (int)(L & 7); u.pn = 0; return true; }
;     __device__ __forceinline__ size_t a_off(const Unit& u) const { return ((size_t)u.g * NROW + (size_t)u.pm * BM) * KA * 2; }
;     __device__ __forceinline__ size_t b_off(const Unit& u) const { return (size_t)u.g * btile; }
;     __device__ __forceinline__ bool next(int i, Unit& u) const { if (i >= 2) return false; u.g = g; u.pm = 2 * b + i; u.pn = 0; return true; }
;     __device__ __forceinline__ size_t a_off(const Unit& u) const { return ((size_t)u.g * NROW + (size_t)u.pm * BM) * KA * 2; }
;     __device__ __forceinline__ size_t b_off(const Unit& u) const { return (size_t)u.g * btile; }
; #define PG8_WAIT_L(n) asm volatile("s_waitcnt lgkmcnt(" #n ")" ::: "memory")
; #define PG8_BAR __builtin_amdgcn_s_barrier()
; #define PG8_SCHED __builtin_amdgcn_sched_barrier(0)
;     ...
;         const bool has_next = S.next(ui + 1, nxt);
;         const char* nA = has_next ? (const char*)Ap + S.a_off(nxt) : cA; const char* nB = has_next ? (const char*)Btp + S.b_off(nxt) : cB;
;         for (int t = 0; t < nt; t += 2) {
;             const bool last = (t == nt - 2);
;             const char* a1 = cA + (size_t)(t + 1) * kstep;
;             const char* a2 = last ? nA : cA + (size_t)(t + 2) * kstep; const char* b2 = last ? nB : cB + (size_t)(t + 2) * kstep;
;             const char* a3 = a2 + kstep; const char* b3 = b2 + kstep;
;             PG8_LDB(B0, 0, 0); PG8_SCHED; PG8_LDA(At, 0, 0); PG8_STAGE(PG8_SA(1, 1), a1 + hstepA, voffA);
;             PG8_WAIT_L(8); PG8_BAR; PG8_WAIT_L(0); PG8_MMA(0, 0, At, B0); PG8_BAR; PG8_SCHED;
;             PG8_LDB(B1, 0, 1); PG8_STAGE(PG8_SB(0, 0), b2, voffB);
;             PG8_BAR; PG8_WAIT_L(0); PG8_MMA(0, 1, At, B1); PG8_BAR;
;     ...
; #pragma unroll
;         for (int a = 0; a < 2; ++a)
; #pragma unroll
;             for (int b = 0; b < 2; ++b)
; #pragma unroll
;                 for (int m = 0; m < 4; ++m)
; #pragma unroll
;                     for (int n = 0; n < 2; ++n) acc[a][b][m][n] = (f32x4){0.f, 0.f, 0.f, 0.f};
.LBB0_770:
	s_andn2_b64 vcc, exec, s[46:47]
	s_waitcnt lgkmcnt(0)
	s_cbranch_vccnz .Lkzero_772
	s_add_u32 s89, s18, 0x100
	s_addc_u32 s90, s19, 0
	s_add_u32 s91, s16, 0x100
	s_addc_u32 s92, s17, 0
	s_mov_b32 s8, 0
	ds_read_b128 v[128:131], v227
	ds_read_b128 v[132:135], v227 offset:1024
	ds_read_b128 v[136:139], v227 offset:2048
	ds_read_b128 v[140:143], v227 offset:3072
	s_add_i32 s22, s8, 2
	s_cmp_eq_u32 s81, s8
	s_cselect_b32 s28, s0, s89
	s_cselect_b32 s19, s1, s90
	s_cselect_b32 s18, s51, s92
	s_cselect_b32 s24, s50, s91
	s_add_u32 s16, s28, 0x80
	s_addc_u32 s17, s19, 0
	s_add_u32 s8, s89, s36
	s_addc_u32 s9, s90, s37
	s_add_u32 s8, s8, 0xffffff80
	s_addc_u32 s9, s9, -1
	s_and_b32 s9, s9, 0xffff
	s_mov_b32 m0, s82
	ds_read_b128 v[144:147], v228
	ds_read_b128 v[148:151], v228 offset:1024
	ds_read_b128 v[152:155], v228 offset:2048
	ds_read_b128 v[156:159], v228 offset:3072
	ds_read_b128 v[160:163], v228 offset:4096
	ds_read_b128 v[164:167], v228 offset:5120
	ds_read_b128 v[168:171], v228 offset:6144
	ds_read_b128 v[172:175], v228 offset:7168
	buffer_load_dwordx4 v222, s[8:11], 0 offen lds
	s_mov_b32 m0, s83
	s_nop 0
	buffer_load_dwordx4 v224, s[8:11], 0 offen lds
	s_waitcnt lgkmcnt(8)
	s_barrier
	s_waitcnt lgkmcnt(0)
	s_setprio 1
	s_waitcnt lgkmcnt(7)
	v_mfma_f32_16x16x32_bf16 v[120:123], v[128:131], v[144:147], 0
	v_mfma_f32_16x16x32_bf16 v[124:127], v[136:139], v[144:147], 0
	s_waitcnt lgkmcnt(5)
	v_mfma_f32_16x16x32_bf16 v[108:111], v[128:131], v[152:155], 0
	v_mfma_f32_16x16x32_bf16 v[104:107], v[136:139], v[152:155], 0
	s_waitcnt lgkmcnt(3)
	v_mfma_f32_16x16x32_bf16 v[92:95], v[128:131], v[160:163], 0
	v_mfma_f32_16x16x32_bf16 v[88:91], v[136:139], v[160:163], 0
	s_waitcnt lgkmcnt(1)
	v_mfma_f32_16x16x32_bf16 v[76:79], v[128:131], v[168:171], 0
	v_mfma_f32_16x16x32_bf16 v[72:75], v[136:139], v[168:171], 0
	v_mfma_f32_16x16x32_bf16 v[120:123], v[132:135], v[148:151], v[120:123]
	v_mfma_f32_16x16x32_bf16 v[124:127], v[140:143], v[148:151], v[124:127]
	v_mfma_f32_16x16x32_bf16 v[108:111], v[132:135], v[156:159], v[108:111]
	v_mfma_f32_16x16x32_bf16 v[104:107], v[140:143], v[156:159], v[104:107]
	v_mfma_f32_16x16x32_bf16 v[92:95], v[132:135], v[164:167], v[92:95]
	v_mfma_f32_16x16x32_bf16 v[88:91], v[140:143], v[164:167], v[88:91]
	s_waitcnt lgkmcnt(0)
	v_mfma_f32_16x16x32_bf16 v[76:79], v[132:135], v[172:175], v[76:79]
	v_mfma_f32_16x16x32_bf16 v[72:75], v[140:143], v[172:175], v[72:75]
	s_setprio 0
	s_barrier
	s_and_b32 s25, s18, 0xffff
	s_mov_b32 s26, s10
	s_mov_b32 s27, s11
	s_mov_b32 m0, s64
	ds_read_b128 v[176:179], v229
	ds_read_b128 v[180:183], v229 offset:1024
	ds_read_b128 v[192:195], v229 offset:2048
	ds_read_b128 v[196:199], v229 offset:3072
	buffer_load_dwordx4 v223, s[24:27], 0 offen lds
	s_mov_b32 m0, s65
	s_nop 0
	buffer_load_dwordx4 v225, s[24:27], 0 offen lds
	s_barrier
	s_waitcnt lgkmcnt(0)
	s_setprio 1
	s_waitcnt lgkmcnt(3)
	v_mfma_f32_16x16x32_bf16 v[116:119], v[176:179], v[144:147], 0
	s_waitcnt lgkmcnt(1)
	v_mfma_f32_16x16x32_bf16 v[112:115], v[192:195], v[144:147], 0
	v_mfma_f32_16x16x32_bf16 v[100:103], v[176:179], v[152:155], 0
	v_mfma_f32_16x16x32_bf16 v[96:99], v[192:195], v[152:155], 0
	v_mfma_f32_16x16x32_bf16 v[84:87], v[176:179], v[160:163], 0
	v_mfma_f32_16x16x32_bf16 v[80:83], v[192:195], v[160:163], 0
	v_mfma_f32_16x16x32_bf16 v[68:71], v[176:179], v[168:171], 0
	v_mfma_f32_16x16x32_bf16 v[64:67], v[192:195], v[168:171], 0
	v_mfma_f32_16x16x32_bf16 v[116:119], v[180:183], v[148:151], v[116:119]
	s_waitcnt lgkmcnt(0)
	v_mfma_f32_16x16x32_bf16 v[112:115], v[196:199], v[148:151], v[112:115]
	v_mfma_f32_16x16x32_bf16 v[100:103], v[180:183], v[156:159], v[100:103]
	v_mfma_f32_16x16x32_bf16 v[96:99], v[196:199], v[156:159], v[96:99]
	v_mfma_f32_16x16x32_bf16 v[84:87], v[180:183], v[164:167], v[84:87]
	v_mfma_f32_16x16x32_bf16 v[80:83], v[196:199], v[164:167], v[80:83]
	v_mfma_f32_16x16x32_bf16 v[68:71], v[180:183], v[172:175], v[68:71]
	v_mfma_f32_16x16x32_bf16 v[64:67], v[196:199], v[172:175], v[64:67]
	s_setprio 0
	s_and_b32 s29, s19, 0xffff
	s_mov_b32 s30, s10
	s_mov_b32 s31, s11
	s_mov_b32 m0, s59
	s_barrier
; #define PG8_STAGE(bufoff, gbase, voff) do { const __amdgpu_buffer_rsrc_t _r = __builtin_amdgcn_make_buffer_rsrc((void*)(gbase), (short)0, 0x7fffffff, 0x00020000); _Pragma("unroll") for (int _i = 0; _i < 2; ++_i) \
;         __builtin_amdgcn_raw_ptr_buffer_load_lds(_r, (LAS unsigned*)(lds + (bufoff) + ldsw + _i * 8192), 16, (int)(voff)[_i], 0, 0, 0); } while (0)
; #define PG8_LDA(dst, b, h) do { _Pragma("unroll") for (int m = 0; m < 4; ++m) _Pragma("unroll") for (int k = 0; k < 2; ++k) dst[m][k] = *(const LAS bf16x8*)(lds + PG8_SA(b, h) + aoff + m * 2048 + k * 1024); } while (0)
; #define PG8_MMA(ai, bj, At, Bt) do { __builtin_amdgcn_s_setprio(1); _Pragma("unroll") for (int k = 0; k < 2; ++k) _Pragma("unroll") for (int m = 0; m < 4; ++m) _Pragma("unroll") for (int n = 0; n < ((bj) == 1 ? NB1 : 2); ++n) \
;         acc[ai][bj][m][n] = __builtin_amdgcn_mfma_f32_16x16x32_bf16(Bt[n][k], At[m][k], acc[ai][bj][m][n], 0, 0, 0); __builtin_amdgcn_s_setprio(0); } while (0)
; #define PG8_WAIT_V(n) asm volatile("s_waitcnt vmcnt(" #n ")" ::: "memory")
; #define PG8_WAIT_L(n) asm volatile("s_waitcnt lgkmcnt(" #n ")" ::: "memory")
; #define PG8_BAR __builtin_amdgcn_s_barrier()
; #define PG8_SCHED __builtin_amdgcn_sched_barrier(0)
;     ...
;             PG8_LDA(At, 0, 1); PG8_STAGE(PG8_SA(0, 0), a2, voffA);
;             PG8_BAR; PG8_WAIT_L(0); PG8_MMA(1, 0, At, B0); PG8_BAR; PG8_SCHED;
;             PG8_STAGE(PG8_SB(0, 1), b2 + hstepB, voffB);
;             PG8_WAIT_V(6); PG8_BAR; PG8_MMA(1, 1, At, B1); PG8_BAR;
	ds_read_b128 v[144:147], v228 offset:16384
	ds_read_b128 v[148:151], v228 offset:17408
	ds_read_b128 v[152:155], v228 offset:18432
	ds_read_b128 v[156:159], v228 offset:19456
	ds_read_b128 v[160:163], v228 offset:20480
	ds_read_b128 v[164:167], v228 offset:21504
	ds_read_b128 v[168:171], v228 offset:22528
	ds_read_b128 v[172:175], v228 offset:23552
	buffer_load_dwordx4 v222, s[28:31], 0 offen lds
	s_mov_b32 m0, s67
	s_nop 0
	buffer_load_dwordx4 v224, s[28:31], 0 offen lds
	s_barrier
	s_waitcnt lgkmcnt(0)
	s_setprio 1
	s_waitcnt lgkmcnt(7)
	v_mfma_f32_16x16x32_bf16 v[60:63], v[128:131], v[144:147], 0
	v_mfma_f32_16x16x32_bf16 v[56:59], v[136:139], v[144:147], 0
	s_waitcnt lgkmcnt(5)
	v_mfma_f32_16x16x32_bf16 v[44:47], v[128:131], v[152:155], 0
	v_mfma_f32_16x16x32_bf16 v[40:43], v[136:139], v[152:155], 0
	s_waitcnt lgkmcnt(3)
	v_mfma_f32_16x16x32_bf16 v[28:31], v[128:131], v[160:163], 0
	v_mfma_f32_16x16x32_bf16 v[24:27], v[136:139], v[160:163], 0
	s_waitcnt lgkmcnt(1)
	v_mfma_f32_16x16x32_bf16 v[12:15], v[128:131], v[168:171], 0
	v_mfma_f32_16x16x32_bf16 v[8:11], v[136:139], v[168:171], 0
	v_mfma_f32_16x16x32_bf16 v[60:63], v[132:135], v[148:151], v[60:63]
	v_mfma_f32_16x16x32_bf16 v[56:59], v[140:143], v[148:151], v[56:59]
	v_mfma_f32_16x16x32_bf16 v[44:47], v[132:135], v[156:159], v[44:47]
	v_mfma_f32_16x16x32_bf16 v[40:43], v[140:143], v[156:159], v[40:43]
	v_mfma_f32_16x16x32_bf16 v[28:31], v[132:135], v[164:167], v[28:31]
	v_mfma_f32_16x16x32_bf16 v[24:27], v[140:143], v[164:167], v[24:27]
	s_waitcnt lgkmcnt(0)
	v_mfma_f32_16x16x32_bf16 v[12:15], v[132:135], v[172:175], v[12:15]
	v_mfma_f32_16x16x32_bf16 v[8:11], v[140:143], v[172:175], v[8:11]
	s_setprio 0
	s_barrier
	s_add_u32 s8, s24, s38
	s_addc_u32 s23, s18, s39
	s_and_b32 s9, s23, 0xffff
	s_mov_b32 m0, s70
	s_nop 0
	buffer_load_dwordx4 v223, s[8:11], 0 offen lds
	s_mov_b32 m0, s71
	s_nop 0
	buffer_load_dwordx4 v225, s[8:11], 0 offen lds
	s_waitcnt vmcnt(6)
	s_barrier
	s_setprio 1
	v_mfma_f32_16x16x32_bf16 v[52:55], v[176:179], v[144:147], 0
	v_mfma_f32_16x16x32_bf16 v[48:51], v[192:195], v[144:147], 0
	v_mfma_f32_16x16x32_bf16 v[36:39], v[176:179], v[152:155], 0
	v_mfma_f32_16x16x32_bf16 v[32:35], v[192:195], v[152:155], 0
	v_mfma_f32_16x16x32_bf16 v[20:23], v[176:179], v[160:163], 0
	v_mfma_f32_16x16x32_bf16 v[16:19], v[192:195], v[160:163], 0
	v_mfma_f32_16x16x32_bf16 v[4:7], v[176:179], v[168:171], 0
	v_mfma_f32_16x16x32_bf16 v[0:3], v[192:195], v[168:171], 0
	v_mfma_f32_16x16x32_bf16 v[52:55], v[180:183], v[148:151], v[52:55]
	v_mfma_f32_16x16x32_bf16 v[48:51], v[196:199], v[148:151], v[48:51]
	v_mfma_f32_16x16x32_bf16 v[36:39], v[180:183], v[156:159], v[36:39]
	v_mfma_f32_16x16x32_bf16 v[32:35], v[196:199], v[156:159], v[32:35]
	v_mfma_f32_16x16x32_bf16 v[20:23], v[180:183], v[164:167], v[20:23]
	v_mfma_f32_16x16x32_bf16 v[16:19], v[196:199], v[164:167], v[16:19]
	v_mfma_f32_16x16x32_bf16 v[4:7], v[180:183], v[172:175], v[4:7]
	v_mfma_f32_16x16x32_bf16 v[0:3], v[196:199], v[172:175], v[0:3]
	s_setprio 0
	s_barrier
	s_branch .Lkmid_772

; #define PG8_STAGE(bufoff, gbase, voff) do { const __amdgpu_buffer_rsrc_t _r = __builtin_amdgcn_make_buffer_rsrc((void*)(gbase), (short)0, 0x7fffffff, 0x00020000); _Pragma("unroll") for (int _i = 0; _i < 2; ++_i) \
;         __builtin_amdgcn_raw_ptr_buffer_load_lds(_r, (LAS unsigned*)(lds + (bufoff) + ldsw + _i * 8192), 16, (int)(voff)[_i], 0, 0, 0); } while (0)
; #define PG8_LDA(dst, b, h) do { _Pragma("unroll") for (int m = 0; m < 4; ++m) _Pragma("unroll") for (int k = 0; k < 2; ++k) dst[m][k] = *(const LAS bf16x8*)(lds + PG8_SA(b, h) + aoff + m * 2048 + k * 1024); } while (0)
; #define PG8_LDB(dst, b, h) do { _Pragma("unroll") for (int n = 0; n < 2; ++n) _Pragma("unroll") for (int k = 0; k < 2; ++k) dst[n][k] = *(const LAS bf16x8*)(lds + PG8_SB(b, h) + boff + n * 2048 + k * 1024); } while (0)
; #define PG8_MMA(ai, bj, At, Bt) do { __builtin_amdgcn_s_setprio(1); _Pragma("unroll") for (int k = 0; k < 2; ++k) _Pragma("unroll") for (int m = 0; m < 4; ++m) _Pragma("unroll") for (int n = 0; n < ((bj) == 1 ? NB1 : 2); ++n) \
;         acc[ai][bj][m][n] = __builtin_amdgcn_mfma_f32_16x16x32_bf16(Bt[n][k], At[m][k], acc[ai][bj][m][n], 0, 0, 0); __builtin_amdgcn_s_setprio(0); } while (0)
; #define PG8_WAIT_L(n) asm volatile("s_waitcnt lgkmcnt(" #n ")" ::: "memory")
; #define PG8_BAR __builtin_amdgcn_s_barrier()
; #define PG8_SCHED __builtin_amdgcn_sched_barrier(0)
;     ...
;             PG8_LDB(B0, 1, 0); PG8_SCHED; PG8_LDA(At, 1, 0); PG8_STAGE(PG8_SA(0, 1), a2 + hstepA, voffA);
;             PG8_WAIT_L(8); PG8_BAR; PG8_WAIT_L(0); PG8_MMA(0, 0, At, B0); PG8_BAR; PG8_SCHED;
;             PG8_LDB(B1, 1, 1); PG8_STAGE(PG8_SB(1, 0), b3, voffB);
;             PG8_BAR; PG8_WAIT_L(0); PG8_MMA(0, 1, At, B1); PG8_BAR;
;             PG8_LDA(At, 1, 1); PG8_STAGE(PG8_SA(1, 0), a3, voffA);
;             PG8_BAR; PG8_WAIT_L(0); PG8_MMA(1, 0, At, B0); PG8_BAR; PG8_SCHED;
.Lkmid_772:
	ds_read_b128 v[128:131], v230
	ds_read_b128 v[132:135], v230 offset:1024
	ds_read_b128 v[136:139], v230 offset:2048
	ds_read_b128 v[140:143], v230 offset:3072
	s_add_u32 s28, s28, s36
	s_addc_u32 s9, s19, s37
	s_and_b32 s29, s9, 0xffff
	s_mov_b32 m0, s72
	ds_read_b128 v[144:147], v228 offset:32768
	ds_read_b128 v[148:151], v228 offset:33792
	ds_read_b128 v[152:155], v228 offset:34816
	ds_read_b128 v[156:159], v228 offset:35840
	ds_read_b128 v[160:163], v228 offset:36864
	ds_read_b128 v[164:167], v228 offset:37888
	ds_read_b128 v[168:171], v228 offset:38912
	ds_read_b128 v[172:175], v228 offset:39936
	buffer_load_dwordx4 v222, s[28:31], 0 offen lds
	s_mov_b32 m0, s73
	s_nop 0
	buffer_load_dwordx4 v224, s[28:31], 0 offen lds
	s_waitcnt lgkmcnt(8)
	s_barrier
	s_waitcnt lgkmcnt(0)
	s_setprio 1
	s_waitcnt lgkmcnt(7)
	v_mfma_f32_16x16x32_bf16 v[120:123], v[128:131], v[144:147], v[120:123]
	v_mfma_f32_16x16x32_bf16 v[124:127], v[136:139], v[144:147], v[124:127]
	s_waitcnt lgkmcnt(5)
	v_mfma_f32_16x16x32_bf16 v[108:111], v[128:131], v[152:155], v[108:111]
	v_mfma_f32_16x16x32_bf16 v[104:107], v[136:139], v[152:155], v[104:107]
	s_waitcnt lgkmcnt(3)
	v_mfma_f32_16x16x32_bf16 v[92:95], v[128:131], v[160:163], v[92:95]
	v_mfma_f32_16x16x32_bf16 v[88:91], v[136:139], v[160:163], v[88:91]
	s_waitcnt lgkmcnt(1)
	v_mfma_f32_16x16x32_bf16 v[76:79], v[128:131], v[168:171], v[76:79]
	v_mfma_f32_16x16x32_bf16 v[72:75], v[136:139], v[168:171], v[72:75]
	v_mfma_f32_16x16x32_bf16 v[120:123], v[132:135], v[148:151], v[120:123]
	v_mfma_f32_16x16x32_bf16 v[124:127], v[140:143], v[148:151], v[124:127]
	v_mfma_f32_16x16x32_bf16 v[108:111], v[132:135], v[156:159], v[108:111]
	v_mfma_f32_16x16x32_bf16 v[104:107], v[140:143], v[156:159], v[104:107]
	v_mfma_f32_16x16x32_bf16 v[92:95], v[132:135], v[164:167], v[92:95]
	v_mfma_f32_16x16x32_bf16 v[88:91], v[140:143], v[164:167], v[88:91]
	s_waitcnt lgkmcnt(0)
	v_mfma_f32_16x16x32_bf16 v[76:79], v[132:135], v[172:175], v[76:79]
	v_mfma_f32_16x16x32_bf16 v[72:75], v[140:143], v[172:175], v[72:75]
	s_setprio 0
	s_barrier
	s_add_u32 s24, s24, 0x80
	s_addc_u32 s9, s18, 0
	s_and_b32 s25, s9, 0xffff
	s_mov_b32 m0, s75
	ds_read_b128 v[176:179], v231
	ds_read_b128 v[180:183], v231 offset:1024
	ds_read_b128 v[192:195], v231 offset:2048
	ds_read_b128 v[196:199], v231 offset:3072
	buffer_load_dwordx4 v223, s[24:27], 0 offen lds
	s_mov_b32 m0, s76
	s_nop 0
	buffer_load_dwordx4 v225, s[24:27], 0 offen lds
	s_barrier
	s_waitcnt lgkmcnt(0)
	s_setprio 1
	s_waitcnt lgkmcnt(3)
	v_mfma_f32_16x16x32_bf16 v[116:119], v[176:179], v[144:147], v[116:119]
	s_waitcnt lgkmcnt(1)
	v_mfma_f32_16x16x32_bf16 v[112:115], v[192:195], v[144:147], v[112:115]
	v_mfma_f32_16x16x32_bf16 v[100:103], v[176:179], v[152:155], v[100:103]
	v_mfma_f32_16x16x32_bf16 v[96:99], v[192:195], v[152:155], v[96:99]
	v_mfma_f32_16x16x32_bf16 v[84:87], v[176:179], v[160:163], v[84:87]
	v_mfma_f32_16x16x32_bf16 v[80:83], v[192:195], v[160:163], v[80:83]
	v_mfma_f32_16x16x32_bf16 v[68:71], v[176:179], v[168:171], v[68:71]
	v_mfma_f32_16x16x32_bf16 v[64:67], v[192:195], v[168:171], v[64:67]
	v_mfma_f32_16x16x32_bf16 v[116:119], v[180:183], v[148:151], v[116:119]
	s_waitcnt lgkmcnt(0)
	v_mfma_f32_16x16x32_bf16 v[112:115], v[196:199], v[148:151], v[112:115]
	v_mfma_f32_16x16x32_bf16 v[100:103], v[180:183], v[156:159], v[100:103]
	v_mfma_f32_16x16x32_bf16 v[96:99], v[196:199], v[156:159], v[96:99]
	v_mfma_f32_16x16x32_bf16 v[84:87], v[180:183], v[164:167], v[84:87]
	v_mfma_f32_16x16x32_bf16 v[80:83], v[196:199], v[164:167], v[80:83]
	v_mfma_f32_16x16x32_bf16 v[68:71], v[180:183], v[172:175], v[68:71]
	v_mfma_f32_16x16x32_bf16 v[64:67], v[196:199], v[172:175], v[64:67]
	s_setprio 0
	s_and_b32 s17, s17, 0xffff
	s_mov_b32 s18, s10
	s_mov_b32 s19, s11
	s_mov_b32 m0, s77
	s_barrier
; #define PG8_STAGE(bufoff, gbase, voff) do { const __amdgpu_buffer_rsrc_t _r = __builtin_amdgcn_make_buffer_rsrc((void*)(gbase), (short)0, 0x7fffffff, 0x00020000); _Pragma("unroll") for (int _i = 0; _i < 2; ++_i) \
;         __builtin_amdgcn_raw_ptr_buffer_load_lds(_r, (LAS unsigned*)(lds + (bufoff) + ldsw + _i * 8192), 16, (int)(voff)[_i], 0, 0, 0); } while (0)
; #define PG8_LDA(dst, b, h) do { _Pragma("unroll") for (int m = 0; m < 4; ++m) _Pragma("unroll") for (int k = 0; k < 2; ++k) dst[m][k] = *(const LAS bf16x8*)(lds + PG8_SA(b, h) + aoff + m * 2048 + k * 1024); } while (0)
; #define PG8_MMA(ai, bj, At, Bt) do { __builtin_amdgcn_s_setprio(1); _Pragma("unroll") for (int k = 0; k < 2; ++k) _Pragma("unroll") for (int m = 0; m < 4; ++m) _Pragma("unroll") for (int n = 0; n < ((bj) == 1 ? NB1 : 2); ++n) \
;         acc[ai][bj][m][n] = __builtin_amdgcn_mfma_f32_16x16x32_bf16(Bt[n][k], At[m][k], acc[ai][bj][m][n], 0, 0, 0); __builtin_amdgcn_s_setprio(0); } while (0)
; #define PG8_WAIT_V(n) asm volatile("s_waitcnt vmcnt(" #n ")" ::: "memory")
; #define PG8_WAIT_L(n) asm volatile("s_waitcnt lgkmcnt(" #n ")" ::: "memory")
; #define PG8_BAR __builtin_amdgcn_s_barrier()
; #define PG8_SCHED __builtin_amdgcn_sched_barrier(0)
;     ...
;             PG8_LDA(At, 1, 1); PG8_STAGE(PG8_SA(1, 0), a3, voffA);
;             PG8_BAR; PG8_WAIT_L(0); PG8_MMA(1, 0, At, B0); PG8_BAR; PG8_SCHED;
;             PG8_STAGE(PG8_SB(1, 1), b3 + hstepB, voffB);
;             PG8_WAIT_V(6); PG8_BAR; PG8_MMA(1, 1, At, B1); PG8_BAR;
;         }
	ds_read_b128 v[144:147], v228 offset:49152
	ds_read_b128 v[148:151], v228 offset:50176
	ds_read_b128 v[152:155], v228 offset:51200
	ds_read_b128 v[156:159], v228 offset:52224
	ds_read_b128 v[160:163], v228 offset:53248
	ds_read_b128 v[164:167], v228 offset:54272
	ds_read_b128 v[168:171], v228 offset:55296
	ds_read_b128 v[172:175], v228 offset:56320
	buffer_load_dwordx4 v222, s[16:19], 0 offen lds
	s_mov_b32 m0, s78
	s_nop 0
	buffer_load_dwordx4 v224, s[16:19], 0 offen lds
	s_barrier
	s_waitcnt lgkmcnt(0)
	s_setprio 1
	s_waitcnt lgkmcnt(7)
	v_mfma_f32_16x16x32_bf16 v[60:63], v[128:131], v[144:147], v[60:63]
	v_mfma_f32_16x16x32_bf16 v[56:59], v[136:139], v[144:147], v[56:59]
	s_waitcnt lgkmcnt(5)
	v_mfma_f32_16x16x32_bf16 v[44:47], v[128:131], v[152:155], v[44:47]
	v_mfma_f32_16x16x32_bf16 v[40:43], v[136:139], v[152:155], v[40:43]
	s_waitcnt lgkmcnt(3)
	v_mfma_f32_16x16x32_bf16 v[28:31], v[128:131], v[160:163], v[28:31]
	v_mfma_f32_16x16x32_bf16 v[24:27], v[136:139], v[160:163], v[24:27]
	s_waitcnt lgkmcnt(1)
	v_mfma_f32_16x16x32_bf16 v[12:15], v[128:131], v[168:171], v[12:15]
	v_mfma_f32_16x16x32_bf16 v[8:11], v[136:139], v[168:171], v[8:11]
	v_mfma_f32_16x16x32_bf16 v[60:63], v[132:135], v[148:151], v[60:63]
	v_mfma_f32_16x16x32_bf16 v[56:59], v[140:143], v[148:151], v[56:59]
	v_mfma_f32_16x16x32_bf16 v[44:47], v[132:135], v[156:159], v[44:47]
	v_mfma_f32_16x16x32_bf16 v[40:43], v[140:143], v[156:159], v[40:43]
	v_mfma_f32_16x16x32_bf16 v[28:31], v[132:135], v[164:167], v[28:31]
	v_mfma_f32_16x16x32_bf16 v[24:27], v[140:143], v[164:167], v[24:27]
	s_waitcnt lgkmcnt(0)
	v_mfma_f32_16x16x32_bf16 v[12:15], v[132:135], v[172:175], v[12:15]
	v_mfma_f32_16x16x32_bf16 v[8:11], v[140:143], v[172:175], v[8:11]
	s_setprio 0
	s_barrier
	s_add_u32 s8, s8, 0x80
	s_addc_u32 s9, s23, 0
	s_and_b32 s9, s9, 0xffff
	s_mov_b32 m0, s79
	s_nop 0
	buffer_load_dwordx4 v223, s[8:11], 0 offen lds
	s_mov_b32 m0, s80
	s_nop 0
	buffer_load_dwordx4 v225, s[8:11], 0 offen lds
	s_waitcnt vmcnt(6)
	s_barrier
	s_setprio 1
	v_mfma_f32_16x16x32_bf16 v[52:55], v[176:179], v[144:147], v[52:55]
	v_mfma_f32_16x16x32_bf16 v[48:51], v[192:195], v[144:147], v[48:51]
	v_mfma_f32_16x16x32_bf16 v[36:39], v[176:179], v[152:155], v[36:39]
	v_mfma_f32_16x16x32_bf16 v[32:35], v[192:195], v[152:155], v[32:35]
	v_mfma_f32_16x16x32_bf16 v[20:23], v[176:179], v[160:163], v[20:23]
	v_mfma_f32_16x16x32_bf16 v[16:19], v[192:195], v[160:163], v[16:19]
	v_mfma_f32_16x16x32_bf16 v[4:7], v[176:179], v[168:171], v[4:7]
	v_mfma_f32_16x16x32_bf16 v[0:3], v[192:195], v[168:171], v[0:3]
	v_mfma_f32_16x16x32_bf16 v[52:55], v[180:183], v[148:151], v[52:55]
	v_mfma_f32_16x16x32_bf16 v[48:51], v[196:199], v[148:151], v[48:51]
	v_mfma_f32_16x16x32_bf16 v[36:39], v[180:183], v[156:159], v[36:39]
	v_mfma_f32_16x16x32_bf16 v[32:35], v[196:199], v[156:159], v[32:35]
	v_mfma_f32_16x16x32_bf16 v[20:23], v[180:183], v[164:167], v[20:23]
	v_mfma_f32_16x16x32_bf16 v[16:19], v[196:199], v[164:167], v[16:19]
	v_mfma_f32_16x16x32_bf16 v[4:7], v[180:183], v[172:175], v[4:7]
	v_mfma_f32_16x16x32_bf16 v[0:3], v[196:199], v[172:175], v[0:3]
	s_setprio 0
	s_add_u32 s89, s89, 0x100
	s_addc_u32 s90, s90, 0
	s_add_u32 s91, s91, 0x100
	s_addc_u32 s92, s92, 0
	s_cmp_ge_i32 s22, s74
	s_mov_b32 s8, s22
	s_barrier
	s_cbranch_scc0 .LBB0_772

;     __device__ __forceinline__ size_t a_off(const Unit& u) const { return (size_t)u.pm * atile; }
;     __device__ __forceinline__ size_t b_off(const Unit& u) const { return (size_t)u.pn * btile; }
;     __device__ __forceinline__ bool next(int i, Unit& u) const { const long L = (long)i * G + c; if (L >= NG * 8) return false; u.g = (int)(L >> 3); u.pm = (int)(L & 7); u.pn = 0; return true; }
;     __device__ __forceinline__ size_t a_off(const Unit& u) const { return ((size_t)u.g * NROW + (size_t)u.pm * BM) * KA * 2; }
;     __device__ __forceinline__ size_t b_off(const Unit& u) const { return (size_t)u.g * btile; }
;     __device__ __forceinline__ bool next(int i, Unit& u) const {
;         const long L = (long)i * G + c; if (L >= nwg) return false;
;         int wgid = (int)L; { const int q = nwg / NXCD, r = nwg % NXCD, xcd = wgid % NXCD, off = wgid / NXCD; wgid = (xcd < r ? xcd * (q + 1) : r * (q + 1) + (xcd - r) * q) + off; }
;         const int nig = WGM * nN, gid = wgid / nig, fm = gid * WGM, gsz = (nM - fm) < WGM ? (nM - fm) : WGM;
;         u.pm = __builtin_amdgcn_readfirstlane(fm + ((wgid % nig) % gsz)); u.pn = __builtin_amdgcn_readfirstlane((wgid % nig) / gsz); u.g = 0; return true;
;     ...
;         const bool has_next = S.next(ui + 1, nxt);
;         const char* nA = has_next ? (const char*)Ap + S.a_off(nxt) : cA; const char* nB = has_next ? (const char*)Btp + S.b_off(nxt) : cB;
;         for (int t = 0; t < nt; t += 2) {
;             const bool last = (t == nt - 2);
;             const char* a1 = cA + (size_t)(t + 1) * kstep;
;             const char* a2 = last ? nA : cA + (size_t)(t + 2) * kstep; const char* b2 = last ? nB : cB + (size_t)(t + 2) * kstep;
;             const char* a3 = a2 + kstep; const char* b3 = b2 + kstep;
;             PG8_LDB(B0, 0, 0); PG8_SCHED; PG8_LDA(At, 0, 0); PG8_STAGE(PG8_SA(1, 1), a1 + hstepA, voffA);
;             PG8_WAIT_L(8); PG8_BAR; PG8_WAIT_L(0); PG8_MMA(0, 0, At, B0); PG8_BAR; PG8_SCHED;
;             PG8_LDB(B1, 0, 1); PG8_STAGE(PG8_SB(0, 0), b2, voffB);
;             PG8_BAR; PG8_WAIT_L(0); PG8_MMA(0, 1, At, B1); PG8_BAR;
;             PG8_LDA(At, 0, 1); PG8_STAGE(PG8_SA(0, 0), a2, voffA);
;             PG8_BAR; PG8_WAIT_L(0); PG8_MMA(1, 0, At, B0); PG8_BAR; PG8_SCHED;
;             PG8_STAGE(PG8_SB(0, 1), b2 + hstepB, voffB);
;             PG8_WAIT_V(6); PG8_BAR; PG8_MMA(1, 1, At, B1); PG8_BAR;
.LBB0_836:
	s_add_i32 s47, s47, 1
	s_mul_i32 s12, s47, s3
	s_mul_hi_u32 s13, s47, s34
	s_add_i32 s13, s13, s12
	s_mul_i32 s12, s47, s34
	s_add_u32 s12, s12, s2
	s_addc_u32 s13, s13, s90
	v_cmp_gt_i64_e32 vcc, s[12:13], v[120:121]
	s_cbranch_vccnz .LBB0_842
	s_add_i32 s52, s72, 4
	s_cmp_ge_i32 s52, 16
	s_cselect_b32 s16, 16, 0
	s_cselect_b32 s17, 8, 0
	s_sub_i32 s52, s52, s16
	s_add_i32 s58, s70, s17
.LBB0_842:
	s_ashr_i32 s59, s58, 31
	s_lshl_b64 s[16:17], s[58:59], 19
	s_add_u32 s64, s20, s16
	s_addc_u32 s65, s21, s17
	s_ashr_i32 s53, s52, 31
	s_lshl_b64 s[16:17], s[52:53], 19
	s_add_u32 s66, s33, s16
	v_cmp_lt_i64_e64 s[12:13], s[12:13], v[118:119]
	s_addc_u32 s67, s35, s17
	s_andn2_b64 vcc, exec, s[68:69]
	s_cbranch_vccnz .Lkzero_844
	s_and_b64 s[16:17], s[12:13], exec
	s_cselect_b32 s22, s65, s27
	s_cselect_b32 s23, s64, s26
	s_cselect_b32 s53, s67, s25
	s_cselect_b32 s59, s66, s24
	s_add_u32 s94, s26, 0x100
	s_addc_u32 s95, s27, 0
	s_add_u32 s96, s24, 0x100
	s_addc_u32 s97, s25, 0
	s_mov_b32 s16, 0
	ds_read_b128 v[100:103], v141
	ds_read_b128 v[104:107], v141 offset:1024
	ds_read_b128 v[122:125], v141 offset:2048
	ds_read_b128 v[126:129], v141 offset:3072
	s_add_i32 vcc_lo, s16, 2
	s_cmp_eq_u32 s87, s16
	s_cselect_b32 s36, s23, s94
	s_cselect_b32 s26, s22, s95
	s_cselect_b32 s27, s53, s97
	s_cselect_b32 s28, s59, s96
	s_add_u32 s24, s36, 0x80
	s_addc_u32 s25, s26, 0
	s_add_u32 s16, s94, s0
	s_addc_u32 s17, s95, s1
	s_add_u32 s16, s16, 0xffffff80
	s_addc_u32 s17, s17, -1
	s_and_b32 s17, s17, 0xffff
	s_mov_b32 m0, s88
	ds_read_b128 v[130:133], v142
	ds_read_b128 v[150:153], v142 offset:1024
	ds_read_b128 v[154:157], v142 offset:2048
	ds_read_b128 v[158:161], v142 offset:3072
	ds_read_b128 v[162:165], v142 offset:4096
	ds_read_b128 v[166:169], v142 offset:5120
	ds_read_b128 v[170:173], v142 offset:6144
	ds_read_b128 v[174:177], v142 offset:7168
	buffer_load_dwordx4 v134, s[16:19], 0 offen lds
	s_mov_b32 m0, s89
	s_nop 0
	buffer_load_dwordx4 v136, s[16:19], 0 offen lds
	s_waitcnt lgkmcnt(8)
	s_barrier
	s_waitcnt lgkmcnt(0)
	s_setprio 1
	s_waitcnt lgkmcnt(7)
	v_mfma_f32_16x16x32_bf16 v[88:91], v[100:103], v[130:133], 0
	v_mfma_f32_16x16x32_bf16 v[96:99], v[122:125], v[130:133], 0
	s_waitcnt lgkmcnt(5)
	v_mfma_f32_16x16x32_bf16 v[76:79], v[100:103], v[154:157], 0
	v_mfma_f32_16x16x32_bf16 v[84:87], v[122:125], v[154:157], 0
	s_waitcnt lgkmcnt(3)
	v_mfma_f32_16x16x32_bf16 v[64:67], v[100:103], v[162:165], 0
	v_mfma_f32_16x16x32_bf16 v[72:75], v[122:125], v[162:165], 0
	s_waitcnt lgkmcnt(1)
	v_mfma_f32_16x16x32_bf16 v[52:55], v[100:103], v[170:173], 0
	v_mfma_f32_16x16x32_bf16 v[60:63], v[122:125], v[170:173], 0
	v_mfma_f32_16x16x32_bf16 v[88:91], v[104:107], v[150:153], v[88:91]
	v_mfma_f32_16x16x32_bf16 v[96:99], v[126:129], v[150:153], v[96:99]
	v_mfma_f32_16x16x32_bf16 v[76:79], v[104:107], v[158:161], v[76:79]
	v_mfma_f32_16x16x32_bf16 v[84:87], v[126:129], v[158:161], v[84:87]
	v_mfma_f32_16x16x32_bf16 v[64:67], v[104:107], v[166:169], v[64:67]
	v_mfma_f32_16x16x32_bf16 v[72:75], v[126:129], v[166:169], v[72:75]
	s_waitcnt lgkmcnt(0)
	v_mfma_f32_16x16x32_bf16 v[52:55], v[104:107], v[174:177], v[52:55]
	v_mfma_f32_16x16x32_bf16 v[60:63], v[126:129], v[174:177], v[60:63]
	s_setprio 0
	s_barrier
	s_and_b32 s29, s27, 0xffff
	s_mov_b32 s30, s18
	s_mov_b32 s31, s19
	s_mov_b32 m0, s73
	ds_read_b128 v[178:181], v143
	ds_read_b128 v[182:185], v143 offset:1024
	buffer_load_dwordx4 v135, s[28:31], 0 offen lds
	s_mov_b32 m0, s74
	s_nop 0
	buffer_load_dwordx4 v137, s[28:31], 0 offen lds
	s_barrier
	s_waitcnt lgkmcnt(0)
	s_setprio 1
	s_waitcnt lgkmcnt(1)
	v_mfma_f32_16x16x32_bf16 v[92:95], v[178:181], v[130:133], 0
	v_mfma_f32_16x16x32_bf16 v[80:83], v[178:181], v[154:157], 0
	v_mfma_f32_16x16x32_bf16 v[68:71], v[178:181], v[162:165], 0
	v_mfma_f32_16x16x32_bf16 v[56:59], v[178:181], v[170:173], 0
	s_waitcnt lgkmcnt(0)
	v_mfma_f32_16x16x32_bf16 v[92:95], v[182:185], v[150:153], v[92:95]
	v_mfma_f32_16x16x32_bf16 v[80:83], v[182:185], v[158:161], v[80:83]
	v_mfma_f32_16x16x32_bf16 v[68:71], v[182:185], v[166:169], v[68:71]
	v_mfma_f32_16x16x32_bf16 v[56:59], v[182:185], v[174:177], v[56:59]
	s_setprio 0
	s_and_b32 s37, s26, 0xffff
	s_mov_b32 s38, s18
	s_mov_b32 s39, s19
	s_mov_b32 m0, s71
	s_barrier
	ds_read_b128 v[130:133], v142 offset:16384
	ds_read_b128 v[150:153], v142 offset:17408
	ds_read_b128 v[154:157], v142 offset:18432
	ds_read_b128 v[158:161], v142 offset:19456
	ds_read_b128 v[162:165], v142 offset:20480
	ds_read_b128 v[166:169], v142 offset:21504
	ds_read_b128 v[170:173], v142 offset:22528
	ds_read_b128 v[174:177], v142 offset:23552
	buffer_load_dwordx4 v134, s[36:39], 0 offen lds
	s_mov_b32 m0, s75
	s_nop 0
	buffer_load_dwordx4 v136, s[36:39], 0 offen lds
	s_barrier
	s_waitcnt lgkmcnt(0)
	s_setprio 1
	s_waitcnt lgkmcnt(7)
	v_mfma_f32_16x16x32_bf16 v[44:47], v[100:103], v[130:133], 0
	v_mfma_f32_16x16x32_bf16 v[48:51], v[122:125], v[130:133], 0
	s_waitcnt lgkmcnt(5)
	v_mfma_f32_16x16x32_bf16 v[28:31], v[100:103], v[154:157], 0
	v_mfma_f32_16x16x32_bf16 v[36:39], v[122:125], v[154:157], 0
	s_waitcnt lgkmcnt(3)
	v_mfma_f32_16x16x32_bf16 v[12:15], v[100:103], v[162:165], 0
	v_mfma_f32_16x16x32_bf16 v[20:23], v[122:125], v[162:165], 0
	s_waitcnt lgkmcnt(1)
	v_mfma_f32_16x16x32_bf16 v[0:3], v[100:103], v[170:173], 0
	v_mfma_f32_16x16x32_bf16 v[8:11], v[122:125], v[170:173], 0
	v_mfma_f32_16x16x32_bf16 v[44:47], v[104:107], v[150:153], v[44:47]
	v_mfma_f32_16x16x32_bf16 v[48:51], v[126:129], v[150:153], v[48:51]
	v_mfma_f32_16x16x32_bf16 v[28:31], v[104:107], v[158:161], v[28:31]
	v_mfma_f32_16x16x32_bf16 v[36:39], v[126:129], v[158:161], v[36:39]
	v_mfma_f32_16x16x32_bf16 v[12:15], v[104:107], v[166:169], v[12:15]
	v_mfma_f32_16x16x32_bf16 v[20:23], v[126:129], v[166:169], v[20:23]
	s_waitcnt lgkmcnt(0)
	v_mfma_f32_16x16x32_bf16 v[0:3], v[104:107], v[174:177], v[0:3]
	v_mfma_f32_16x16x32_bf16 v[8:11], v[126:129], v[174:177], v[8:11]
	s_setprio 0
	s_barrier
	s_add_u32 s16, s28, s44
	s_addc_u32 vcc_hi, s27, s45
	s_and_b32 s17, vcc_hi, 0xffff
	s_mov_b32 m0, s76
	s_nop 0
	buffer_load_dwordx4 v135, s[16:19], 0 offen lds
	s_mov_b32 m0, s77
	s_nop 0
	buffer_load_dwordx4 v137, s[16:19], 0 offen lds
	s_waitcnt vmcnt(6)
	s_barrier
	s_setprio 1
	v_mfma_f32_16x16x32_bf16 v[40:43], v[178:181], v[130:133], 0
	v_mfma_f32_16x16x32_bf16 v[32:35], v[178:181], v[154:157], 0
	v_mfma_f32_16x16x32_bf16 v[16:19], v[178:181], v[162:165], 0
	v_mfma_f32_16x16x32_bf16 v[4:7], v[178:181], v[170:173], 0
	v_mfma_f32_16x16x32_bf16 v[40:43], v[182:185], v[150:153], v[40:43]
	v_mfma_f32_16x16x32_bf16 v[32:35], v[182:185], v[158:161], v[32:35]
	v_mfma_f32_16x16x32_bf16 v[16:19], v[182:185], v[166:169], v[16:19]
	v_mfma_f32_16x16x32_bf16 v[4:7], v[182:185], v[174:177], v[4:7]
	s_setprio 0
	s_barrier
	s_branch .Lkmid_844

; #define PG8_STAGE(bufoff, gbase, voff) do { const __amdgpu_buffer_rsrc_t _r = __builtin_amdgcn_make_buffer_rsrc((void*)(gbase), (short)0, 0x7fffffff, 0x00020000); _Pragma("unroll") for (int _i = 0; _i < 2; ++_i) \
;         __builtin_amdgcn_raw_ptr_buffer_load_lds(_r, (LAS unsigned*)(lds + (bufoff) + ldsw + _i * 8192), 16, (int)(voff)[_i], 0, 0, 0); } while (0)
; #define PG8_LDA(dst, b, h) do { _Pragma("unroll") for (int m = 0; m < 4; ++m) _Pragma("unroll") for (int k = 0; k < 2; ++k) dst[m][k] = *(const LAS bf16x8*)(lds + PG8_SA(b, h) + aoff + m * 2048 + k * 1024); } while (0)
; #define PG8_LDB(dst, b, h) do { _Pragma("unroll") for (int n = 0; n < 2; ++n) _Pragma("unroll") for (int k = 0; k < 2; ++k) dst[n][k] = *(const LAS bf16x8*)(lds + PG8_SB(b, h) + boff + n * 2048 + k * 1024); } while (0)
; #define PG8_MMA(ai, bj, At, Bt) do { __builtin_amdgcn_s_setprio(1); _Pragma("unroll") for (int k = 0; k < 2; ++k) _Pragma("unroll") for (int m = 0; m < 4; ++m) _Pragma("unroll") for (int n = 0; n < ((bj) == 1 ? NB1 : 2); ++n) \
;         acc[ai][bj][m][n] = __builtin_amdgcn_mfma_f32_16x16x32_bf16(Bt[n][k], At[m][k], acc[ai][bj][m][n], 0, 0, 0); __builtin_amdgcn_s_setprio(0); } while (0)
; #define PG8_WAIT_V(n) asm volatile("s_waitcnt vmcnt(" #n ")" ::: "memory")
; #define PG8_WAIT_L(n) asm volatile("s_waitcnt lgkmcnt(" #n ")" ::: "memory")
; #define PG8_BAR __builtin_amdgcn_s_barrier()
; #define PG8_SCHED __builtin_amdgcn_sched_barrier(0)
;     ...
;             PG8_LDB(B0, 1, 0); PG8_SCHED; PG8_LDA(At, 1, 0); PG8_STAGE(PG8_SA(0, 1), a2 + hstepA, voffA);
;             PG8_WAIT_L(8); PG8_BAR; PG8_WAIT_L(0); PG8_MMA(0, 0, At, B0); PG8_BAR; PG8_SCHED;
;             PG8_LDB(B1, 1, 1); PG8_STAGE(PG8_SB(1, 0), b3, voffB);
;             PG8_BAR; PG8_WAIT_L(0); PG8_MMA(0, 1, At, B1); PG8_BAR;
;             PG8_LDA(At, 1, 1); PG8_STAGE(PG8_SA(1, 0), a3, voffA);
;             PG8_BAR; PG8_WAIT_L(0); PG8_MMA(1, 0, At, B0); PG8_BAR; PG8_SCHED;
;             PG8_STAGE(PG8_SB(1, 1), b3 + hstepB, voffB);
;             PG8_WAIT_V(6); PG8_BAR; PG8_MMA(1, 1, At, B1); PG8_BAR;
.Lkmid_844:
	ds_read_b128 v[100:103], v144
	ds_read_b128 v[104:107], v144 offset:1024
	ds_read_b128 v[122:125], v144 offset:2048
	ds_read_b128 v[126:129], v144 offset:3072
	s_add_u32 s36, s36, s0
	s_addc_u32 s17, s26, s1
	s_and_b32 s37, s17, 0xffff
	s_mov_b32 m0, s78
	ds_read_b128 v[130:133], v142 offset:32768
	ds_read_b128 v[150:153], v142 offset:33792
	ds_read_b128 v[154:157], v142 offset:34816
	ds_read_b128 v[158:161], v142 offset:35840
	ds_read_b128 v[162:165], v142 offset:36864
	ds_read_b128 v[166:169], v142 offset:37888
	ds_read_b128 v[170:173], v142 offset:38912
	ds_read_b128 v[174:177], v142 offset:39936
	buffer_load_dwordx4 v134, s[36:39], 0 offen lds
	s_mov_b32 m0, s79
	s_nop 0
	buffer_load_dwordx4 v136, s[36:39], 0 offen lds
	s_waitcnt lgkmcnt(8)
	s_barrier
	s_waitcnt lgkmcnt(0)
	s_setprio 1
	s_waitcnt lgkmcnt(7)
	v_mfma_f32_16x16x32_bf16 v[88:91], v[100:103], v[130:133], v[88:91]
	v_mfma_f32_16x16x32_bf16 v[96:99], v[122:125], v[130:133], v[96:99]
	s_waitcnt lgkmcnt(5)
	v_mfma_f32_16x16x32_bf16 v[76:79], v[100:103], v[154:157], v[76:79]
	v_mfma_f32_16x16x32_bf16 v[84:87], v[122:125], v[154:157], v[84:87]
	s_waitcnt lgkmcnt(3)
	v_mfma_f32_16x16x32_bf16 v[64:67], v[100:103], v[162:165], v[64:67]
	v_mfma_f32_16x16x32_bf16 v[72:75], v[122:125], v[162:165], v[72:75]
	s_waitcnt lgkmcnt(1)
	v_mfma_f32_16x16x32_bf16 v[52:55], v[100:103], v[170:173], v[52:55]
	v_mfma_f32_16x16x32_bf16 v[60:63], v[122:125], v[170:173], v[60:63]
	v_mfma_f32_16x16x32_bf16 v[88:91], v[104:107], v[150:153], v[88:91]
	v_mfma_f32_16x16x32_bf16 v[96:99], v[126:129], v[150:153], v[96:99]
	v_mfma_f32_16x16x32_bf16 v[76:79], v[104:107], v[158:161], v[76:79]
	v_mfma_f32_16x16x32_bf16 v[84:87], v[126:129], v[158:161], v[84:87]
	v_mfma_f32_16x16x32_bf16 v[64:67], v[104:107], v[166:169], v[64:67]
	v_mfma_f32_16x16x32_bf16 v[72:75], v[126:129], v[166:169], v[72:75]
	s_waitcnt lgkmcnt(0)
	v_mfma_f32_16x16x32_bf16 v[52:55], v[104:107], v[174:177], v[52:55]
	v_mfma_f32_16x16x32_bf16 v[60:63], v[126:129], v[174:177], v[60:63]
	s_setprio 0
	s_barrier
	s_add_u32 s28, s28, 0x80
	s_addc_u32 s17, s27, 0
	s_and_b32 s29, s17, 0xffff
	s_mov_b32 m0, s81
	ds_read_b128 v[178:181], v145
	ds_read_b128 v[182:185], v145 offset:1024
	buffer_load_dwordx4 v135, s[28:31], 0 offen lds
	s_mov_b32 m0, s82
	s_nop 0
	buffer_load_dwordx4 v137, s[28:31], 0 offen lds
	s_barrier
	s_waitcnt lgkmcnt(0)
	s_setprio 1
	s_waitcnt lgkmcnt(1)
	v_mfma_f32_16x16x32_bf16 v[92:95], v[178:181], v[130:133], v[92:95]
	v_mfma_f32_16x16x32_bf16 v[80:83], v[178:181], v[154:157], v[80:83]
	v_mfma_f32_16x16x32_bf16 v[68:71], v[178:181], v[162:165], v[68:71]
	v_mfma_f32_16x16x32_bf16 v[56:59], v[178:181], v[170:173], v[56:59]
	s_waitcnt lgkmcnt(0)
	v_mfma_f32_16x16x32_bf16 v[92:95], v[182:185], v[150:153], v[92:95]
	v_mfma_f32_16x16x32_bf16 v[80:83], v[182:185], v[158:161], v[80:83]
	v_mfma_f32_16x16x32_bf16 v[68:71], v[182:185], v[166:169], v[68:71]
	v_mfma_f32_16x16x32_bf16 v[56:59], v[182:185], v[174:177], v[56:59]
	s_setprio 0
	s_and_b32 s25, s25, 0xffff
	s_mov_b32 s26, s18
	s_mov_b32 s27, s19
	s_mov_b32 m0, s83
	s_barrier
	ds_read_b128 v[130:133], v142 offset:49152
	ds_read_b128 v[150:153], v142 offset:50176
	ds_read_b128 v[154:157], v142 offset:51200
	ds_read_b128 v[158:161], v142 offset:52224
	ds_read_b128 v[162:165], v142 offset:53248
	ds_read_b128 v[166:169], v142 offset:54272
	ds_read_b128 v[170:173], v142 offset:55296
	ds_read_b128 v[174:177], v142 offset:56320
	buffer_load_dwordx4 v134, s[24:27], 0 offen lds
	s_mov_b32 m0, s84
	s_nop 0
	buffer_load_dwordx4 v136, s[24:27], 0 offen lds
	s_barrier
	s_waitcnt lgkmcnt(0)
	s_setprio 1
	s_waitcnt lgkmcnt(7)
	v_mfma_f32_16x16x32_bf16 v[44:47], v[100:103], v[130:133], v[44:47]
	v_mfma_f32_16x16x32_bf16 v[48:51], v[122:125], v[130:133], v[48:51]
	s_waitcnt lgkmcnt(5)
	v_mfma_f32_16x16x32_bf16 v[28:31], v[100:103], v[154:157], v[28:31]
	v_mfma_f32_16x16x32_bf16 v[36:39], v[122:125], v[154:157], v[36:39]
	s_waitcnt lgkmcnt(3)
	v_mfma_f32_16x16x32_bf16 v[12:15], v[100:103], v[162:165], v[12:15]
	v_mfma_f32_16x16x32_bf16 v[20:23], v[122:125], v[162:165], v[20:23]
	s_waitcnt lgkmcnt(1)
	v_mfma_f32_16x16x32_bf16 v[0:3], v[100:103], v[170:173], v[0:3]
	v_mfma_f32_16x16x32_bf16 v[8:11], v[122:125], v[170:173], v[8:11]
	v_mfma_f32_16x16x32_bf16 v[44:47], v[104:107], v[150:153], v[44:47]
	v_mfma_f32_16x16x32_bf16 v[48:51], v[126:129], v[150:153], v[48:51]
	v_mfma_f32_16x16x32_bf16 v[28:31], v[104:107], v[158:161], v[28:31]
	v_mfma_f32_16x16x32_bf16 v[36:39], v[126:129], v[158:161], v[36:39]
	v_mfma_f32_16x16x32_bf16 v[12:15], v[104:107], v[166:169], v[12:15]
	v_mfma_f32_16x16x32_bf16 v[20:23], v[126:129], v[166:169], v[20:23]
	s_waitcnt lgkmcnt(0)
	v_mfma_f32_16x16x32_bf16 v[0:3], v[104:107], v[174:177], v[0:3]
	v_mfma_f32_16x16x32_bf16 v[8:11], v[126:129], v[174:177], v[8:11]
	s_setprio 0
	s_barrier
	s_add_u32 s16, s16, 0x80
	s_addc_u32 s17, vcc_hi, 0
	s_and_b32 s17, s17, 0xffff
	s_mov_b32 m0, s85
	s_nop 0
	buffer_load_dwordx4 v135, s[16:19], 0 offen lds
	s_mov_b32 m0, s86
	s_nop 0
	buffer_load_dwordx4 v137, s[16:19], 0 offen lds
	s_waitcnt vmcnt(6)
	s_barrier
	s_setprio 1
	v_mfma_f32_16x16x32_bf16 v[40:43], v[178:181], v[130:133], v[40:43]
	v_mfma_f32_16x16x32_bf16 v[32:35], v[178:181], v[154:157], v[32:35]
	v_mfma_f32_16x16x32_bf16 v[16:19], v[178:181], v[162:165], v[16:19]
	v_mfma_f32_16x16x32_bf16 v[4:7], v[178:181], v[170:173], v[4:7]
	v_mfma_f32_16x16x32_bf16 v[40:43], v[182:185], v[150:153], v[40:43]
	v_mfma_f32_16x16x32_bf16 v[32:35], v[182:185], v[158:161], v[32:35]
	v_mfma_f32_16x16x32_bf16 v[16:19], v[182:185], v[166:169], v[16:19]
	v_mfma_f32_16x16x32_bf16 v[4:7], v[182:185], v[174:177], v[4:7]
	s_setprio 0
	s_add_u32 s94, s94, 0x100
	s_addc_u32 s95, s95, 0
	s_add_u32 s96, s96, 0x100
	s_addc_u32 s97, s97, 0
	s_cmp_ge_i32 vcc_lo, s80
	s_mov_b32 s16, vcc_lo
	s_barrier
	s_cbranch_scc0 .LBB0_844
	v_readlane_b32 s96, v252, 38
	v_readlane_b32 s97, v252, 39

;     __device__ __forceinline__ size_t a_off(const Unit& u) const { return (size_t)u.pm * atile; }
;     __device__ __forceinline__ size_t b_off(const Unit& u) const { return (size_t)u.pn * btile; }
;     __device__ __forceinline__ bool next(int i, Unit& u) const { const long L = (long)i * G + c; if (L >= NG * 8) return false; u.g = (int)(L >> 3); u.pm = (int)(L & 7); u.pn = 0; return true; }
;     __device__ __forceinline__ size_t a_off(const Unit& u) const { return ((size_t)u.g * NROW + (size_t)u.pm * BM) * KA * 2; }
;     __device__ __forceinline__ size_t b_off(const Unit& u) const { return (size_t)u.g * btile; }
;     __device__ __forceinline__ bool next(int i, Unit& u) const { if (i >= 2) return false; u.g = g; u.pm = 2 * b + i; u.pn = 0; return true; }
;     __device__ __forceinline__ size_t a_off(const Unit& u) const { return ((size_t)u.g * NROW + (size_t)u.pm * BM) * KA * 2; }
;     __device__ __forceinline__ size_t b_off(const Unit& u) const { return (size_t)u.g * btile; }
; #define PG8_STAGE(bufoff, gbase, voff) do { const __amdgpu_buffer_rsrc_t _r = __builtin_amdgcn_make_buffer_rsrc((void*)(gbase), (short)0, 0x7fffffff, 0x00020000); _Pragma("unroll") for (int _i = 0; _i < 2; ++_i) \
;         __builtin_amdgcn_raw_ptr_buffer_load_lds(_r, (LAS unsigned*)(lds + (bufoff) + ldsw + _i * 8192), 16, (int)(voff)[_i], 0, 0, 0); } while (0)
; #define PG8_WAIT_L(n) asm volatile("s_waitcnt lgkmcnt(" #n ")" ::: "memory")
; #define PG8_BAR __builtin_amdgcn_s_barrier()
;     ...
;         const bool has_next = S.next(ui + 1, nxt);
;         const char* nA = has_next ? (const char*)Ap + S.a_off(nxt) : cA; const char* nB = has_next ? (const char*)Btp + S.b_off(nxt) : cB;
;         for (int t = 0; t < nt; t += 2) {
;             const bool last = (t == nt - 2);
;             const char* a1 = cA + (size_t)(t + 1) * kstep;
;             const char* a2 = last ? nA : cA + (size_t)(t + 2) * kstep; const char* b2 = last ? nB : cB + (size_t)(t + 2) * kstep;
;             const char* a3 = a2 + kstep; const char* b3 = b2 + kstep;
;             PG8_LDB(B0, 0, 0); PG8_SCHED; PG8_LDA(At, 0, 0); PG8_STAGE(PG8_SA(1, 1), a1 + hstepA, voffA);
;             PG8_WAIT_L(8); PG8_BAR; PG8_WAIT_L(0); PG8_MMA(0, 0, At, B0); PG8_BAR; PG8_SCHED;
;             PG8_LDB(B1, 0, 1); PG8_STAGE(PG8_SB(0, 0), b2, voffB);
;             PG8_BAR; PG8_WAIT_L(0); PG8_MMA(0, 1, At, B1); PG8_BAR;
.LBB0_920:
	s_ashr_i32 s51, s50, 31
	s_lshl_b64 s[8:9], s[50:51], 19
	s_add_u32 s52, s40, s8
	s_addc_u32 s53, s41, s9
	s_ashr_i32 s49, s48, 31
	s_lshl_b64 s[8:9], s[48:49], 19
	s_add_u32 s58, s72, s8
	v_cmp_lt_i64_e64 s[0:1], s[0:1], v[188:189]
	s_addc_u32 s59, s73, s9
	s_andn2_b64 vcc, exec, s[46:47]
	s_waitcnt lgkmcnt(0)
	s_cbranch_vccnz .Lkzero_922
	s_and_b64 s[0:1], s[0:1], exec
	s_cselect_b32 s0, s53, s19
	s_cselect_b32 s1, s52, s18
	s_cselect_b32 s49, s59, s17
	s_cselect_b32 s51, s58, s16
	s_add_u32 s91, s18, 0x100
	s_addc_u32 s92, s19, 0
	s_add_u32 s93, s16, 0x100
	s_addc_u32 s94, s17, 0
	s_mov_b32 s8, 0
	ds_read_b128 v[128:131], v227
	ds_read_b128 v[132:135], v227 offset:1024
	ds_read_b128 v[136:139], v227 offset:2048
	ds_read_b128 v[140:143], v227 offset:3072
	s_add_i32 s22, s8, 2
	s_cmp_eq_u32 s87, s8
	s_cselect_b32 s28, s1, s91
	s_cselect_b32 s19, s0, s92
	s_cselect_b32 s18, s49, s94
	s_cselect_b32 s24, s51, s93
	s_add_u32 s16, s28, 0x80
	s_addc_u32 s17, s19, 0
	s_add_u32 s8, s91, s36
	s_addc_u32 s9, s92, s37
	s_add_u32 s8, s8, 0xffffff80
	s_addc_u32 s9, s9, -1
	s_and_b32 s9, s9, 0xffff
	s_mov_b32 m0, s88
	ds_read_b128 v[144:147], v228
	ds_read_b128 v[148:151], v228 offset:1024
	ds_read_b128 v[152:155], v228 offset:2048
	ds_read_b128 v[156:159], v228 offset:3072
	ds_read_b128 v[160:163], v228 offset:4096
	ds_read_b128 v[164:167], v228 offset:5120
	ds_read_b128 v[168:171], v228 offset:6144
	ds_read_b128 v[172:175], v228 offset:7168
	buffer_load_dwordx4 v222, s[8:11], 0 offen lds
	s_mov_b32 m0, s89
	s_nop 0
	buffer_load_dwordx4 v224, s[8:11], 0 offen lds
	s_waitcnt lgkmcnt(8)
	s_barrier
	s_waitcnt lgkmcnt(0)
	s_setprio 1
	s_waitcnt lgkmcnt(7)
	v_mfma_f32_16x16x32_bf16 v[120:123], v[128:131], v[144:147], 0
	v_mfma_f32_16x16x32_bf16 v[124:127], v[136:139], v[144:147], 0
	s_waitcnt lgkmcnt(5)
	v_mfma_f32_16x16x32_bf16 v[108:111], v[128:131], v[152:155], 0
	v_mfma_f32_16x16x32_bf16 v[104:107], v[136:139], v[152:155], 0
	s_waitcnt lgkmcnt(3)
	v_mfma_f32_16x16x32_bf16 v[92:95], v[128:131], v[160:163], 0
	v_mfma_f32_16x16x32_bf16 v[88:91], v[136:139], v[160:163], 0
	s_waitcnt lgkmcnt(1)
	v_mfma_f32_16x16x32_bf16 v[76:79], v[128:131], v[168:171], 0
	v_mfma_f32_16x16x32_bf16 v[72:75], v[136:139], v[168:171], 0
	v_mfma_f32_16x16x32_bf16 v[120:123], v[132:135], v[148:151], v[120:123]
	v_mfma_f32_16x16x32_bf16 v[124:127], v[140:143], v[148:151], v[124:127]
	v_mfma_f32_16x16x32_bf16 v[108:111], v[132:135], v[156:159], v[108:111]
	v_mfma_f32_16x16x32_bf16 v[104:107], v[140:143], v[156:159], v[104:107]
	v_mfma_f32_16x16x32_bf16 v[92:95], v[132:135], v[164:167], v[92:95]
	v_mfma_f32_16x16x32_bf16 v[88:91], v[140:143], v[164:167], v[88:91]
	s_waitcnt lgkmcnt(0)
	v_mfma_f32_16x16x32_bf16 v[76:79], v[132:135], v[172:175], v[76:79]
	v_mfma_f32_16x16x32_bf16 v[72:75], v[140:143], v[172:175], v[72:75]
	s_setprio 0
	s_barrier
	s_and_b32 s25, s18, 0xffff
	s_mov_b32 s26, s10
	s_mov_b32 s27, s11
	s_mov_b32 m0, s67
	ds_read_b128 v[176:179], v229
	ds_read_b128 v[180:183], v229 offset:1024
	ds_read_b128 v[192:195], v229 offset:2048
	ds_read_b128 v[196:199], v229 offset:3072
	buffer_load_dwordx4 v223, s[24:27], 0 offen lds
	s_mov_b32 m0, s74
	s_nop 0
	buffer_load_dwordx4 v225, s[24:27], 0 offen lds
	s_barrier
; #define PG8_STAGE(bufoff, gbase, voff) do { const __amdgpu_buffer_rsrc_t _r = __builtin_amdgcn_make_buffer_rsrc((void*)(gbase), (short)0, 0x7fffffff, 0x00020000); _Pragma("unroll") for (int _i = 0; _i < 2; ++_i) \
;         __builtin_amdgcn_raw_ptr_buffer_load_lds(_r, (LAS unsigned*)(lds + (bufoff) + ldsw + _i * 8192), 16, (int)(voff)[_i], 0, 0, 0); } while (0)
; #define PG8_LDA(dst, b, h) do { _Pragma("unroll") for (int m = 0; m < 4; ++m) _Pragma("unroll") for (int k = 0; k < 2; ++k) dst[m][k] = *(const LAS bf16x8*)(lds + PG8_SA(b, h) + aoff + m * 2048 + k * 1024); } while (0)
; #define PG8_MMA(ai, bj, At, Bt) do { __builtin_amdgcn_s_setprio(1); _Pragma("unroll") for (int k = 0; k < 2; ++k) _Pragma("unroll") for (int m = 0; m < 4; ++m) _Pragma("unroll") for (int n = 0; n < ((bj) == 1 ? NB1 : 2); ++n) \
;         acc[ai][bj][m][n] = __builtin_amdgcn_mfma_f32_16x16x32_bf16(Bt[n][k], At[m][k], acc[ai][bj][m][n], 0, 0, 0); __builtin_amdgcn_s_setprio(0); } while (0)
; #define PG8_WAIT_V(n) asm volatile("s_waitcnt vmcnt(" #n ")" ::: "memory")
; #define PG8_WAIT_L(n) asm volatile("s_waitcnt lgkmcnt(" #n ")" ::: "memory")
; #define PG8_BAR __builtin_amdgcn_s_barrier()
; #define PG8_SCHED __builtin_amdgcn_sched_barrier(0)
;     ...
;             PG8_BAR; PG8_WAIT_L(0); PG8_MMA(0, 1, At, B1); PG8_BAR;
;             PG8_LDA(At, 0, 1); PG8_STAGE(PG8_SA(0, 0), a2, voffA);
;             PG8_BAR; PG8_WAIT_L(0); PG8_MMA(1, 0, At, B0); PG8_BAR; PG8_SCHED;
;             PG8_STAGE(PG8_SB(0, 1), b2 + hstepB, voffB);
;             PG8_WAIT_V(6); PG8_BAR; PG8_MMA(1, 1, At, B1); PG8_BAR;
	s_waitcnt lgkmcnt(0)
	s_setprio 1
	s_waitcnt lgkmcnt(3)
	v_mfma_f32_16x16x32_bf16 v[116:119], v[176:179], v[144:147], 0
	s_waitcnt lgkmcnt(1)
	v_mfma_f32_16x16x32_bf16 v[112:115], v[192:195], v[144:147], 0
	v_mfma_f32_16x16x32_bf16 v[100:103], v[176:179], v[152:155], 0
	v_mfma_f32_16x16x32_bf16 v[96:99], v[192:195], v[152:155], 0
	v_mfma_f32_16x16x32_bf16 v[84:87], v[176:179], v[160:163], 0
	v_mfma_f32_16x16x32_bf16 v[80:83], v[192:195], v[160:163], 0
	v_mfma_f32_16x16x32_bf16 v[68:71], v[176:179], v[168:171], 0
	v_mfma_f32_16x16x32_bf16 v[64:67], v[192:195], v[168:171], 0
	v_mfma_f32_16x16x32_bf16 v[116:119], v[180:183], v[148:151], v[116:119]
	s_waitcnt lgkmcnt(0)
	v_mfma_f32_16x16x32_bf16 v[112:115], v[196:199], v[148:151], v[112:115]
	v_mfma_f32_16x16x32_bf16 v[100:103], v[180:183], v[156:159], v[100:103]
	v_mfma_f32_16x16x32_bf16 v[96:99], v[196:199], v[156:159], v[96:99]
	v_mfma_f32_16x16x32_bf16 v[84:87], v[180:183], v[164:167], v[84:87]
	v_mfma_f32_16x16x32_bf16 v[80:83], v[196:199], v[164:167], v[80:83]
	v_mfma_f32_16x16x32_bf16 v[68:71], v[180:183], v[172:175], v[68:71]
	v_mfma_f32_16x16x32_bf16 v[64:67], v[196:199], v[172:175], v[64:67]
	s_setprio 0
	s_and_b32 s29, s19, 0xffff
	s_mov_b32 s30, s10
	s_mov_b32 s31, s11
	s_mov_b32 m0, s65
	s_barrier
	ds_read_b128 v[144:147], v228 offset:16384
	ds_read_b128 v[148:151], v228 offset:17408
	ds_read_b128 v[152:155], v228 offset:18432
	ds_read_b128 v[156:159], v228 offset:19456
	ds_read_b128 v[160:163], v228 offset:20480
	ds_read_b128 v[164:167], v228 offset:21504
	ds_read_b128 v[168:171], v228 offset:22528
	ds_read_b128 v[172:175], v228 offset:23552
	buffer_load_dwordx4 v222, s[28:31], 0 offen lds
	s_mov_b32 m0, s75
	s_nop 0
	buffer_load_dwordx4 v224, s[28:31], 0 offen lds
	s_barrier
	s_waitcnt lgkmcnt(0)
	s_setprio 1
	s_waitcnt lgkmcnt(7)
	v_mfma_f32_16x16x32_bf16 v[60:63], v[128:131], v[144:147], 0
	v_mfma_f32_16x16x32_bf16 v[56:59], v[136:139], v[144:147], 0
	s_waitcnt lgkmcnt(5)
	v_mfma_f32_16x16x32_bf16 v[44:47], v[128:131], v[152:155], 0
	v_mfma_f32_16x16x32_bf16 v[40:43], v[136:139], v[152:155], 0
	s_waitcnt lgkmcnt(3)
	v_mfma_f32_16x16x32_bf16 v[28:31], v[128:131], v[160:163], 0
	v_mfma_f32_16x16x32_bf16 v[24:27], v[136:139], v[160:163], 0
	s_waitcnt lgkmcnt(1)
	v_mfma_f32_16x16x32_bf16 v[12:15], v[128:131], v[168:171], 0
	v_mfma_f32_16x16x32_bf16 v[8:11], v[136:139], v[168:171], 0
	v_mfma_f32_16x16x32_bf16 v[60:63], v[132:135], v[148:151], v[60:63]
	v_mfma_f32_16x16x32_bf16 v[56:59], v[140:143], v[148:151], v[56:59]
	v_mfma_f32_16x16x32_bf16 v[44:47], v[132:135], v[156:159], v[44:47]
	v_mfma_f32_16x16x32_bf16 v[40:43], v[140:143], v[156:159], v[40:43]
	v_mfma_f32_16x16x32_bf16 v[28:31], v[132:135], v[164:167], v[28:31]
	v_mfma_f32_16x16x32_bf16 v[24:27], v[140:143], v[164:167], v[24:27]
	s_waitcnt lgkmcnt(0)
	v_mfma_f32_16x16x32_bf16 v[12:15], v[132:135], v[172:175], v[12:15]
	v_mfma_f32_16x16x32_bf16 v[8:11], v[140:143], v[172:175], v[8:11]
	s_setprio 0
	s_barrier
	s_add_u32 s8, s24, s38
	s_addc_u32 s23, s18, s39
	s_and_b32 s9, s23, 0xffff
	s_mov_b32 m0, s76
	s_nop 0
	buffer_load_dwordx4 v223, s[8:11], 0 offen lds
	s_mov_b32 m0, s77
	s_nop 0
	buffer_load_dwordx4 v225, s[8:11], 0 offen lds
	s_waitcnt vmcnt(6)
	s_barrier
	s_setprio 1
	v_mfma_f32_16x16x32_bf16 v[52:55], v[176:179], v[144:147], 0
	v_mfma_f32_16x16x32_bf16 v[48:51], v[192:195], v[144:147], 0
	v_mfma_f32_16x16x32_bf16 v[36:39], v[176:179], v[152:155], 0
	v_mfma_f32_16x16x32_bf16 v[32:35], v[192:195], v[152:155], 0
	v_mfma_f32_16x16x32_bf16 v[20:23], v[176:179], v[160:163], 0
	v_mfma_f32_16x16x32_bf16 v[16:19], v[192:195], v[160:163], 0
	v_mfma_f32_16x16x32_bf16 v[4:7], v[176:179], v[168:171], 0
	v_mfma_f32_16x16x32_bf16 v[0:3], v[192:195], v[168:171], 0
	v_mfma_f32_16x16x32_bf16 v[52:55], v[180:183], v[148:151], v[52:55]
	v_mfma_f32_16x16x32_bf16 v[48:51], v[196:199], v[148:151], v[48:51]
	v_mfma_f32_16x16x32_bf16 v[36:39], v[180:183], v[156:159], v[36:39]
	v_mfma_f32_16x16x32_bf16 v[32:35], v[196:199], v[156:159], v[32:35]
	v_mfma_f32_16x16x32_bf16 v[20:23], v[180:183], v[164:167], v[20:23]
	v_mfma_f32_16x16x32_bf16 v[16:19], v[196:199], v[164:167], v[16:19]
	v_mfma_f32_16x16x32_bf16 v[4:7], v[180:183], v[172:175], v[4:7]
	v_mfma_f32_16x16x32_bf16 v[0:3], v[196:199], v[172:175], v[0:3]
	s_setprio 0
	s_barrier
	s_branch .Lkmid_922

; #define PG8_STAGE(bufoff, gbase, voff) do { const __amdgpu_buffer_rsrc_t _r = __builtin_amdgcn_make_buffer_rsrc((void*)(gbase), (short)0, 0x7fffffff, 0x00020000); _Pragma("unroll") for (int _i = 0; _i < 2; ++_i) \
;         __builtin_amdgcn_raw_ptr_buffer_load_lds(_r, (LAS unsigned*)(lds + (bufoff) + ldsw + _i * 8192), 16, (int)(voff)[_i], 0, 0, 0); } while (0)
; #define PG8_LDA(dst, b, h) do { _Pragma("unroll") for (int m = 0; m < 4; ++m) _Pragma("unroll") for (int k = 0; k < 2; ++k) dst[m][k] = *(const LAS bf16x8*)(lds + PG8_SA(b, h) + aoff + m * 2048 + k * 1024); } while (0)
; #define PG8_LDB(dst, b, h) do { _Pragma("unroll") for (int n = 0; n < 2; ++n) _Pragma("unroll") for (int k = 0; k < 2; ++k) dst[n][k] = *(const LAS bf16x8*)(lds + PG8_SB(b, h) + boff + n * 2048 + k * 1024); } while (0)
; #define PG8_MMA(ai, bj, At, Bt) do { __builtin_amdgcn_s_setprio(1); _Pragma("unroll") for (int k = 0; k < 2; ++k) _Pragma("unroll") for (int m = 0; m < 4; ++m) _Pragma("unroll") for (int n = 0; n < ((bj) == 1 ? NB1 : 2); ++n) \
;         acc[ai][bj][m][n] = __builtin_amdgcn_mfma_f32_16x16x32_bf16(Bt[n][k], At[m][k], acc[ai][bj][m][n], 0, 0, 0); __builtin_amdgcn_s_setprio(0); } while (0)
; #define PG8_WAIT_L(n) asm volatile("s_waitcnt lgkmcnt(" #n ")" ::: "memory")
; #define PG8_BAR __builtin_amdgcn_s_barrier()
; #define PG8_SCHED __builtin_amdgcn_sched_barrier(0)
;     ...
;             PG8_LDB(B0, 1, 0); PG8_SCHED; PG8_LDA(At, 1, 0); PG8_STAGE(PG8_SA(0, 1), a2 + hstepA, voffA);
;             PG8_WAIT_L(8); PG8_BAR; PG8_WAIT_L(0); PG8_MMA(0, 0, At, B0); PG8_BAR; PG8_SCHED;
;             PG8_LDB(B1, 1, 1); PG8_STAGE(PG8_SB(1, 0), b3, voffB);
;             PG8_BAR; PG8_WAIT_L(0); PG8_MMA(0, 1, At, B1); PG8_BAR;
;             PG8_LDA(At, 1, 1); PG8_STAGE(PG8_SA(1, 0), a3, voffA);
;             PG8_BAR; PG8_WAIT_L(0); PG8_MMA(1, 0, At, B0); PG8_BAR; PG8_SCHED;
.Lkmid_922:
	ds_read_b128 v[128:131], v230
	ds_read_b128 v[132:135], v230 offset:1024
	ds_read_b128 v[136:139], v230 offset:2048
	ds_read_b128 v[140:143], v230 offset:3072
	s_add_u32 s28, s28, s36
	s_addc_u32 s9, s19, s37
	s_and_b32 s29, s9, 0xffff
	s_mov_b32 m0, s78
	ds_read_b128 v[144:147], v228 offset:32768
	ds_read_b128 v[148:151], v228 offset:33792
	ds_read_b128 v[152:155], v228 offset:34816
	ds_read_b128 v[156:159], v228 offset:35840
	ds_read_b128 v[160:163], v228 offset:36864
	ds_read_b128 v[164:167], v228 offset:37888
	ds_read_b128 v[168:171], v228 offset:38912
	ds_read_b128 v[172:175], v228 offset:39936
	buffer_load_dwordx4 v222, s[28:31], 0 offen lds
	s_mov_b32 m0, s79
	s_nop 0
	buffer_load_dwordx4 v224, s[28:31], 0 offen lds
	s_waitcnt lgkmcnt(8)
	s_barrier
	s_waitcnt lgkmcnt(0)
	s_setprio 1
	s_waitcnt lgkmcnt(7)
	v_mfma_f32_16x16x32_bf16 v[120:123], v[128:131], v[144:147], v[120:123]
	v_mfma_f32_16x16x32_bf16 v[124:127], v[136:139], v[144:147], v[124:127]
	s_waitcnt lgkmcnt(5)
	v_mfma_f32_16x16x32_bf16 v[108:111], v[128:131], v[152:155], v[108:111]
	v_mfma_f32_16x16x32_bf16 v[104:107], v[136:139], v[152:155], v[104:107]
	s_waitcnt lgkmcnt(3)
	v_mfma_f32_16x16x32_bf16 v[92:95], v[128:131], v[160:163], v[92:95]
	v_mfma_f32_16x16x32_bf16 v[88:91], v[136:139], v[160:163], v[88:91]
	s_waitcnt lgkmcnt(1)
	v_mfma_f32_16x16x32_bf16 v[76:79], v[128:131], v[168:171], v[76:79]
	v_mfma_f32_16x16x32_bf16 v[72:75], v[136:139], v[168:171], v[72:75]
	v_mfma_f32_16x16x32_bf16 v[120:123], v[132:135], v[148:151], v[120:123]
	v_mfma_f32_16x16x32_bf16 v[124:127], v[140:143], v[148:151], v[124:127]
	v_mfma_f32_16x16x32_bf16 v[108:111], v[132:135], v[156:159], v[108:111]
	v_mfma_f32_16x16x32_bf16 v[104:107], v[140:143], v[156:159], v[104:107]
	v_mfma_f32_16x16x32_bf16 v[92:95], v[132:135], v[164:167], v[92:95]
	v_mfma_f32_16x16x32_bf16 v[88:91], v[140:143], v[164:167], v[88:91]
	s_waitcnt lgkmcnt(0)
	v_mfma_f32_16x16x32_bf16 v[76:79], v[132:135], v[172:175], v[76:79]
	v_mfma_f32_16x16x32_bf16 v[72:75], v[140:143], v[172:175], v[72:75]
	s_setprio 0
	s_barrier
	s_add_u32 s24, s24, 0x80
	s_addc_u32 s9, s18, 0
	s_and_b32 s25, s9, 0xffff
	s_mov_b32 m0, s81
	ds_read_b128 v[176:179], v231
	ds_read_b128 v[180:183], v231 offset:1024
	ds_read_b128 v[192:195], v231 offset:2048
	ds_read_b128 v[196:199], v231 offset:3072
	buffer_load_dwordx4 v223, s[24:27], 0 offen lds
	s_mov_b32 m0, s82
	s_nop 0
	buffer_load_dwordx4 v225, s[24:27], 0 offen lds
	s_barrier
	s_waitcnt lgkmcnt(0)
	s_setprio 1
	s_waitcnt lgkmcnt(3)
	v_mfma_f32_16x16x32_bf16 v[116:119], v[176:179], v[144:147], v[116:119]
	s_waitcnt lgkmcnt(1)
	v_mfma_f32_16x16x32_bf16 v[112:115], v[192:195], v[144:147], v[112:115]
	v_mfma_f32_16x16x32_bf16 v[100:103], v[176:179], v[152:155], v[100:103]
	v_mfma_f32_16x16x32_bf16 v[96:99], v[192:195], v[152:155], v[96:99]
	v_mfma_f32_16x16x32_bf16 v[84:87], v[176:179], v[160:163], v[84:87]
	v_mfma_f32_16x16x32_bf16 v[80:83], v[192:195], v[160:163], v[80:83]
	v_mfma_f32_16x16x32_bf16 v[68:71], v[176:179], v[168:171], v[68:71]
	v_mfma_f32_16x16x32_bf16 v[64:67], v[192:195], v[168:171], v[64:67]
	v_mfma_f32_16x16x32_bf16 v[116:119], v[180:183], v[148:151], v[116:119]
	s_waitcnt lgkmcnt(0)
	v_mfma_f32_16x16x32_bf16 v[112:115], v[196:199], v[148:151], v[112:115]
	v_mfma_f32_16x16x32_bf16 v[100:103], v[180:183], v[156:159], v[100:103]
	v_mfma_f32_16x16x32_bf16 v[96:99], v[196:199], v[156:159], v[96:99]
	v_mfma_f32_16x16x32_bf16 v[84:87], v[180:183], v[164:167], v[84:87]
	v_mfma_f32_16x16x32_bf16 v[80:83], v[196:199], v[164:167], v[80:83]
	v_mfma_f32_16x16x32_bf16 v[68:71], v[180:183], v[172:175], v[68:71]
	v_mfma_f32_16x16x32_bf16 v[64:67], v[196:199], v[172:175], v[64:67]
	s_setprio 0
	s_and_b32 s17, s17, 0xffff
	s_mov_b32 s18, s10
	s_mov_b32 s19, s11
	s_mov_b32 m0, s83
	s_barrier
; #define PG8_STAGE(bufoff, gbase, voff) do { const __amdgpu_buffer_rsrc_t _r = __builtin_amdgcn_make_buffer_rsrc((void*)(gbase), (short)0, 0x7fffffff, 0x00020000); _Pragma("unroll") for (int _i = 0; _i < 2; ++_i) \
;         __builtin_amdgcn_raw_ptr_buffer_load_lds(_r, (LAS unsigned*)(lds + (bufoff) + ldsw + _i * 8192), 16, (int)(voff)[_i], 0, 0, 0); } while (0)
; #define PG8_LDA(dst, b, h) do { _Pragma("unroll") for (int m = 0; m < 4; ++m) _Pragma("unroll") for (int k = 0; k < 2; ++k) dst[m][k] = *(const LAS bf16x8*)(lds + PG8_SA(b, h) + aoff + m * 2048 + k * 1024); } while (0)
; #define PG8_MMA(ai, bj, At, Bt) do { __builtin_amdgcn_s_setprio(1); _Pragma("unroll") for (int k = 0; k < 2; ++k) _Pragma("unroll") for (int m = 0; m < 4; ++m) _Pragma("unroll") for (int n = 0; n < ((bj) == 1 ? NB1 : 2); ++n) \
;         acc[ai][bj][m][n] = __builtin_amdgcn_mfma_f32_16x16x32_bf16(Bt[n][k], At[m][k], acc[ai][bj][m][n], 0, 0, 0); __builtin_amdgcn_s_setprio(0); } while (0)
; #define PG8_WAIT_V(n) asm volatile("s_waitcnt vmcnt(" #n ")" ::: "memory")
; #define PG8_WAIT_L(n) asm volatile("s_waitcnt lgkmcnt(" #n ")" ::: "memory")
; #define PG8_BAR __builtin_amdgcn_s_barrier()
; #define PG8_SCHED __builtin_amdgcn_sched_barrier(0)
;     ...
;             PG8_LDA(At, 1, 1); PG8_STAGE(PG8_SA(1, 0), a3, voffA);
;             PG8_BAR; PG8_WAIT_L(0); PG8_MMA(1, 0, At, B0); PG8_BAR; PG8_SCHED;
;             PG8_STAGE(PG8_SB(1, 1), b3 + hstepB, voffB);
;             PG8_WAIT_V(6); PG8_BAR; PG8_MMA(1, 1, At, B1); PG8_BAR;
;         }
	ds_read_b128 v[144:147], v228 offset:49152
	ds_read_b128 v[148:151], v228 offset:50176
	ds_read_b128 v[152:155], v228 offset:51200
	ds_read_b128 v[156:159], v228 offset:52224
	ds_read_b128 v[160:163], v228 offset:53248
	ds_read_b128 v[164:167], v228 offset:54272
	ds_read_b128 v[168:171], v228 offset:55296
	ds_read_b128 v[172:175], v228 offset:56320
	buffer_load_dwordx4 v222, s[16:19], 0 offen lds
	s_mov_b32 m0, s84
	s_nop 0
	buffer_load_dwordx4 v224, s[16:19], 0 offen lds
	s_barrier
	s_waitcnt lgkmcnt(0)
	s_setprio 1
	s_waitcnt lgkmcnt(7)
	v_mfma_f32_16x16x32_bf16 v[60:63], v[128:131], v[144:147], v[60:63]
	v_mfma_f32_16x16x32_bf16 v[56:59], v[136:139], v[144:147], v[56:59]
	s_waitcnt lgkmcnt(5)
	v_mfma_f32_16x16x32_bf16 v[44:47], v[128:131], v[152:155], v[44:47]
	v_mfma_f32_16x16x32_bf16 v[40:43], v[136:139], v[152:155], v[40:43]
	s_waitcnt lgkmcnt(3)
	v_mfma_f32_16x16x32_bf16 v[28:31], v[128:131], v[160:163], v[28:31]
	v_mfma_f32_16x16x32_bf16 v[24:27], v[136:139], v[160:163], v[24:27]
	s_waitcnt lgkmcnt(1)
	v_mfma_f32_16x16x32_bf16 v[12:15], v[128:131], v[168:171], v[12:15]
	v_mfma_f32_16x16x32_bf16 v[8:11], v[136:139], v[168:171], v[8:11]
	v_mfma_f32_16x16x32_bf16 v[60:63], v[132:135], v[148:151], v[60:63]
	v_mfma_f32_16x16x32_bf16 v[56:59], v[140:143], v[148:151], v[56:59]
	v_mfma_f32_16x16x32_bf16 v[44:47], v[132:135], v[156:159], v[44:47]
	v_mfma_f32_16x16x32_bf16 v[40:43], v[140:143], v[156:159], v[40:43]
	v_mfma_f32_16x16x32_bf16 v[28:31], v[132:135], v[164:167], v[28:31]
	v_mfma_f32_16x16x32_bf16 v[24:27], v[140:143], v[164:167], v[24:27]
	s_waitcnt lgkmcnt(0)
	v_mfma_f32_16x16x32_bf16 v[12:15], v[132:135], v[172:175], v[12:15]
	v_mfma_f32_16x16x32_bf16 v[8:11], v[140:143], v[172:175], v[8:11]
	s_setprio 0
	s_barrier
	s_add_u32 s8, s8, 0x80
	s_addc_u32 s9, s23, 0
	s_and_b32 s9, s9, 0xffff
	s_mov_b32 m0, s85
	s_nop 0
	buffer_load_dwordx4 v223, s[8:11], 0 offen lds
	s_mov_b32 m0, s86
	s_nop 0
	buffer_load_dwordx4 v225, s[8:11], 0 offen lds
	s_waitcnt vmcnt(6)
	s_barrier
	s_setprio 1
	v_mfma_f32_16x16x32_bf16 v[52:55], v[176:179], v[144:147], v[52:55]
	v_mfma_f32_16x16x32_bf16 v[48:51], v[192:195], v[144:147], v[48:51]
	v_mfma_f32_16x16x32_bf16 v[36:39], v[176:179], v[152:155], v[36:39]
	v_mfma_f32_16x16x32_bf16 v[32:35], v[192:195], v[152:155], v[32:35]
	v_mfma_f32_16x16x32_bf16 v[20:23], v[176:179], v[160:163], v[20:23]
	v_mfma_f32_16x16x32_bf16 v[16:19], v[192:195], v[160:163], v[16:19]
	v_mfma_f32_16x16x32_bf16 v[4:7], v[176:179], v[168:171], v[4:7]
	v_mfma_f32_16x16x32_bf16 v[0:3], v[192:195], v[168:171], v[0:3]
	v_mfma_f32_16x16x32_bf16 v[52:55], v[180:183], v[148:151], v[52:55]
	v_mfma_f32_16x16x32_bf16 v[48:51], v[196:199], v[148:151], v[48:51]
	v_mfma_f32_16x16x32_bf16 v[36:39], v[180:183], v[156:159], v[36:39]
	v_mfma_f32_16x16x32_bf16 v[32:35], v[196:199], v[156:159], v[32:35]
	v_mfma_f32_16x16x32_bf16 v[20:23], v[180:183], v[164:167], v[20:23]
	v_mfma_f32_16x16x32_bf16 v[16:19], v[196:199], v[164:167], v[16:19]
	v_mfma_f32_16x16x32_bf16 v[4:7], v[180:183], v[172:175], v[4:7]
	v_mfma_f32_16x16x32_bf16 v[0:3], v[196:199], v[172:175], v[0:3]
	s_setprio 0
	s_add_u32 s91, s91, 0x100
	s_addc_u32 s92, s92, 0
	s_add_u32 s93, s93, 0x100
	s_addc_u32 s94, s94, 0
	s_cmp_ge_i32 s22, s80
	s_mov_b32 s8, s22
	s_barrier
	s_cbranch_scc0 .LBB0_922

;     __device__ __forceinline__ size_t a_off(const Unit& u) const { return (size_t)u.pm * atile; }
;     __device__ __forceinline__ size_t b_off(const Unit& u) const { return (size_t)u.pn * btile; }
;     __device__ __forceinline__ bool next(int i, Unit& u) const { const long L = (long)i * G + c; if (L >= NG * 8) return false; u.g = (int)(L >> 3); u.pm = (int)(L & 7); u.pn = 0; return true; }
;     __device__ __forceinline__ size_t a_off(const Unit& u) const { return ((size_t)u.g * NROW + (size_t)u.pm * BM) * KA * 2; }
;     __device__ __forceinline__ size_t b_off(const Unit& u) const { return (size_t)u.g * btile; }
;     __device__ __forceinline__ bool next(int i, Unit& u) const { if (i >= 2) return false; u.g = g; u.pm = 2 * b + i; u.pn = 0; return true; }
;     __device__ __forceinline__ size_t a_off(const Unit& u) const { return ((size_t)u.g * NROW + (size_t)u.pm * BM) * KA * 2; }
;     __device__ __forceinline__ bool next(int i, Unit& u) const {
;         const long L = (long)i * G + c; if (L >= nwg) return false;
;         int wgid = (int)L; { const int q = nwg / NXCD, r = nwg % NXCD, xcd = wgid % NXCD, off = wgid / NXCD; wgid = (xcd < r ? xcd * (q + 1) : r * (q + 1) + (xcd - r) * q) + off; }
;         const int nig = WGM * nN, gid = wgid / nig, fm = gid * WGM, gsz = (nM - fm) < WGM ? (nM - fm) : WGM;
;         u.pm = __builtin_amdgcn_readfirstlane(fm + ((wgid % nig) % gsz)); u.pn = __builtin_amdgcn_readfirstlane((wgid % nig) / gsz); u.g = 0; return true;
;     ...
;         const bool has_next = S.next(ui + 1, nxt);
;         const char* nA = has_next ? (const char*)Ap + S.a_off(nxt) : cA; const char* nB = has_next ? (const char*)Btp + S.b_off(nxt) : cB;
;         for (int t = 0; t < nt; t += 2) {
;             const bool last = (t == nt - 2);
;             const char* a1 = cA + (size_t)(t + 1) * kstep;
;             const char* a2 = last ? nA : cA + (size_t)(t + 2) * kstep; const char* b2 = last ? nB : cB + (size_t)(t + 2) * kstep;
;             const char* a3 = a2 + kstep; const char* b3 = b2 + kstep;
;             PG8_LDB(B0, 0, 0); PG8_SCHED; PG8_LDA(At, 0, 0); PG8_STAGE(PG8_SA(1, 1), a1 + hstepA, voffA);
;             PG8_WAIT_L(8); PG8_BAR; PG8_WAIT_L(0); PG8_MMA(0, 0, At, B0); PG8_BAR; PG8_SCHED;
;             PG8_LDB(B1, 0, 1); PG8_STAGE(PG8_SB(0, 0), b2, voffB);
;             PG8_BAR; PG8_WAIT_L(0); PG8_MMA(0, 1, At, B1); PG8_BAR;
.LBB0_980:
	s_add_i32 s49, s49, 1
	s_mul_i32 s12, s49, s3
	s_mul_hi_u32 s13, s49, s34
	s_add_i32 s13, s13, s12
	s_mul_i32 s12, s49, s34
	s_add_u32 s12, s12, s2
	s_addc_u32 s13, s13, s33
	v_cmp_gt_i64_e32 vcc, s[12:13], v[172:173]
	s_cbranch_vccnz .LBB0_982
	s_add_i32 s52, s70, 4
	s_cmp_ge_i32 s52, 22
	s_cselect_b32 s16, 22, 0
	s_cselect_b32 s17, 8, 0
	s_sub_i32 s52, s52, s16
	s_add_i32 s56, s66, s17
.LBB0_982:
	s_ashr_i32 s57, s56, 31
	s_lshl_b64 s[16:17], s[56:57], 19
	s_add_u32 s58, s20, s16
	s_addc_u32 s59, s21, s17
	s_ashr_i32 s53, s52, 31
	s_lshl_b64 s[16:17], s[52:53], 19
	s_add_u32 s64, s75, s16
	v_cmp_lt_i64_e64 s[12:13], s[12:13], v[170:171]
	s_addc_u32 s65, s76, s17
	s_andn2_b64 vcc, exec, s[50:51]
	s_cbranch_vccnz .Lkzero_984
	s_and_b64 s[16:17], s[12:13], exec
	s_cselect_b32 s53, s59, s27
	s_cselect_b32 s57, s58, s26
	s_cselect_b32 s94, s65, s25
	s_cselect_b32 s95, s64, s24
	s_add_u32 s96, s26, 0x100
	s_addc_u32 s97, s27, 0
	s_add_u32 vcc_lo, s24, 0x100
	s_addc_u32 vcc_hi, s25, 0
	s_mov_b32 s16, 0
	ds_read_b128 v[76:79], v193
	ds_read_b128 v[88:91], v193 offset:1024
	ds_read_b128 v[92:95], v193 offset:2048
	ds_read_b128 v[128:131], v193 offset:3072
	s_add_i32 s22, s16, 2
	s_cmp_eq_u32 s90, s16
	s_cselect_b32 s36, s57, s96
	s_cselect_b32 s26, s53, s97
	s_cselect_b32 s25, s94, vcc_hi
	s_cselect_b32 s28, s95, vcc_lo
	s_add_u32 s24, s36, 0x80
	s_addc_u32 s23, s26, 0
	s_add_u32 s16, s96, s44
	s_addc_u32 s17, s97, s45
	s_add_u32 s16, s16, 0xffffff80
	s_addc_u32 s17, s17, -1
	s_and_b32 s17, s17, 0xffff
	s_mov_b32 m0, s91
	ds_read_b128 v[132:135], v194
	ds_read_b128 v[136:139], v194 offset:1024
	ds_read_b128 v[140:143], v194 offset:2048
	ds_read_b128 v[174:177], v194 offset:3072
	ds_read_b128 v[178:181], v194 offset:4096
	ds_read_b128 v[182:185], v194 offset:5120
	ds_read_b128 v[202:205], v194 offset:6144
	ds_read_b128 v[206:209], v194 offset:7168
	buffer_load_dwordx4 v186, s[16:19], 0 offen lds
	s_mov_b32 m0, s92
	s_nop 0
	buffer_load_dwordx4 v188, s[16:19], 0 offen lds
	s_waitcnt lgkmcnt(8)
	s_barrier
	s_waitcnt lgkmcnt(0)
	s_setprio 1
	s_waitcnt lgkmcnt(7)
	v_mfma_f32_16x16x32_bf16 v[152:155], v[76:79], v[132:135], 0
	v_mfma_f32_16x16x32_bf16 v[144:147], v[92:95], v[132:135], 0
	s_waitcnt lgkmcnt(5)
	v_mfma_f32_16x16x32_bf16 v[124:127], v[76:79], v[140:143], 0
	v_mfma_f32_16x16x32_bf16 v[120:123], v[92:95], v[140:143], 0
	s_waitcnt lgkmcnt(3)
	v_mfma_f32_16x16x32_bf16 v[108:111], v[76:79], v[178:181], 0
	v_mfma_f32_16x16x32_bf16 v[104:107], v[92:95], v[178:181], 0
	s_waitcnt lgkmcnt(1)
	v_mfma_f32_16x16x32_bf16 v[84:87], v[76:79], v[202:205], 0
	v_mfma_f32_16x16x32_bf16 v[80:83], v[92:95], v[202:205], 0
	v_mfma_f32_16x16x32_bf16 v[152:155], v[88:91], v[136:139], v[152:155]
	v_mfma_f32_16x16x32_bf16 v[144:147], v[128:131], v[136:139], v[144:147]
	v_mfma_f32_16x16x32_bf16 v[124:127], v[88:91], v[174:177], v[124:127]
	v_mfma_f32_16x16x32_bf16 v[120:123], v[128:131], v[174:177], v[120:123]
	v_mfma_f32_16x16x32_bf16 v[108:111], v[88:91], v[182:185], v[108:111]
	v_mfma_f32_16x16x32_bf16 v[104:107], v[128:131], v[182:185], v[104:107]
	s_waitcnt lgkmcnt(0)
	v_mfma_f32_16x16x32_bf16 v[84:87], v[88:91], v[206:209], v[84:87]
	v_mfma_f32_16x16x32_bf16 v[80:83], v[128:131], v[206:209], v[80:83]
	s_setprio 0
	s_barrier
	s_and_b32 s29, s25, 0xffff
	s_mov_b32 s30, s18
	s_mov_b32 s31, s19
	s_mov_b32 m0, s71
	ds_read_b128 v[210:213], v195
	ds_read_b128 v[214:217], v195 offset:1024
	ds_read_b128 v[218:221], v195 offset:2048
	ds_read_b128 v[222:225], v195 offset:3072
	buffer_load_dwordx4 v187, s[28:31], 0 offen lds
	s_mov_b32 m0, s77
	s_nop 0
	buffer_load_dwordx4 v189, s[28:31], 0 offen lds
	s_barrier
; #define PG8_STAGE(bufoff, gbase, voff) do { const __amdgpu_buffer_rsrc_t _r = __builtin_amdgcn_make_buffer_rsrc((void*)(gbase), (short)0, 0x7fffffff, 0x00020000); _Pragma("unroll") for (int _i = 0; _i < 2; ++_i) \
;         __builtin_amdgcn_raw_ptr_buffer_load_lds(_r, (LAS unsigned*)(lds + (bufoff) + ldsw + _i * 8192), 16, (int)(voff)[_i], 0, 0, 0); } while (0)
; #define PG8_LDA(dst, b, h) do { _Pragma("unroll") for (int m = 0; m < 4; ++m) _Pragma("unroll") for (int k = 0; k < 2; ++k) dst[m][k] = *(const LAS bf16x8*)(lds + PG8_SA(b, h) + aoff + m * 2048 + k * 1024); } while (0)
; #define PG8_MMA(ai, bj, At, Bt) do { __builtin_amdgcn_s_setprio(1); _Pragma("unroll") for (int k = 0; k < 2; ++k) _Pragma("unroll") for (int m = 0; m < 4; ++m) _Pragma("unroll") for (int n = 0; n < ((bj) == 1 ? NB1 : 2); ++n) \
;         acc[ai][bj][m][n] = __builtin_amdgcn_mfma_f32_16x16x32_bf16(Bt[n][k], At[m][k], acc[ai][bj][m][n], 0, 0, 0); __builtin_amdgcn_s_setprio(0); } while (0)
; #define PG8_WAIT_V(n) asm volatile("s_waitcnt vmcnt(" #n ")" ::: "memory")
; #define PG8_WAIT_L(n) asm volatile("s_waitcnt lgkmcnt(" #n ")" ::: "memory")
; #define PG8_BAR __builtin_amdgcn_s_barrier()
; #define PG8_SCHED __builtin_amdgcn_sched_barrier(0)
;     ...
;             PG8_BAR; PG8_WAIT_L(0); PG8_MMA(0, 1, At, B1); PG8_BAR;
;             PG8_LDA(At, 0, 1); PG8_STAGE(PG8_SA(0, 0), a2, voffA);
;             PG8_BAR; PG8_WAIT_L(0); PG8_MMA(1, 0, At, B0); PG8_BAR; PG8_SCHED;
;             PG8_STAGE(PG8_SB(0, 1), b2 + hstepB, voffB);
;             PG8_WAIT_V(6); PG8_BAR; PG8_MMA(1, 1, At, B1); PG8_BAR;
	s_waitcnt lgkmcnt(0)
	s_setprio 1
	s_waitcnt lgkmcnt(3)
	v_mfma_f32_16x16x32_bf16 v[116:119], v[210:213], v[140:143], 0
	s_waitcnt lgkmcnt(1)
	v_mfma_f32_16x16x32_bf16 v[112:115], v[218:221], v[140:143], 0
	v_mfma_f32_16x16x32_bf16 v[100:103], v[210:213], v[178:181], 0
	v_mfma_f32_16x16x32_bf16 v[96:99], v[218:221], v[178:181], 0
	v_mfma_f32_16x16x32_bf16 v[68:71], v[210:213], v[202:205], 0
	v_mfma_f32_16x16x32_bf16 v[64:67], v[218:221], v[202:205], 0
	v_mfma_f32_16x16x32_bf16 v[156:159], v[210:213], v[132:135], 0
	v_mfma_f32_16x16x32_bf16 v[132:135], v[218:221], v[132:135], 0
	v_mfma_f32_16x16x32_bf16 v[116:119], v[214:217], v[174:177], v[116:119]
	s_waitcnt lgkmcnt(0)
	v_mfma_f32_16x16x32_bf16 v[112:115], v[222:225], v[174:177], v[112:115]
	v_mfma_f32_16x16x32_bf16 v[100:103], v[214:217], v[182:185], v[100:103]
	v_mfma_f32_16x16x32_bf16 v[96:99], v[222:225], v[182:185], v[96:99]
	v_mfma_f32_16x16x32_bf16 v[68:71], v[214:217], v[206:209], v[68:71]
	v_mfma_f32_16x16x32_bf16 v[64:67], v[222:225], v[206:209], v[64:67]
	v_mfma_f32_16x16x32_bf16 v[140:143], v[214:217], v[136:139], v[156:159]
	v_mfma_f32_16x16x32_bf16 v[132:135], v[222:225], v[136:139], v[132:135]
	s_setprio 0
	s_and_b32 s37, s26, 0xffff
	s_mov_b32 s38, s18
	s_mov_b32 s39, s19
	s_mov_b32 m0, s67
	s_barrier
	ds_read_b128 v[136:139], v194 offset:16384
	ds_read_b128 v[148:151], v194 offset:17408
	ds_read_b128 v[156:159], v194 offset:18432
	ds_read_b128 v[174:177], v194 offset:19456
	ds_read_b128 v[178:181], v194 offset:20480
	ds_read_b128 v[182:185], v194 offset:21504
	ds_read_b128 v[202:205], v194 offset:22528
	ds_read_b128 v[206:209], v194 offset:23552
	buffer_load_dwordx4 v186, s[36:39], 0 offen lds
	s_mov_b32 m0, s78
	s_nop 0
	buffer_load_dwordx4 v188, s[36:39], 0 offen lds
	s_barrier
	s_waitcnt lgkmcnt(0)
	s_setprio 1
	s_waitcnt lgkmcnt(7)
	v_mfma_f32_16x16x32_bf16 v[60:63], v[76:79], v[136:139], 0
	v_mfma_f32_16x16x32_bf16 v[52:55], v[92:95], v[136:139], 0
	s_waitcnt lgkmcnt(5)
	v_mfma_f32_16x16x32_bf16 v[44:47], v[76:79], v[156:159], 0
	v_mfma_f32_16x16x32_bf16 v[40:43], v[92:95], v[156:159], 0
	s_waitcnt lgkmcnt(3)
	v_mfma_f32_16x16x32_bf16 v[28:31], v[76:79], v[178:181], 0
	v_mfma_f32_16x16x32_bf16 v[24:27], v[92:95], v[178:181], 0
	s_waitcnt lgkmcnt(1)
	v_mfma_f32_16x16x32_bf16 v[12:15], v[76:79], v[202:205], 0
	v_mfma_f32_16x16x32_bf16 v[8:11], v[92:95], v[202:205], 0
	v_mfma_f32_16x16x32_bf16 v[60:63], v[88:91], v[148:151], v[60:63]
	v_mfma_f32_16x16x32_bf16 v[52:55], v[128:131], v[148:151], v[52:55]
	v_mfma_f32_16x16x32_bf16 v[44:47], v[88:91], v[174:177], v[44:47]
	v_mfma_f32_16x16x32_bf16 v[40:43], v[128:131], v[174:177], v[40:43]
	v_mfma_f32_16x16x32_bf16 v[28:31], v[88:91], v[182:185], v[28:31]
	v_mfma_f32_16x16x32_bf16 v[24:27], v[128:131], v[182:185], v[24:27]
	s_waitcnt lgkmcnt(0)
	v_mfma_f32_16x16x32_bf16 v[12:15], v[88:91], v[206:209], v[12:15]
	v_mfma_f32_16x16x32_bf16 v[8:11], v[128:131], v[206:209], v[8:11]
	s_setprio 0
	s_barrier
	s_add_u32 s16, s28, s46
	s_addc_u32 s14, s25, s47
	s_and_b32 s17, s14, 0xffff
	s_mov_b32 m0, s79
	s_nop 0
	buffer_load_dwordx4 v187, s[16:19], 0 offen lds
	s_mov_b32 m0, s80
	s_nop 0
	buffer_load_dwordx4 v189, s[16:19], 0 offen lds
	s_waitcnt vmcnt(6)
	s_barrier
	s_setprio 1
	v_mfma_f32_16x16x32_bf16 v[56:59], v[210:213], v[136:139], 0
	v_mfma_f32_16x16x32_bf16 v[48:51], v[218:221], v[136:139], 0
	v_mfma_f32_16x16x32_bf16 v[36:39], v[210:213], v[156:159], 0
	v_mfma_f32_16x16x32_bf16 v[32:35], v[218:221], v[156:159], 0
	v_mfma_f32_16x16x32_bf16 v[20:23], v[210:213], v[178:181], 0
	v_mfma_f32_16x16x32_bf16 v[16:19], v[218:221], v[178:181], 0
	v_mfma_f32_16x16x32_bf16 v[4:7], v[210:213], v[202:205], 0
	v_mfma_f32_16x16x32_bf16 v[0:3], v[218:221], v[202:205], 0
	v_mfma_f32_16x16x32_bf16 v[56:59], v[214:217], v[148:151], v[56:59]
	v_mfma_f32_16x16x32_bf16 v[48:51], v[222:225], v[148:151], v[48:51]
	v_mfma_f32_16x16x32_bf16 v[36:39], v[214:217], v[174:177], v[36:39]
	v_mfma_f32_16x16x32_bf16 v[32:35], v[222:225], v[174:177], v[32:35]
	v_mfma_f32_16x16x32_bf16 v[20:23], v[214:217], v[182:185], v[20:23]
	v_mfma_f32_16x16x32_bf16 v[16:19], v[222:225], v[182:185], v[16:19]
	v_mfma_f32_16x16x32_bf16 v[4:7], v[214:217], v[206:209], v[4:7]
	v_mfma_f32_16x16x32_bf16 v[0:3], v[222:225], v[206:209], v[0:3]
	s_setprio 0
	s_barrier
	s_branch .Lkmid_984

; #define PG8_STAGE(bufoff, gbase, voff) do { const __amdgpu_buffer_rsrc_t _r = __builtin_amdgcn_make_buffer_rsrc((void*)(gbase), (short)0, 0x7fffffff, 0x00020000); _Pragma("unroll") for (int _i = 0; _i < 2; ++_i) \
;         __builtin_amdgcn_raw_ptr_buffer_load_lds(_r, (LAS unsigned*)(lds + (bufoff) + ldsw + _i * 8192), 16, (int)(voff)[_i], 0, 0, 0); } while (0)
; #define PG8_LDA(dst, b, h) do { _Pragma("unroll") for (int m = 0; m < 4; ++m) _Pragma("unroll") for (int k = 0; k < 2; ++k) dst[m][k] = *(const LAS bf16x8*)(lds + PG8_SA(b, h) + aoff + m * 2048 + k * 1024); } while (0)
; #define PG8_LDB(dst, b, h) do { _Pragma("unroll") for (int n = 0; n < 2; ++n) _Pragma("unroll") for (int k = 0; k < 2; ++k) dst[n][k] = *(const LAS bf16x8*)(lds + PG8_SB(b, h) + boff + n * 2048 + k * 1024); } while (0)
; #define PG8_MMA(ai, bj, At, Bt) do { __builtin_amdgcn_s_setprio(1); _Pragma("unroll") for (int k = 0; k < 2; ++k) _Pragma("unroll") for (int m = 0; m < 4; ++m) _Pragma("unroll") for (int n = 0; n < ((bj) == 1 ? NB1 : 2); ++n) \
;         acc[ai][bj][m][n] = __builtin_amdgcn_mfma_f32_16x16x32_bf16(Bt[n][k], At[m][k], acc[ai][bj][m][n], 0, 0, 0); __builtin_amdgcn_s_setprio(0); } while (0)
; #define PG8_WAIT_L(n) asm volatile("s_waitcnt lgkmcnt(" #n ")" ::: "memory")
; #define PG8_BAR __builtin_amdgcn_s_barrier()
; #define PG8_SCHED __builtin_amdgcn_sched_barrier(0)
;     ...
;             PG8_LDB(B0, 1, 0); PG8_SCHED; PG8_LDA(At, 1, 0); PG8_STAGE(PG8_SA(0, 1), a2 + hstepA, voffA);
;             PG8_WAIT_L(8); PG8_BAR; PG8_WAIT_L(0); PG8_MMA(0, 0, At, B0); PG8_BAR; PG8_SCHED;
;             PG8_LDB(B1, 1, 1); PG8_STAGE(PG8_SB(1, 0), b3, voffB);
;             PG8_BAR; PG8_WAIT_L(0); PG8_MMA(0, 1, At, B1); PG8_BAR;
;             PG8_LDA(At, 1, 1); PG8_STAGE(PG8_SA(1, 0), a3, voffA);
;             PG8_BAR; PG8_WAIT_L(0); PG8_MMA(1, 0, At, B0); PG8_BAR; PG8_SCHED;
.Lkmid_984:
	ds_read_b128 v[76:79], v196
	ds_read_b128 v[88:91], v196 offset:1024
	ds_read_b128 v[92:95], v196 offset:2048
	ds_read_b128 v[128:131], v196 offset:3072
	s_add_u32 s36, s36, s44
	s_addc_u32 s17, s26, s45
	s_and_b32 s37, s17, 0xffff
	s_mov_b32 m0, s81
	ds_read_b128 v[136:139], v194 offset:32768
	ds_read_b128 v[148:151], v194 offset:33792
	ds_read_b128 v[156:159], v194 offset:34816
	ds_read_b128 v[174:177], v194 offset:35840
	ds_read_b128 v[178:181], v194 offset:36864
	ds_read_b128 v[182:185], v194 offset:37888
	ds_read_b128 v[202:205], v194 offset:38912
	ds_read_b128 v[206:209], v194 offset:39936
	buffer_load_dwordx4 v186, s[36:39], 0 offen lds
	s_mov_b32 m0, s82
	s_nop 0
	buffer_load_dwordx4 v188, s[36:39], 0 offen lds
	s_waitcnt lgkmcnt(8)
	s_barrier
	s_waitcnt lgkmcnt(0)
	s_setprio 1
	s_waitcnt lgkmcnt(7)
	v_mfma_f32_16x16x32_bf16 v[152:155], v[76:79], v[136:139], v[152:155]
	v_mfma_f32_16x16x32_bf16 v[144:147], v[92:95], v[136:139], v[144:147]
	s_waitcnt lgkmcnt(5)
	v_mfma_f32_16x16x32_bf16 v[124:127], v[76:79], v[156:159], v[124:127]
	v_mfma_f32_16x16x32_bf16 v[120:123], v[92:95], v[156:159], v[120:123]
	s_waitcnt lgkmcnt(3)
	v_mfma_f32_16x16x32_bf16 v[108:111], v[76:79], v[178:181], v[108:111]
	v_mfma_f32_16x16x32_bf16 v[104:107], v[92:95], v[178:181], v[104:107]
	s_waitcnt lgkmcnt(1)
	v_mfma_f32_16x16x32_bf16 v[84:87], v[76:79], v[202:205], v[84:87]
	v_mfma_f32_16x16x32_bf16 v[80:83], v[92:95], v[202:205], v[80:83]
	v_mfma_f32_16x16x32_bf16 v[152:155], v[88:91], v[148:151], v[152:155]
	v_mfma_f32_16x16x32_bf16 v[144:147], v[128:131], v[148:151], v[144:147]
	v_mfma_f32_16x16x32_bf16 v[124:127], v[88:91], v[174:177], v[124:127]
	v_mfma_f32_16x16x32_bf16 v[120:123], v[128:131], v[174:177], v[120:123]
	v_mfma_f32_16x16x32_bf16 v[108:111], v[88:91], v[182:185], v[108:111]
	v_mfma_f32_16x16x32_bf16 v[104:107], v[128:131], v[182:185], v[104:107]
	s_waitcnt lgkmcnt(0)
	v_mfma_f32_16x16x32_bf16 v[84:87], v[88:91], v[206:209], v[84:87]
	v_mfma_f32_16x16x32_bf16 v[80:83], v[128:131], v[206:209], v[80:83]
	s_setprio 0
	s_barrier
	s_add_u32 s28, s28, 0x80
	s_addc_u32 s17, s25, 0
	s_and_b32 s29, s17, 0xffff
	s_mov_b32 m0, s84
	ds_read_b128 v[210:213], v197
	ds_read_b128 v[214:217], v197 offset:1024
	ds_read_b128 v[218:221], v197 offset:2048
	ds_read_b128 v[222:225], v197 offset:3072
	buffer_load_dwordx4 v187, s[28:31], 0 offen lds
	s_mov_b32 m0, s85
	s_nop 0
	buffer_load_dwordx4 v189, s[28:31], 0 offen lds
	s_barrier
	s_waitcnt lgkmcnt(0)
	s_setprio 1
	s_waitcnt lgkmcnt(3)
	v_mfma_f32_16x16x32_bf16 v[140:143], v[210:213], v[136:139], v[140:143]
	s_waitcnt lgkmcnt(1)
	v_mfma_f32_16x16x32_bf16 v[132:135], v[218:221], v[136:139], v[132:135]
	v_mfma_f32_16x16x32_bf16 v[116:119], v[210:213], v[156:159], v[116:119]
	v_mfma_f32_16x16x32_bf16 v[112:115], v[218:221], v[156:159], v[112:115]
	v_mfma_f32_16x16x32_bf16 v[100:103], v[210:213], v[178:181], v[100:103]
	v_mfma_f32_16x16x32_bf16 v[96:99], v[218:221], v[178:181], v[96:99]
	v_mfma_f32_16x16x32_bf16 v[68:71], v[210:213], v[202:205], v[68:71]
	v_mfma_f32_16x16x32_bf16 v[64:67], v[218:221], v[202:205], v[64:67]
	v_mfma_f32_16x16x32_bf16 v[156:159], v[214:217], v[148:151], v[140:143]
	s_waitcnt lgkmcnt(0)
	v_mfma_f32_16x16x32_bf16 v[148:151], v[222:225], v[148:151], v[132:135]
	v_mfma_f32_16x16x32_bf16 v[116:119], v[214:217], v[174:177], v[116:119]
	v_mfma_f32_16x16x32_bf16 v[112:115], v[222:225], v[174:177], v[112:115]
	v_mfma_f32_16x16x32_bf16 v[100:103], v[214:217], v[182:185], v[100:103]
	v_mfma_f32_16x16x32_bf16 v[96:99], v[222:225], v[182:185], v[96:99]
	v_mfma_f32_16x16x32_bf16 v[68:71], v[214:217], v[206:209], v[68:71]
	v_mfma_f32_16x16x32_bf16 v[64:67], v[222:225], v[206:209], v[64:67]
	s_setprio 0
	s_and_b32 s25, s23, 0xffff
	s_mov_b32 s26, s18
	s_mov_b32 s27, s19
	s_mov_b32 m0, s86
	s_barrier
; #define PG8_STAGE(bufoff, gbase, voff) do { const __amdgpu_buffer_rsrc_t _r = __builtin_amdgcn_make_buffer_rsrc((void*)(gbase), (short)0, 0x7fffffff, 0x00020000); _Pragma("unroll") for (int _i = 0; _i < 2; ++_i) \
;         __builtin_amdgcn_raw_ptr_buffer_load_lds(_r, (LAS unsigned*)(lds + (bufoff) + ldsw + _i * 8192), 16, (int)(voff)[_i], 0, 0, 0); } while (0)
; #define PG8_LDA(dst, b, h) do { _Pragma("unroll") for (int m = 0; m < 4; ++m) _Pragma("unroll") for (int k = 0; k < 2; ++k) dst[m][k] = *(const LAS bf16x8*)(lds + PG8_SA(b, h) + aoff + m * 2048 + k * 1024); } while (0)
; #define PG8_MMA(ai, bj, At, Bt) do { __builtin_amdgcn_s_setprio(1); _Pragma("unroll") for (int k = 0; k < 2; ++k) _Pragma("unroll") for (int m = 0; m < 4; ++m) _Pragma("unroll") for (int n = 0; n < ((bj) == 1 ? NB1 : 2); ++n) \
;         acc[ai][bj][m][n] = __builtin_amdgcn_mfma_f32_16x16x32_bf16(Bt[n][k], At[m][k], acc[ai][bj][m][n], 0, 0, 0); __builtin_amdgcn_s_setprio(0); } while (0)
; #define PG8_WAIT_V(n) asm volatile("s_waitcnt vmcnt(" #n ")" ::: "memory")
; #define PG8_WAIT_L(n) asm volatile("s_waitcnt lgkmcnt(" #n ")" ::: "memory")
; #define PG8_BAR __builtin_amdgcn_s_barrier()
; #define PG8_SCHED __builtin_amdgcn_sched_barrier(0)
;     ...
;             PG8_LDA(At, 1, 1); PG8_STAGE(PG8_SA(1, 0), a3, voffA);
;             PG8_BAR; PG8_WAIT_L(0); PG8_MMA(1, 0, At, B0); PG8_BAR; PG8_SCHED;
;             PG8_STAGE(PG8_SB(1, 1), b3 + hstepB, voffB);
;             PG8_WAIT_V(6); PG8_BAR; PG8_MMA(1, 1, At, B1); PG8_BAR;
;         }
	ds_read_b128 v[132:135], v194 offset:49152
	ds_read_b128 v[136:139], v194 offset:50176
	ds_read_b128 v[140:143], v194 offset:51200
	ds_read_b128 v[174:177], v194 offset:52224
	ds_read_b128 v[178:181], v194 offset:53248
	ds_read_b128 v[182:185], v194 offset:54272
	ds_read_b128 v[202:205], v194 offset:55296
	ds_read_b128 v[206:209], v194 offset:56320
	buffer_load_dwordx4 v186, s[24:27], 0 offen lds
	s_mov_b32 m0, s87
	s_nop 0
	buffer_load_dwordx4 v188, s[24:27], 0 offen lds
	s_barrier
	s_waitcnt lgkmcnt(0)
	s_setprio 1
	s_waitcnt lgkmcnt(7)
	v_mfma_f32_16x16x32_bf16 v[60:63], v[76:79], v[132:135], v[60:63]
	v_mfma_f32_16x16x32_bf16 v[52:55], v[92:95], v[132:135], v[52:55]
	s_waitcnt lgkmcnt(5)
	v_mfma_f32_16x16x32_bf16 v[44:47], v[76:79], v[140:143], v[44:47]
	v_mfma_f32_16x16x32_bf16 v[40:43], v[92:95], v[140:143], v[40:43]
	s_waitcnt lgkmcnt(3)
	v_mfma_f32_16x16x32_bf16 v[28:31], v[76:79], v[178:181], v[28:31]
	v_mfma_f32_16x16x32_bf16 v[24:27], v[92:95], v[178:181], v[24:27]
	s_waitcnt lgkmcnt(1)
	v_mfma_f32_16x16x32_bf16 v[12:15], v[76:79], v[202:205], v[12:15]
	v_mfma_f32_16x16x32_bf16 v[8:11], v[92:95], v[202:205], v[8:11]
	v_mfma_f32_16x16x32_bf16 v[60:63], v[88:91], v[136:139], v[60:63]
	v_mfma_f32_16x16x32_bf16 v[52:55], v[128:131], v[136:139], v[52:55]
	v_mfma_f32_16x16x32_bf16 v[44:47], v[88:91], v[174:177], v[44:47]
	v_mfma_f32_16x16x32_bf16 v[40:43], v[128:131], v[174:177], v[40:43]
	v_mfma_f32_16x16x32_bf16 v[28:31], v[88:91], v[182:185], v[28:31]
	v_mfma_f32_16x16x32_bf16 v[24:27], v[128:131], v[182:185], v[24:27]
	s_waitcnt lgkmcnt(0)
	v_mfma_f32_16x16x32_bf16 v[12:15], v[88:91], v[206:209], v[12:15]
	v_mfma_f32_16x16x32_bf16 v[8:11], v[128:131], v[206:209], v[8:11]
	s_setprio 0
	s_barrier
	s_add_u32 s16, s16, 0x80
	s_addc_u32 s14, s14, 0
	s_and_b32 s17, s14, 0xffff
	s_mov_b32 m0, s88
	s_nop 0
	buffer_load_dwordx4 v187, s[16:19], 0 offen lds
	s_mov_b32 m0, s89
	s_nop 0
	buffer_load_dwordx4 v189, s[16:19], 0 offen lds
	s_waitcnt vmcnt(6)
	s_barrier
	s_setprio 1
	v_mfma_f32_16x16x32_bf16 v[56:59], v[210:213], v[132:135], v[56:59]
	v_mfma_f32_16x16x32_bf16 v[48:51], v[218:221], v[132:135], v[48:51]
	v_mfma_f32_16x16x32_bf16 v[36:39], v[210:213], v[140:143], v[36:39]
	v_mfma_f32_16x16x32_bf16 v[32:35], v[218:221], v[140:143], v[32:35]
	v_mfma_f32_16x16x32_bf16 v[20:23], v[210:213], v[178:181], v[20:23]
	v_mfma_f32_16x16x32_bf16 v[16:19], v[218:221], v[178:181], v[16:19]
	v_mfma_f32_16x16x32_bf16 v[4:7], v[210:213], v[202:205], v[4:7]
	v_mfma_f32_16x16x32_bf16 v[0:3], v[218:221], v[202:205], v[0:3]
	v_mfma_f32_16x16x32_bf16 v[56:59], v[214:217], v[136:139], v[56:59]
	v_mfma_f32_16x16x32_bf16 v[48:51], v[222:225], v[136:139], v[48:51]
	v_mfma_f32_16x16x32_bf16 v[36:39], v[214:217], v[174:177], v[36:39]
	v_mfma_f32_16x16x32_bf16 v[32:35], v[222:225], v[174:177], v[32:35]
	v_mfma_f32_16x16x32_bf16 v[20:23], v[214:217], v[182:185], v[20:23]
	v_mfma_f32_16x16x32_bf16 v[16:19], v[222:225], v[182:185], v[16:19]
	v_mfma_f32_16x16x32_bf16 v[4:7], v[214:217], v[206:209], v[4:7]
	v_mfma_f32_16x16x32_bf16 v[0:3], v[222:225], v[206:209], v[0:3]
	s_setprio 0
	s_add_u32 s96, s96, 0x100
	s_addc_u32 s97, s97, 0
	s_add_u32 vcc_lo, vcc_lo, 0x100
	s_addc_u32 vcc_hi, vcc_hi, 0
	s_cmp_ge_i32 s22, s83
	s_mov_b32 s16, s22
	s_barrier
	s_cbranch_scc0 .LBB0_984
	v_readlane_b32 s96, v252, 38
	v_readlane_b32 s97, v252, 39

;     __device__ __forceinline__ size_t a_off(const Unit& u) const { return (size_t)u.pm * atile; }
;     __device__ __forceinline__ size_t b_off(const Unit& u) const { return (size_t)u.pn * btile; }
;     __device__ __forceinline__ bool next(int i, Unit& u) const { const long L = (long)i * G + c; if (L >= NG * 8) return false; u.g = (int)(L >> 3); u.pm = (int)(L & 7); u.pn = 0; return true; }
;     __device__ __forceinline__ size_t a_off(const Unit& u) const { return ((size_t)u.g * NROW + (size_t)u.pm * BM) * KA * 2; }
;     __device__ __forceinline__ size_t b_off(const Unit& u) const { return (size_t)u.g * btile; }
;     __device__ __forceinline__ bool next(int i, Unit& u) const { if (i >= 2) return false; u.g = g; u.pm = 2 * b + i; u.pn = 0; return true; }
;     __device__ __forceinline__ size_t a_off(const Unit& u) const { return ((size_t)u.g * NROW + (size_t)u.pm * BM) * KA * 2; }
;     __device__ __forceinline__ size_t b_off(const Unit& u) const { return (size_t)u.g * btile; }
; #define PG8_STAGE(bufoff, gbase, voff) do { const __amdgpu_buffer_rsrc_t _r = __builtin_amdgcn_make_buffer_rsrc((void*)(gbase), (short)0, 0x7fffffff, 0x00020000); _Pragma("unroll") for (int _i = 0; _i < 2; ++_i) \
;         __builtin_amdgcn_raw_ptr_buffer_load_lds(_r, (LAS unsigned*)(lds + (bufoff) + ldsw + _i * 8192), 16, (int)(voff)[_i], 0, 0, 0); } while (0)
; #define PG8_WAIT_L(n) asm volatile("s_waitcnt lgkmcnt(" #n ")" ::: "memory")
; #define PG8_BAR __builtin_amdgcn_s_barrier()
;     ...
;         const bool has_next = S.next(ui + 1, nxt);
;         const char* nA = has_next ? (const char*)Ap + S.a_off(nxt) : cA; const char* nB = has_next ? (const char*)Btp + S.b_off(nxt) : cB;
;         for (int t = 0; t < nt; t += 2) {
;             const bool last = (t == nt - 2);
;             const char* a1 = cA + (size_t)(t + 1) * kstep;
;             const char* a2 = last ? nA : cA + (size_t)(t + 2) * kstep; const char* b2 = last ? nB : cB + (size_t)(t + 2) * kstep;
;             const char* a3 = a2 + kstep; const char* b3 = b2 + kstep;
;             PG8_LDB(B0, 0, 0); PG8_SCHED; PG8_LDA(At, 0, 0); PG8_STAGE(PG8_SA(1, 1), a1 + hstepA, voffA);
;             PG8_WAIT_L(8); PG8_BAR; PG8_WAIT_L(0); PG8_MMA(0, 0, At, B0); PG8_BAR; PG8_SCHED;
;             PG8_LDB(B1, 0, 1); PG8_STAGE(PG8_SB(0, 0), b2, voffB);
;             PG8_BAR; PG8_WAIT_L(0); PG8_MMA(0, 1, At, B1); PG8_BAR;
.LBB0_1064:
	s_andn2_b64 vcc, exec, s[42:43]
	s_waitcnt lgkmcnt(0)
	s_cbranch_vccnz .Lkzero_1066
	s_add_u32 s79, s18, 0x100
	s_addc_u32 s80, s19, 0
	s_add_u32 s81, s16, 0x100
	s_addc_u32 s82, s17, 0
	s_mov_b32 s8, 0
	ds_read_b128 v[128:131], v227
	ds_read_b128 v[132:135], v227 offset:1024
	ds_read_b128 v[136:139], v227 offset:2048
	ds_read_b128 v[140:143], v227 offset:3072
	s_add_i32 s22, s8, 2
	s_cmp_eq_u32 s71, s8
	s_cselect_b32 s28, s0, s79
	s_cselect_b32 s19, s1, s80
	s_cselect_b32 s18, s45, s82
	s_cselect_b32 s24, s44, s81
	s_add_u32 s16, s28, 0x80
	s_addc_u32 s17, s19, 0
	s_add_u32 s8, s79, s36
	s_addc_u32 s9, s80, s37
	s_add_u32 s8, s8, 0xffffff80
	s_addc_u32 s9, s9, -1
	s_and_b32 s9, s9, 0xffff
	s_mov_b32 m0, s72
	ds_read_b128 v[144:147], v228
	ds_read_b128 v[148:151], v228 offset:1024
	ds_read_b128 v[152:155], v228 offset:2048
	ds_read_b128 v[156:159], v228 offset:3072
	ds_read_b128 v[160:163], v228 offset:4096
	ds_read_b128 v[164:167], v228 offset:5120
	ds_read_b128 v[168:171], v228 offset:6144
	ds_read_b128 v[172:175], v228 offset:7168
	buffer_load_dwordx4 v222, s[8:11], 0 offen lds
	s_mov_b32 m0, s73
	s_nop 0
	buffer_load_dwordx4 v224, s[8:11], 0 offen lds
	s_waitcnt lgkmcnt(8)
	s_barrier
	s_waitcnt lgkmcnt(0)
	s_setprio 1
	s_waitcnt lgkmcnt(7)
	v_mfma_f32_16x16x32_bf16 v[120:123], v[128:131], v[144:147], 0
	v_mfma_f32_16x16x32_bf16 v[124:127], v[136:139], v[144:147], 0
	s_waitcnt lgkmcnt(5)
	v_mfma_f32_16x16x32_bf16 v[108:111], v[128:131], v[152:155], 0
	v_mfma_f32_16x16x32_bf16 v[104:107], v[136:139], v[152:155], 0
	s_waitcnt lgkmcnt(3)
	v_mfma_f32_16x16x32_bf16 v[92:95], v[128:131], v[160:163], 0
	v_mfma_f32_16x16x32_bf16 v[88:91], v[136:139], v[160:163], 0
	s_waitcnt lgkmcnt(1)
	v_mfma_f32_16x16x32_bf16 v[76:79], v[128:131], v[168:171], 0
	v_mfma_f32_16x16x32_bf16 v[72:75], v[136:139], v[168:171], 0
	v_mfma_f32_16x16x32_bf16 v[120:123], v[132:135], v[148:151], v[120:123]
	v_mfma_f32_16x16x32_bf16 v[124:127], v[140:143], v[148:151], v[124:127]
	v_mfma_f32_16x16x32_bf16 v[108:111], v[132:135], v[156:159], v[108:111]
	v_mfma_f32_16x16x32_bf16 v[104:107], v[140:143], v[156:159], v[104:107]
	v_mfma_f32_16x16x32_bf16 v[92:95], v[132:135], v[164:167], v[92:95]
	v_mfma_f32_16x16x32_bf16 v[88:91], v[140:143], v[164:167], v[88:91]
	s_waitcnt lgkmcnt(0)
	v_mfma_f32_16x16x32_bf16 v[76:79], v[132:135], v[172:175], v[76:79]
	v_mfma_f32_16x16x32_bf16 v[72:75], v[140:143], v[172:175], v[72:75]
	s_setprio 0
	s_barrier
	s_and_b32 s25, s18, 0xffff
	s_mov_b32 s26, s10
	s_mov_b32 s27, s11
	s_mov_b32 m0, s50
	ds_read_b128 v[176:179], v229
	ds_read_b128 v[180:183], v229 offset:1024
	ds_read_b128 v[192:195], v229 offset:2048
	ds_read_b128 v[196:199], v229 offset:3072
	buffer_load_dwordx4 v223, s[24:27], 0 offen lds
	s_mov_b32 m0, s51
	s_nop 0
	buffer_load_dwordx4 v225, s[24:27], 0 offen lds
	s_barrier
	s_waitcnt lgkmcnt(0)
	s_setprio 1
	s_waitcnt lgkmcnt(3)
	v_mfma_f32_16x16x32_bf16 v[116:119], v[176:179], v[144:147], 0
	s_waitcnt lgkmcnt(1)
	v_mfma_f32_16x16x32_bf16 v[112:115], v[192:195], v[144:147], 0
	v_mfma_f32_16x16x32_bf16 v[100:103], v[176:179], v[152:155], 0
	v_mfma_f32_16x16x32_bf16 v[96:99], v[192:195], v[152:155], 0
	v_mfma_f32_16x16x32_bf16 v[84:87], v[176:179], v[160:163], 0
	v_mfma_f32_16x16x32_bf16 v[80:83], v[192:195], v[160:163], 0
	v_mfma_f32_16x16x32_bf16 v[68:71], v[176:179], v[168:171], 0
	v_mfma_f32_16x16x32_bf16 v[64:67], v[192:195], v[168:171], 0
	v_mfma_f32_16x16x32_bf16 v[116:119], v[180:183], v[148:151], v[116:119]
	s_waitcnt lgkmcnt(0)
	v_mfma_f32_16x16x32_bf16 v[112:115], v[196:199], v[148:151], v[112:115]
	v_mfma_f32_16x16x32_bf16 v[100:103], v[180:183], v[156:159], v[100:103]
	v_mfma_f32_16x16x32_bf16 v[96:99], v[196:199], v[156:159], v[96:99]
	v_mfma_f32_16x16x32_bf16 v[84:87], v[180:183], v[164:167], v[84:87]
	v_mfma_f32_16x16x32_bf16 v[80:83], v[196:199], v[164:167], v[80:83]
	v_mfma_f32_16x16x32_bf16 v[68:71], v[180:183], v[172:175], v[68:71]
	v_mfma_f32_16x16x32_bf16 v[64:67], v[196:199], v[172:175], v[64:67]
	s_setprio 0
	s_and_b32 s29, s19, 0xffff
	s_mov_b32 s30, s10
	s_mov_b32 s31, s11
	s_mov_b32 m0, s49
	s_barrier
; #define PG8_STAGE(bufoff, gbase, voff) do { const __amdgpu_buffer_rsrc_t _r = __builtin_amdgcn_make_buffer_rsrc((void*)(gbase), (short)0, 0x7fffffff, 0x00020000); _Pragma("unroll") for (int _i = 0; _i < 2; ++_i) \
;         __builtin_amdgcn_raw_ptr_buffer_load_lds(_r, (LAS unsigned*)(lds + (bufoff) + ldsw + _i * 8192), 16, (int)(voff)[_i], 0, 0, 0); } while (0)
; #define PG8_LDA(dst, b, h) do { _Pragma("unroll") for (int m = 0; m < 4; ++m) _Pragma("unroll") for (int k = 0; k < 2; ++k) dst[m][k] = *(const LAS bf16x8*)(lds + PG8_SA(b, h) + aoff + m * 2048 + k * 1024); } while (0)
; #define PG8_MMA(ai, bj, At, Bt) do { __builtin_amdgcn_s_setprio(1); _Pragma("unroll") for (int k = 0; k < 2; ++k) _Pragma("unroll") for (int m = 0; m < 4; ++m) _Pragma("unroll") for (int n = 0; n < ((bj) == 1 ? NB1 : 2); ++n) \
;         acc[ai][bj][m][n] = __builtin_amdgcn_mfma_f32_16x16x32_bf16(Bt[n][k], At[m][k], acc[ai][bj][m][n], 0, 0, 0); __builtin_amdgcn_s_setprio(0); } while (0)
; #define PG8_WAIT_V(n) asm volatile("s_waitcnt vmcnt(" #n ")" ::: "memory")
; #define PG8_WAIT_L(n) asm volatile("s_waitcnt lgkmcnt(" #n ")" ::: "memory")
; #define PG8_BAR __builtin_amdgcn_s_barrier()
; #define PG8_SCHED __builtin_amdgcn_sched_barrier(0)
;     ...
;             PG8_LDA(At, 0, 1); PG8_STAGE(PG8_SA(0, 0), a2, voffA);
;             PG8_BAR; PG8_WAIT_L(0); PG8_MMA(1, 0, At, B0); PG8_BAR; PG8_SCHED;
;             PG8_STAGE(PG8_SB(0, 1), b2 + hstepB, voffB);
;             PG8_WAIT_V(6); PG8_BAR; PG8_MMA(1, 1, At, B1); PG8_BAR;
	ds_read_b128 v[144:147], v228 offset:16384
	ds_read_b128 v[148:151], v228 offset:17408
	ds_read_b128 v[152:155], v228 offset:18432
	ds_read_b128 v[156:159], v228 offset:19456
	ds_read_b128 v[160:163], v228 offset:20480
	ds_read_b128 v[164:167], v228 offset:21504
	ds_read_b128 v[168:171], v228 offset:22528
	ds_read_b128 v[172:175], v228 offset:23552
	buffer_load_dwordx4 v222, s[28:31], 0 offen lds
	s_mov_b32 m0, s52
	s_nop 0
	buffer_load_dwordx4 v224, s[28:31], 0 offen lds
	s_barrier
	s_waitcnt lgkmcnt(0)
	s_setprio 1
	s_waitcnt lgkmcnt(7)
	v_mfma_f32_16x16x32_bf16 v[60:63], v[128:131], v[144:147], 0
	v_mfma_f32_16x16x32_bf16 v[56:59], v[136:139], v[144:147], 0
	s_waitcnt lgkmcnt(5)
	v_mfma_f32_16x16x32_bf16 v[44:47], v[128:131], v[152:155], 0
	v_mfma_f32_16x16x32_bf16 v[40:43], v[136:139], v[152:155], 0
	s_waitcnt lgkmcnt(3)
	v_mfma_f32_16x16x32_bf16 v[28:31], v[128:131], v[160:163], 0
	v_mfma_f32_16x16x32_bf16 v[24:27], v[136:139], v[160:163], 0
	s_waitcnt lgkmcnt(1)
	v_mfma_f32_16x16x32_bf16 v[12:15], v[128:131], v[168:171], 0
	v_mfma_f32_16x16x32_bf16 v[8:11], v[136:139], v[168:171], 0
	v_mfma_f32_16x16x32_bf16 v[60:63], v[132:135], v[148:151], v[60:63]
	v_mfma_f32_16x16x32_bf16 v[56:59], v[140:143], v[148:151], v[56:59]
	v_mfma_f32_16x16x32_bf16 v[44:47], v[132:135], v[156:159], v[44:47]
	v_mfma_f32_16x16x32_bf16 v[40:43], v[140:143], v[156:159], v[40:43]
	v_mfma_f32_16x16x32_bf16 v[28:31], v[132:135], v[164:167], v[28:31]
	v_mfma_f32_16x16x32_bf16 v[24:27], v[140:143], v[164:167], v[24:27]
	s_waitcnt lgkmcnt(0)
	v_mfma_f32_16x16x32_bf16 v[12:15], v[132:135], v[172:175], v[12:15]
	v_mfma_f32_16x16x32_bf16 v[8:11], v[140:143], v[172:175], v[8:11]
	s_setprio 0
	s_barrier
	s_add_u32 s8, s24, s38
	s_addc_u32 s23, s18, s39
	s_and_b32 s9, s23, 0xffff
	s_mov_b32 m0, s53
	s_nop 0
	buffer_load_dwordx4 v223, s[8:11], 0 offen lds
	s_mov_b32 m0, s54
	s_nop 0
	buffer_load_dwordx4 v225, s[8:11], 0 offen lds
	s_waitcnt vmcnt(6)
	s_barrier
	s_setprio 1
	v_mfma_f32_16x16x32_bf16 v[52:55], v[176:179], v[144:147], 0
	v_mfma_f32_16x16x32_bf16 v[48:51], v[192:195], v[144:147], 0
	v_mfma_f32_16x16x32_bf16 v[36:39], v[176:179], v[152:155], 0
	v_mfma_f32_16x16x32_bf16 v[32:35], v[192:195], v[152:155], 0
	v_mfma_f32_16x16x32_bf16 v[20:23], v[176:179], v[160:163], 0
	v_mfma_f32_16x16x32_bf16 v[16:19], v[192:195], v[160:163], 0
	v_mfma_f32_16x16x32_bf16 v[4:7], v[176:179], v[168:171], 0
	v_mfma_f32_16x16x32_bf16 v[0:3], v[192:195], v[168:171], 0
	v_mfma_f32_16x16x32_bf16 v[52:55], v[180:183], v[148:151], v[52:55]
	v_mfma_f32_16x16x32_bf16 v[48:51], v[196:199], v[148:151], v[48:51]
	v_mfma_f32_16x16x32_bf16 v[36:39], v[180:183], v[156:159], v[36:39]
	v_mfma_f32_16x16x32_bf16 v[32:35], v[196:199], v[156:159], v[32:35]
	v_mfma_f32_16x16x32_bf16 v[20:23], v[180:183], v[164:167], v[20:23]
	v_mfma_f32_16x16x32_bf16 v[16:19], v[196:199], v[164:167], v[16:19]
	v_mfma_f32_16x16x32_bf16 v[4:7], v[180:183], v[172:175], v[4:7]
	v_mfma_f32_16x16x32_bf16 v[0:3], v[196:199], v[172:175], v[0:3]
	s_setprio 0
	s_barrier
	s_branch .Lkmid_1066

; #define PG8_STAGE(bufoff, gbase, voff) do { const __amdgpu_buffer_rsrc_t _r = __builtin_amdgcn_make_buffer_rsrc((void*)(gbase), (short)0, 0x7fffffff, 0x00020000); _Pragma("unroll") for (int _i = 0; _i < 2; ++_i) \
;         __builtin_amdgcn_raw_ptr_buffer_load_lds(_r, (LAS unsigned*)(lds + (bufoff) + ldsw + _i * 8192), 16, (int)(voff)[_i], 0, 0, 0); } while (0)
; #define PG8_LDA(dst, b, h) do { _Pragma("unroll") for (int m = 0; m < 4; ++m) _Pragma("unroll") for (int k = 0; k < 2; ++k) dst[m][k] = *(const LAS bf16x8*)(lds + PG8_SA(b, h) + aoff + m * 2048 + k * 1024); } while (0)
; #define PG8_LDB(dst, b, h) do { _Pragma("unroll") for (int n = 0; n < 2; ++n) _Pragma("unroll") for (int k = 0; k < 2; ++k) dst[n][k] = *(const LAS bf16x8*)(lds + PG8_SB(b, h) + boff + n * 2048 + k * 1024); } while (0)
; #define PG8_MMA(ai, bj, At, Bt) do { __builtin_amdgcn_s_setprio(1); _Pragma("unroll") for (int k = 0; k < 2; ++k) _Pragma("unroll") for (int m = 0; m < 4; ++m) _Pragma("unroll") for (int n = 0; n < ((bj) == 1 ? NB1 : 2); ++n) \
;         acc[ai][bj][m][n] = __builtin_amdgcn_mfma_f32_16x16x32_bf16(Bt[n][k], At[m][k], acc[ai][bj][m][n], 0, 0, 0); __builtin_amdgcn_s_setprio(0); } while (0)
; #define PG8_WAIT_L(n) asm volatile("s_waitcnt lgkmcnt(" #n ")" ::: "memory")
; #define PG8_BAR __builtin_amdgcn_s_barrier()
; #define PG8_SCHED __builtin_amdgcn_sched_barrier(0)
;     ...
;             PG8_LDB(B0, 1, 0); PG8_SCHED; PG8_LDA(At, 1, 0); PG8_STAGE(PG8_SA(0, 1), a2 + hstepA, voffA);
;             PG8_WAIT_L(8); PG8_BAR; PG8_WAIT_L(0); PG8_MMA(0, 0, At, B0); PG8_BAR; PG8_SCHED;
;             PG8_LDB(B1, 1, 1); PG8_STAGE(PG8_SB(1, 0), b3, voffB);
;             PG8_BAR; PG8_WAIT_L(0); PG8_MMA(0, 1, At, B1); PG8_BAR;
;             PG8_LDA(At, 1, 1); PG8_STAGE(PG8_SA(1, 0), a3, voffA);
;             PG8_BAR; PG8_WAIT_L(0); PG8_MMA(1, 0, At, B0); PG8_BAR; PG8_SCHED;
.Lkmid_1066:
	ds_read_b128 v[128:131], v230
	ds_read_b128 v[132:135], v230 offset:1024
	ds_read_b128 v[136:139], v230 offset:2048
	ds_read_b128 v[140:143], v230 offset:3072
	s_add_u32 s28, s28, s36
	s_addc_u32 s9, s19, s37
	s_and_b32 s29, s9, 0xffff
	s_mov_b32 m0, s55
	ds_read_b128 v[144:147], v228 offset:32768
	ds_read_b128 v[148:151], v228 offset:33792
	ds_read_b128 v[152:155], v228 offset:34816
	ds_read_b128 v[156:159], v228 offset:35840
	ds_read_b128 v[160:163], v228 offset:36864
	ds_read_b128 v[164:167], v228 offset:37888
	ds_read_b128 v[168:171], v228 offset:38912
	ds_read_b128 v[172:175], v228 offset:39936
	buffer_load_dwordx4 v222, s[28:31], 0 offen lds
	s_mov_b32 m0, s56
	s_nop 0
	buffer_load_dwordx4 v224, s[28:31], 0 offen lds
	s_waitcnt lgkmcnt(8)
	s_barrier
	s_waitcnt lgkmcnt(0)
	s_setprio 1
	s_waitcnt lgkmcnt(7)
	v_mfma_f32_16x16x32_bf16 v[120:123], v[128:131], v[144:147], v[120:123]
	v_mfma_f32_16x16x32_bf16 v[124:127], v[136:139], v[144:147], v[124:127]
	s_waitcnt lgkmcnt(5)
	v_mfma_f32_16x16x32_bf16 v[108:111], v[128:131], v[152:155], v[108:111]
	v_mfma_f32_16x16x32_bf16 v[104:107], v[136:139], v[152:155], v[104:107]
	s_waitcnt lgkmcnt(3)
	v_mfma_f32_16x16x32_bf16 v[92:95], v[128:131], v[160:163], v[92:95]
	v_mfma_f32_16x16x32_bf16 v[88:91], v[136:139], v[160:163], v[88:91]
	s_waitcnt lgkmcnt(1)
	v_mfma_f32_16x16x32_bf16 v[76:79], v[128:131], v[168:171], v[76:79]
	v_mfma_f32_16x16x32_bf16 v[72:75], v[136:139], v[168:171], v[72:75]
	v_mfma_f32_16x16x32_bf16 v[120:123], v[132:135], v[148:151], v[120:123]
	v_mfma_f32_16x16x32_bf16 v[124:127], v[140:143], v[148:151], v[124:127]
	v_mfma_f32_16x16x32_bf16 v[108:111], v[132:135], v[156:159], v[108:111]
	v_mfma_f32_16x16x32_bf16 v[104:107], v[140:143], v[156:159], v[104:107]
	v_mfma_f32_16x16x32_bf16 v[92:95], v[132:135], v[164:167], v[92:95]
	v_mfma_f32_16x16x32_bf16 v[88:91], v[140:143], v[164:167], v[88:91]
	s_waitcnt lgkmcnt(0)
	v_mfma_f32_16x16x32_bf16 v[76:79], v[132:135], v[172:175], v[76:79]
	v_mfma_f32_16x16x32_bf16 v[72:75], v[140:143], v[172:175], v[72:75]
	s_setprio 0
	s_barrier
	s_add_u32 s24, s24, 0x80
	s_addc_u32 s9, s18, 0
	s_and_b32 s25, s9, 0xffff
	s_mov_b32 m0, s59
	ds_read_b128 v[176:179], v231
	ds_read_b128 v[180:183], v231 offset:1024
	ds_read_b128 v[192:195], v231 offset:2048
	ds_read_b128 v[196:199], v231 offset:3072
	buffer_load_dwordx4 v223, s[24:27], 0 offen lds
	s_mov_b32 m0, s64
	s_nop 0
	buffer_load_dwordx4 v225, s[24:27], 0 offen lds
	s_barrier
	s_waitcnt lgkmcnt(0)
	s_setprio 1
	s_waitcnt lgkmcnt(3)
	v_mfma_f32_16x16x32_bf16 v[116:119], v[176:179], v[144:147], v[116:119]
	s_waitcnt lgkmcnt(1)
	v_mfma_f32_16x16x32_bf16 v[112:115], v[192:195], v[144:147], v[112:115]
	v_mfma_f32_16x16x32_bf16 v[100:103], v[176:179], v[152:155], v[100:103]
	v_mfma_f32_16x16x32_bf16 v[96:99], v[192:195], v[152:155], v[96:99]
	v_mfma_f32_16x16x32_bf16 v[84:87], v[176:179], v[160:163], v[84:87]
	v_mfma_f32_16x16x32_bf16 v[80:83], v[192:195], v[160:163], v[80:83]
	v_mfma_f32_16x16x32_bf16 v[68:71], v[176:179], v[168:171], v[68:71]
	v_mfma_f32_16x16x32_bf16 v[64:67], v[192:195], v[168:171], v[64:67]
	v_mfma_f32_16x16x32_bf16 v[116:119], v[180:183], v[148:151], v[116:119]
	s_waitcnt lgkmcnt(0)
	v_mfma_f32_16x16x32_bf16 v[112:115], v[196:199], v[148:151], v[112:115]
	v_mfma_f32_16x16x32_bf16 v[100:103], v[180:183], v[156:159], v[100:103]
	v_mfma_f32_16x16x32_bf16 v[96:99], v[196:199], v[156:159], v[96:99]
	v_mfma_f32_16x16x32_bf16 v[84:87], v[180:183], v[164:167], v[84:87]
	v_mfma_f32_16x16x32_bf16 v[80:83], v[196:199], v[164:167], v[80:83]
	v_mfma_f32_16x16x32_bf16 v[68:71], v[180:183], v[172:175], v[68:71]
	v_mfma_f32_16x16x32_bf16 v[64:67], v[196:199], v[172:175], v[64:67]
	s_setprio 0
	s_and_b32 s17, s17, 0xffff
	s_mov_b32 s18, s10
	s_mov_b32 s19, s11
	s_mov_b32 m0, s65
	s_barrier
; #define PG8_STAGE(bufoff, gbase, voff) do { const __amdgpu_buffer_rsrc_t _r = __builtin_amdgcn_make_buffer_rsrc((void*)(gbase), (short)0, 0x7fffffff, 0x00020000); _Pragma("unroll") for (int _i = 0; _i < 2; ++_i) \
;         __builtin_amdgcn_raw_ptr_buffer_load_lds(_r, (LAS unsigned*)(lds + (bufoff) + ldsw + _i * 8192), 16, (int)(voff)[_i], 0, 0, 0); } while (0)
; #define PG8_LDA(dst, b, h) do { _Pragma("unroll") for (int m = 0; m < 4; ++m) _Pragma("unroll") for (int k = 0; k < 2; ++k) dst[m][k] = *(const LAS bf16x8*)(lds + PG8_SA(b, h) + aoff + m * 2048 + k * 1024); } while (0)
; #define PG8_MMA(ai, bj, At, Bt) do { __builtin_amdgcn_s_setprio(1); _Pragma("unroll") for (int k = 0; k < 2; ++k) _Pragma("unroll") for (int m = 0; m < 4; ++m) _Pragma("unroll") for (int n = 0; n < ((bj) == 1 ? NB1 : 2); ++n) \
;         acc[ai][bj][m][n] = __builtin_amdgcn_mfma_f32_16x16x32_bf16(Bt[n][k], At[m][k], acc[ai][bj][m][n], 0, 0, 0); __builtin_amdgcn_s_setprio(0); } while (0)
; #define PG8_WAIT_V(n) asm volatile("s_waitcnt vmcnt(" #n ")" ::: "memory")
; #define PG8_WAIT_L(n) asm volatile("s_waitcnt lgkmcnt(" #n ")" ::: "memory")
; #define PG8_BAR __builtin_amdgcn_s_barrier()
; #define PG8_SCHED __builtin_amdgcn_sched_barrier(0)
;     ...
;             PG8_LDA(At, 1, 1); PG8_STAGE(PG8_SA(1, 0), a3, voffA);
;             PG8_BAR; PG8_WAIT_L(0); PG8_MMA(1, 0, At, B0); PG8_BAR; PG8_SCHED;
;             PG8_STAGE(PG8_SB(1, 1), b3 + hstepB, voffB);
;             PG8_WAIT_V(6); PG8_BAR; PG8_MMA(1, 1, At, B1); PG8_BAR;
;         }
	ds_read_b128 v[144:147], v228 offset:49152
	ds_read_b128 v[148:151], v228 offset:50176
	ds_read_b128 v[152:155], v228 offset:51200
	ds_read_b128 v[156:159], v228 offset:52224
	ds_read_b128 v[160:163], v228 offset:53248
	ds_read_b128 v[164:167], v228 offset:54272
	ds_read_b128 v[168:171], v228 offset:55296
	ds_read_b128 v[172:175], v228 offset:56320
	buffer_load_dwordx4 v222, s[16:19], 0 offen lds
	s_mov_b32 m0, s66
	s_nop 0
	buffer_load_dwordx4 v224, s[16:19], 0 offen lds
	s_barrier
	s_waitcnt lgkmcnt(0)
	s_setprio 1
	s_waitcnt lgkmcnt(7)
	v_mfma_f32_16x16x32_bf16 v[60:63], v[128:131], v[144:147], v[60:63]
	v_mfma_f32_16x16x32_bf16 v[56:59], v[136:139], v[144:147], v[56:59]
	s_waitcnt lgkmcnt(5)
	v_mfma_f32_16x16x32_bf16 v[44:47], v[128:131], v[152:155], v[44:47]
	v_mfma_f32_16x16x32_bf16 v[40:43], v[136:139], v[152:155], v[40:43]
	s_waitcnt lgkmcnt(3)
	v_mfma_f32_16x16x32_bf16 v[28:31], v[128:131], v[160:163], v[28:31]
	v_mfma_f32_16x16x32_bf16 v[24:27], v[136:139], v[160:163], v[24:27]
	s_waitcnt lgkmcnt(1)
	v_mfma_f32_16x16x32_bf16 v[12:15], v[128:131], v[168:171], v[12:15]
	v_mfma_f32_16x16x32_bf16 v[8:11], v[136:139], v[168:171], v[8:11]
	v_mfma_f32_16x16x32_bf16 v[60:63], v[132:135], v[148:151], v[60:63]
	v_mfma_f32_16x16x32_bf16 v[56:59], v[140:143], v[148:151], v[56:59]
	v_mfma_f32_16x16x32_bf16 v[44:47], v[132:135], v[156:159], v[44:47]
	v_mfma_f32_16x16x32_bf16 v[40:43], v[140:143], v[156:159], v[40:43]
	v_mfma_f32_16x16x32_bf16 v[28:31], v[132:135], v[164:167], v[28:31]
	v_mfma_f32_16x16x32_bf16 v[24:27], v[140:143], v[164:167], v[24:27]
	s_waitcnt lgkmcnt(0)
	v_mfma_f32_16x16x32_bf16 v[12:15], v[132:135], v[172:175], v[12:15]
	v_mfma_f32_16x16x32_bf16 v[8:11], v[140:143], v[172:175], v[8:11]
	s_setprio 0
	s_barrier
	s_add_u32 s8, s8, 0x80
	s_addc_u32 s9, s23, 0
	s_and_b32 s9, s9, 0xffff
	s_mov_b32 m0, s67
	s_nop 0
	buffer_load_dwordx4 v223, s[8:11], 0 offen lds
	s_mov_b32 m0, s70
	s_nop 0
	buffer_load_dwordx4 v225, s[8:11], 0 offen lds
	s_waitcnt vmcnt(6)
	s_barrier
	s_setprio 1
	v_mfma_f32_16x16x32_bf16 v[52:55], v[176:179], v[144:147], v[52:55]
	v_mfma_f32_16x16x32_bf16 v[48:51], v[192:195], v[144:147], v[48:51]
	v_mfma_f32_16x16x32_bf16 v[36:39], v[176:179], v[152:155], v[36:39]
	v_mfma_f32_16x16x32_bf16 v[32:35], v[192:195], v[152:155], v[32:35]
	v_mfma_f32_16x16x32_bf16 v[20:23], v[176:179], v[160:163], v[20:23]
	v_mfma_f32_16x16x32_bf16 v[16:19], v[192:195], v[160:163], v[16:19]
	v_mfma_f32_16x16x32_bf16 v[4:7], v[176:179], v[168:171], v[4:7]
	v_mfma_f32_16x16x32_bf16 v[0:3], v[192:195], v[168:171], v[0:3]
	v_mfma_f32_16x16x32_bf16 v[52:55], v[180:183], v[148:151], v[52:55]
	v_mfma_f32_16x16x32_bf16 v[48:51], v[196:199], v[148:151], v[48:51]
	v_mfma_f32_16x16x32_bf16 v[36:39], v[180:183], v[156:159], v[36:39]
	v_mfma_f32_16x16x32_bf16 v[32:35], v[196:199], v[156:159], v[32:35]
	v_mfma_f32_16x16x32_bf16 v[20:23], v[180:183], v[164:167], v[20:23]
	v_mfma_f32_16x16x32_bf16 v[16:19], v[196:199], v[164:167], v[16:19]
	v_mfma_f32_16x16x32_bf16 v[4:7], v[180:183], v[172:175], v[4:7]
	v_mfma_f32_16x16x32_bf16 v[0:3], v[196:199], v[172:175], v[0:3]
	s_setprio 0
	s_add_u32 s79, s79, 0x100
	s_addc_u32 s80, s80, 0
	s_add_u32 s81, s81, 0x100
	s_addc_u32 s82, s82, 0
	s_cmp_ge_i32 s22, s57
	s_mov_b32 s8, s22
	s_barrier
	s_cbranch_scc0 .LBB0_1066

;     ...
; #pragma unroll
;     for (int a = 0; a < 2; ++a)
; #pragma unroll
;         for (int b = 0; b < 2; ++b)
; #pragma unroll
;             for (int m = 0; m < 4; ++m)
; #pragma unroll
;                 for (int n = 0; n < 2; ++n) acc[a][b][m][n] = (f32x4){0.f, 0.f, 0.f, 0.f};
.Lkzero_507:
	v_mov_b32_e32 v63, 0
	v_mov_b32_e32 v62, v63
	v_mov_b32_e32 v61, v63
	v_mov_b32_e32 v60, v63
	v_mov_b32_e32 v59, v63
	v_mov_b32_e32 v58, v63
	v_mov_b32_e32 v57, v63
	v_mov_b32_e32 v56, v63
	v_mov_b32_e32 v55, v63
	v_mov_b32_e32 v54, v63
	v_mov_b32_e32 v53, v63
	v_mov_b32_e32 v52, v63
	v_mov_b32_e32 v51, v63
	v_mov_b32_e32 v50, v63
	v_mov_b32_e32 v49, v63
	v_mov_b32_e32 v48, v63
	v_mov_b32_e32 v47, v63
	v_mov_b32_e32 v46, v63
	v_mov_b32_e32 v45, v63
	v_mov_b32_e32 v44, v63
	v_mov_b32_e32 v43, v63
	v_mov_b32_e32 v42, v63
	v_mov_b32_e32 v41, v63
	v_mov_b32_e32 v40, v63
	v_mov_b32_e32 v39, v63
	v_mov_b32_e32 v38, v63
	v_mov_b32_e32 v37, v63
	v_mov_b32_e32 v36, v63
	v_mov_b32_e32 v35, v63
	v_mov_b32_e32 v34, v63
	v_mov_b32_e32 v33, v63
	v_mov_b32_e32 v32, v63
	v_mov_b32_e32 v31, v63
	v_mov_b32_e32 v30, v63
	v_mov_b32_e32 v29, v63
	v_mov_b32_e32 v28, v63
	v_mov_b32_e32 v27, v63
	v_mov_b32_e32 v26, v63
	v_mov_b32_e32 v25, v63
	v_mov_b32_e32 v24, v63
	v_mov_b32_e32 v23, v63
	v_mov_b32_e32 v22, v63
	v_mov_b32_e32 v21, v63
	v_mov_b32_e32 v20, v63
	v_mov_b32_e32 v19, v63
	v_mov_b32_e32 v18, v63
	v_mov_b32_e32 v17, v63
	v_mov_b32_e32 v16, v63
	v_mov_b32_e32 v15, v63
	v_mov_b32_e32 v14, v63
	v_mov_b32_e32 v13, v63
	v_mov_b32_e32 v12, v63
	v_mov_b32_e32 v11, v63
	v_mov_b32_e32 v10, v63
	v_mov_b32_e32 v9, v63
	v_mov_b32_e32 v8, v63
	v_mov_b32_e32 v7, v63
	v_mov_b32_e32 v6, v63
	v_mov_b32_e32 v5, v63
	v_mov_b32_e32 v4, v63
	v_mov_b32_e32 v3, v63
	v_mov_b32_e32 v2, v63
	v_mov_b32_e32 v1, v63
	v_mov_b32_e32 v0, v63
	s_branch .LBB0_502
.Lkzero_575:
	v_mov_b32_e32 v135, 0
	v_mov_b32_e32 v134, v135
	v_mov_b32_e32 v133, v135
	v_mov_b32_e32 v132, v135
	v_mov_b32_e32 v123, v135
	v_mov_b32_e32 v122, v135
	v_mov_b32_e32 v121, v135
	v_mov_b32_e32 v120, v135
	v_mov_b32_e32 v119, v135
	v_mov_b32_e32 v118, v135
	v_mov_b32_e32 v117, v135
	v_mov_b32_e32 v116, v135
	v_mov_b32_e32 v115, v135
	v_mov_b32_e32 v114, v135
	v_mov_b32_e32 v113, v135
	v_mov_b32_e32 v112, v135
	v_mov_b32_e32 v95, v135
	v_mov_b32_e32 v94, v135
	v_mov_b32_e32 v93, v135
	v_mov_b32_e32 v92, v135
	v_mov_b32_e32 v91, v135
	v_mov_b32_e32 v90, v135
	v_mov_b32_e32 v89, v135
	v_mov_b32_e32 v88, v135
	v_mov_b32_e32 v79, v135
	v_mov_b32_e32 v78, v135
	v_mov_b32_e32 v77, v135
	v_mov_b32_e32 v76, v135
	v_mov_b32_e32 v75, v135
	v_mov_b32_e32 v74, v135
	v_mov_b32_e32 v73, v135
	v_mov_b32_e32 v72, v135
	v_mov_b32_e32 v131, v135
	v_mov_b32_e32 v130, v135
	v_mov_b32_e32 v129, v135
	v_mov_b32_e32 v128, v135
	v_mov_b32_e32 v127, v135
	v_mov_b32_e32 v126, v135
	v_mov_b32_e32 v125, v135
	v_mov_b32_e32 v124, v135
	v_mov_b32_e32 v111, v135
	v_mov_b32_e32 v110, v135
	v_mov_b32_e32 v109, v135
	v_mov_b32_e32 v108, v135
	v_mov_b32_e32 v107, v135
	v_mov_b32_e32 v106, v135
	v_mov_b32_e32 v105, v135
	v_mov_b32_e32 v104, v135
	v_mov_b32_e32 v87, v135
	v_mov_b32_e32 v86, v135
	v_mov_b32_e32 v85, v135
	v_mov_b32_e32 v84, v135
	v_mov_b32_e32 v83, v135
	v_mov_b32_e32 v82, v135
	v_mov_b32_e32 v81, v135
	v_mov_b32_e32 v80, v135
	v_mov_b32_e32 v71, v135
	v_mov_b32_e32 v70, v135
	v_mov_b32_e32 v69, v135
	v_mov_b32_e32 v68, v135
	v_mov_b32_e32 v67, v135
	v_mov_b32_e32 v66, v135
	v_mov_b32_e32 v65, v135
	v_mov_b32_e32 v64, v135
	v_mov_b32_e32 v63, v135
	v_mov_b32_e32 v62, v135
	v_mov_b32_e32 v61, v135
	v_mov_b32_e32 v60, v135
	v_mov_b32_e32 v59, v135
	v_mov_b32_e32 v58, v135
	v_mov_b32_e32 v57, v135
	v_mov_b32_e32 v56, v135
	v_mov_b32_e32 v47, v135
	v_mov_b32_e32 v46, v135
	v_mov_b32_e32 v45, v135
	v_mov_b32_e32 v44, v135
	v_mov_b32_e32 v43, v135
	v_mov_b32_e32 v42, v135
	v_mov_b32_e32 v41, v135
	v_mov_b32_e32 v40, v135
	v_mov_b32_e32 v31, v135
	v_mov_b32_e32 v30, v135
	v_mov_b32_e32 v29, v135
	v_mov_b32_e32 v28, v135
	v_mov_b32_e32 v27, v135
	v_mov_b32_e32 v26, v135
	v_mov_b32_e32 v25, v135
	v_mov_b32_e32 v24, v135
	v_mov_b32_e32 v15, v135
	v_mov_b32_e32 v14, v135
	v_mov_b32_e32 v13, v135
	v_mov_b32_e32 v12, v135
	v_mov_b32_e32 v11, v135
	v_mov_b32_e32 v10, v135
	v_mov_b32_e32 v9, v135
	v_mov_b32_e32 v8, v135
	v_mov_b32_e32 v55, v135
	v_mov_b32_e32 v54, v135
	v_mov_b32_e32 v53, v135
	v_mov_b32_e32 v52, v135
	v_mov_b32_e32 v51, v135
	v_mov_b32_e32 v50, v135
	v_mov_b32_e32 v49, v135
	v_mov_b32_e32 v48, v135
	v_mov_b32_e32 v39, v135
	v_mov_b32_e32 v38, v135
	v_mov_b32_e32 v37, v135
	v_mov_b32_e32 v36, v135
	v_mov_b32_e32 v35, v135
	v_mov_b32_e32 v34, v135
	v_mov_b32_e32 v33, v135
	v_mov_b32_e32 v32, v135
	v_mov_b32_e32 v23, v135
	v_mov_b32_e32 v22, v135
	v_mov_b32_e32 v21, v135
	v_mov_b32_e32 v20, v135
	v_mov_b32_e32 v19, v135
	v_mov_b32_e32 v18, v135
	v_mov_b32_e32 v17, v135
	v_mov_b32_e32 v16, v135
	v_mov_b32_e32 v7, v135
	v_mov_b32_e32 v6, v135
	v_mov_b32_e32 v5, v135
	v_mov_b32_e32 v4, v135
	v_mov_b32_e32 v3, v135
	v_mov_b32_e32 v2, v135
	v_mov_b32_e32 v1, v135
	v_mov_b32_e32 v0, v135
	s_branch .LBB0_568
;     ...
; #pragma unroll
;     for (int a = 0; a < 2; ++a)
; #pragma unroll
;         for (int b = 0; b < 2; ++b)
; #pragma unroll
;             for (int m = 0; m < 4; ++m)
; #pragma unroll
;                 for (int n = 0; n < 2; ++n) acc[a][b][m][n] = (f32x4){0.f, 0.f, 0.f, 0.f};
.Lkzero_627:
	v_mov_b32_e32 v115, 0
	v_mov_b32_e32 v114, v115
	v_mov_b32_e32 v113, v115
	v_mov_b32_e32 v112, v115
	v_mov_b32_e32 v119, v115
	v_mov_b32_e32 v118, v115
	v_mov_b32_e32 v117, v115
	v_mov_b32_e32 v116, v115
	v_mov_b32_e32 v103, v115
	v_mov_b32_e32 v102, v115
	v_mov_b32_e32 v101, v115
	v_mov_b32_e32 v100, v115
	v_mov_b32_e32 v99, v115
	v_mov_b32_e32 v98, v115
	v_mov_b32_e32 v97, v115
	v_mov_b32_e32 v96, v115
	v_mov_b32_e32 v87, v115
	v_mov_b32_e32 v86, v115
	v_mov_b32_e32 v85, v115
	v_mov_b32_e32 v84, v115
	v_mov_b32_e32 v83, v115
	v_mov_b32_e32 v82, v115
	v_mov_b32_e32 v81, v115
	v_mov_b32_e32 v80, v115
	v_mov_b32_e32 v71, v115
	v_mov_b32_e32 v70, v115
	v_mov_b32_e32 v69, v115
	v_mov_b32_e32 v68, v115
	v_mov_b32_e32 v67, v115
	v_mov_b32_e32 v66, v115
	v_mov_b32_e32 v65, v115
	v_mov_b32_e32 v64, v115
	v_mov_b32_e32 v127, v115
	v_mov_b32_e32 v126, v115
	v_mov_b32_e32 v125, v115
	v_mov_b32_e32 v124, v115
	v_mov_b32_e32 v123, v115
	v_mov_b32_e32 v122, v115
	v_mov_b32_e32 v121, v115
	v_mov_b32_e32 v120, v115
	v_mov_b32_e32 v111, v115
	v_mov_b32_e32 v110, v115
	v_mov_b32_e32 v109, v115
	v_mov_b32_e32 v108, v115
	v_mov_b32_e32 v107, v115
	v_mov_b32_e32 v106, v115
	v_mov_b32_e32 v105, v115
	v_mov_b32_e32 v104, v115
	v_mov_b32_e32 v95, v115
	v_mov_b32_e32 v94, v115
	v_mov_b32_e32 v93, v115
	v_mov_b32_e32 v92, v115
	v_mov_b32_e32 v91, v115
	v_mov_b32_e32 v90, v115
	v_mov_b32_e32 v89, v115
	v_mov_b32_e32 v88, v115
	v_mov_b32_e32 v79, v115
	v_mov_b32_e32 v78, v115
	v_mov_b32_e32 v77, v115
	v_mov_b32_e32 v76, v115
	v_mov_b32_e32 v75, v115
	v_mov_b32_e32 v74, v115
	v_mov_b32_e32 v73, v115
	v_mov_b32_e32 v72, v115
	v_mov_b32_e32 v55, v115
	v_mov_b32_e32 v54, v115
	v_mov_b32_e32 v53, v115
	v_mov_b32_e32 v52, v115
	v_mov_b32_e32 v51, v115
	v_mov_b32_e32 v50, v115
	v_mov_b32_e32 v49, v115
	v_mov_b32_e32 v48, v115
	v_mov_b32_e32 v39, v115
	v_mov_b32_e32 v38, v115
	v_mov_b32_e32 v37, v115
	v_mov_b32_e32 v36, v115
	v_mov_b32_e32 v35, v115
	v_mov_b32_e32 v34, v115
	v_mov_b32_e32 v33, v115
	v_mov_b32_e32 v32, v115
	v_mov_b32_e32 v23, v115
	v_mov_b32_e32 v22, v115
	v_mov_b32_e32 v21, v115
	v_mov_b32_e32 v20, v115
	v_mov_b32_e32 v19, v115
	v_mov_b32_e32 v18, v115
	v_mov_b32_e32 v17, v115
	v_mov_b32_e32 v16, v115
	v_mov_b32_e32 v7, v115
	v_mov_b32_e32 v6, v115
	v_mov_b32_e32 v5, v115
	v_mov_b32_e32 v4, v115
	v_mov_b32_e32 v3, v115
	v_mov_b32_e32 v2, v115
	v_mov_b32_e32 v1, v115
	v_mov_b32_e32 v0, v115
	v_mov_b32_e32 v63, v115
	v_mov_b32_e32 v62, v115
	v_mov_b32_e32 v61, v115
	v_mov_b32_e32 v60, v115
	v_mov_b32_e32 v59, v115
	v_mov_b32_e32 v58, v115
	v_mov_b32_e32 v57, v115
	v_mov_b32_e32 v56, v115
	v_mov_b32_e32 v47, v115
	v_mov_b32_e32 v46, v115
	v_mov_b32_e32 v45, v115
	v_mov_b32_e32 v44, v115
	v_mov_b32_e32 v43, v115
	v_mov_b32_e32 v42, v115
	v_mov_b32_e32 v41, v115
	v_mov_b32_e32 v40, v115
	v_mov_b32_e32 v31, v115
	v_mov_b32_e32 v30, v115
	v_mov_b32_e32 v29, v115
	v_mov_b32_e32 v28, v115
	v_mov_b32_e32 v27, v115
	v_mov_b32_e32 v26, v115
	v_mov_b32_e32 v25, v115
	v_mov_b32_e32 v24, v115
	v_mov_b32_e32 v15, v115
	v_mov_b32_e32 v14, v115
	v_mov_b32_e32 v13, v115
	v_mov_b32_e32 v12, v115
	v_mov_b32_e32 v11, v115
	v_mov_b32_e32 v10, v115
	v_mov_b32_e32 v9, v115
	v_mov_b32_e32 v8, v115
	s_branch .LBB0_629
.Lkzero_690:
	v_mov_b32_e32 v155, 0
	v_mov_b32_e32 v154, v155
	v_mov_b32_e32 v153, v155
	v_mov_b32_e32 v152, v155
	v_mov_b32_e32 v147, v155
	v_mov_b32_e32 v146, v155
	v_mov_b32_e32 v145, v155
	v_mov_b32_e32 v144, v155
	v_mov_b32_e32 v127, v155
	v_mov_b32_e32 v126, v155
	v_mov_b32_e32 v125, v155
	v_mov_b32_e32 v124, v155
	v_mov_b32_e32 v123, v155
	v_mov_b32_e32 v122, v155
	v_mov_b32_e32 v121, v155
	v_mov_b32_e32 v120, v155
	v_mov_b32_e32 v111, v155
	v_mov_b32_e32 v110, v155
	v_mov_b32_e32 v109, v155
	v_mov_b32_e32 v108, v155
	v_mov_b32_e32 v107, v155
	v_mov_b32_e32 v106, v155
	v_mov_b32_e32 v105, v155
	v_mov_b32_e32 v104, v155
	v_mov_b32_e32 v87, v155
	v_mov_b32_e32 v86, v155
	v_mov_b32_e32 v85, v155
	v_mov_b32_e32 v84, v155
	v_mov_b32_e32 v83, v155
	v_mov_b32_e32 v82, v155
	v_mov_b32_e32 v81, v155
	v_mov_b32_e32 v80, v155
	v_mov_b32_e32 v159, v155
	v_mov_b32_e32 v158, v155
	v_mov_b32_e32 v157, v155
	v_mov_b32_e32 v156, v155
	v_mov_b32_e32 v151, v155
	v_mov_b32_e32 v150, v155
	v_mov_b32_e32 v149, v155
	v_mov_b32_e32 v148, v155
	v_mov_b32_e32 v119, v155
	v_mov_b32_e32 v118, v155
	v_mov_b32_e32 v117, v155
	v_mov_b32_e32 v116, v155
	v_mov_b32_e32 v115, v155
	v_mov_b32_e32 v114, v155
	v_mov_b32_e32 v113, v155
	v_mov_b32_e32 v112, v155
	v_mov_b32_e32 v103, v155
	v_mov_b32_e32 v102, v155
	v_mov_b32_e32 v101, v155
	v_mov_b32_e32 v100, v155
	v_mov_b32_e32 v99, v155
	v_mov_b32_e32 v98, v155
	v_mov_b32_e32 v97, v155
	v_mov_b32_e32 v96, v155
	v_mov_b32_e32 v71, v155
	v_mov_b32_e32 v70, v155
	v_mov_b32_e32 v69, v155
	v_mov_b32_e32 v68, v155
	v_mov_b32_e32 v67, v155
	v_mov_b32_e32 v66, v155
	v_mov_b32_e32 v65, v155
	v_mov_b32_e32 v64, v155
	v_mov_b32_e32 v63, v155
	v_mov_b32_e32 v62, v155
	v_mov_b32_e32 v61, v155
	v_mov_b32_e32 v60, v155
	v_mov_b32_e32 v55, v155
	v_mov_b32_e32 v54, v155
	v_mov_b32_e32 v53, v155
	v_mov_b32_e32 v52, v155
	v_mov_b32_e32 v47, v155
	v_mov_b32_e32 v46, v155
	v_mov_b32_e32 v45, v155
	v_mov_b32_e32 v44, v155
	v_mov_b32_e32 v43, v155
	v_mov_b32_e32 v42, v155
	v_mov_b32_e32 v41, v155
	v_mov_b32_e32 v40, v155
	v_mov_b32_e32 v31, v155
	v_mov_b32_e32 v30, v155
	v_mov_b32_e32 v29, v155
	v_mov_b32_e32 v28, v155
	v_mov_b32_e32 v27, v155
	v_mov_b32_e32 v26, v155
	v_mov_b32_e32 v25, v155
	v_mov_b32_e32 v24, v155
	v_mov_b32_e32 v15, v155
	v_mov_b32_e32 v14, v155
	v_mov_b32_e32 v13, v155
	v_mov_b32_e32 v12, v155
	v_mov_b32_e32 v11, v155
	v_mov_b32_e32 v10, v155
	v_mov_b32_e32 v9, v155
	v_mov_b32_e32 v8, v155
	v_mov_b32_e32 v59, v155
	v_mov_b32_e32 v58, v155
	v_mov_b32_e32 v57, v155
	v_mov_b32_e32 v56, v155
	v_mov_b32_e32 v51, v155
	v_mov_b32_e32 v50, v155
	v_mov_b32_e32 v49, v155
	v_mov_b32_e32 v48, v155
	v_mov_b32_e32 v39, v155
	v_mov_b32_e32 v38, v155
	v_mov_b32_e32 v37, v155
	v_mov_b32_e32 v36, v155
	v_mov_b32_e32 v35, v155
	v_mov_b32_e32 v34, v155
	v_mov_b32_e32 v33, v155
	v_mov_b32_e32 v32, v155
	v_mov_b32_e32 v23, v155
	v_mov_b32_e32 v22, v155
	v_mov_b32_e32 v21, v155
	v_mov_b32_e32 v20, v155
	v_mov_b32_e32 v19, v155
	v_mov_b32_e32 v18, v155
	v_mov_b32_e32 v17, v155
	v_mov_b32_e32 v16, v155
	v_mov_b32_e32 v7, v155
	v_mov_b32_e32 v6, v155
	v_mov_b32_e32 v5, v155
	v_mov_b32_e32 v4, v155
	v_mov_b32_e32 v3, v155
	v_mov_b32_e32 v2, v155
	v_mov_b32_e32 v1, v155
	v_mov_b32_e32 v0, v155
	s_branch .LBB0_692
;     ...
; #pragma unroll
;     for (int a = 0; a < 2; ++a)
; #pragma unroll
;         for (int b = 0; b < 2; ++b)
; #pragma unroll
;             for (int m = 0; m < 4; ++m)
; #pragma unroll
;                 for (int n = 0; n < 2; ++n) acc[a][b][m][n] = (f32x4){0.f, 0.f, 0.f, 0.f};
.Lkzero_772:
	v_mov_b32_e32 v123, 0
	v_mov_b32_e32 v122, v123
	v_mov_b32_e32 v121, v123
	v_mov_b32_e32 v120, v123
	v_mov_b32_e32 v127, v123
	v_mov_b32_e32 v126, v123
	v_mov_b32_e32 v125, v123
	v_mov_b32_e32 v124, v123
	v_mov_b32_e32 v111, v123
	v_mov_b32_e32 v110, v123
	v_mov_b32_e32 v109, v123
	v_mov_b32_e32 v108, v123
	v_mov_b32_e32 v107, v123
	v_mov_b32_e32 v106, v123
	v_mov_b32_e32 v105, v123
	v_mov_b32_e32 v104, v123
	v_mov_b32_e32 v95, v123
	v_mov_b32_e32 v94, v123
	v_mov_b32_e32 v93, v123
	v_mov_b32_e32 v92, v123
	v_mov_b32_e32 v91, v123
	v_mov_b32_e32 v90, v123
	v_mov_b32_e32 v89, v123
	v_mov_b32_e32 v88, v123
	v_mov_b32_e32 v79, v123
	v_mov_b32_e32 v78, v123
	v_mov_b32_e32 v77, v123
	v_mov_b32_e32 v76, v123
	v_mov_b32_e32 v75, v123
	v_mov_b32_e32 v74, v123
	v_mov_b32_e32 v73, v123
	v_mov_b32_e32 v72, v123
	v_mov_b32_e32 v119, v123
	v_mov_b32_e32 v118, v123
	v_mov_b32_e32 v117, v123
	v_mov_b32_e32 v116, v123
	v_mov_b32_e32 v115, v123
	v_mov_b32_e32 v114, v123
	v_mov_b32_e32 v113, v123
	v_mov_b32_e32 v112, v123
	v_mov_b32_e32 v103, v123
	v_mov_b32_e32 v102, v123
	v_mov_b32_e32 v101, v123
	v_mov_b32_e32 v100, v123
	v_mov_b32_e32 v99, v123
	v_mov_b32_e32 v98, v123
	v_mov_b32_e32 v97, v123
	v_mov_b32_e32 v96, v123
	v_mov_b32_e32 v87, v123
	v_mov_b32_e32 v86, v123
	v_mov_b32_e32 v85, v123
	v_mov_b32_e32 v84, v123
	v_mov_b32_e32 v83, v123
	v_mov_b32_e32 v82, v123
	v_mov_b32_e32 v81, v123
	v_mov_b32_e32 v80, v123
	v_mov_b32_e32 v71, v123
	v_mov_b32_e32 v70, v123
	v_mov_b32_e32 v69, v123
	v_mov_b32_e32 v68, v123
	v_mov_b32_e32 v67, v123
	v_mov_b32_e32 v66, v123
	v_mov_b32_e32 v65, v123
	v_mov_b32_e32 v64, v123
	v_mov_b32_e32 v63, v123
	v_mov_b32_e32 v62, v123
	v_mov_b32_e32 v61, v123
	v_mov_b32_e32 v60, v123
	v_mov_b32_e32 v59, v123
	v_mov_b32_e32 v58, v123
	v_mov_b32_e32 v57, v123
	v_mov_b32_e32 v56, v123
	v_mov_b32_e32 v47, v123
	v_mov_b32_e32 v46, v123
	v_mov_b32_e32 v45, v123
	v_mov_b32_e32 v44, v123
	v_mov_b32_e32 v43, v123
	v_mov_b32_e32 v42, v123
	v_mov_b32_e32 v41, v123
	v_mov_b32_e32 v40, v123
	v_mov_b32_e32 v31, v123
	v_mov_b32_e32 v30, v123
	v_mov_b32_e32 v29, v123
	v_mov_b32_e32 v28, v123
	v_mov_b32_e32 v27, v123
	v_mov_b32_e32 v26, v123
	v_mov_b32_e32 v25, v123
	v_mov_b32_e32 v24, v123
	v_mov_b32_e32 v15, v123
	v_mov_b32_e32 v14, v123
	v_mov_b32_e32 v13, v123
	v_mov_b32_e32 v12, v123
	v_mov_b32_e32 v11, v123
	v_mov_b32_e32 v10, v123
	v_mov_b32_e32 v9, v123
	v_mov_b32_e32 v8, v123
	v_mov_b32_e32 v55, v123
	v_mov_b32_e32 v54, v123
	v_mov_b32_e32 v53, v123
	v_mov_b32_e32 v52, v123
	v_mov_b32_e32 v51, v123
	v_mov_b32_e32 v50, v123
	v_mov_b32_e32 v49, v123
	v_mov_b32_e32 v48, v123
	v_mov_b32_e32 v39, v123
	v_mov_b32_e32 v38, v123
	v_mov_b32_e32 v37, v123
	v_mov_b32_e32 v36, v123
	v_mov_b32_e32 v35, v123
	v_mov_b32_e32 v34, v123
	v_mov_b32_e32 v33, v123
	v_mov_b32_e32 v32, v123
	v_mov_b32_e32 v23, v123
	v_mov_b32_e32 v22, v123
	v_mov_b32_e32 v21, v123
	v_mov_b32_e32 v20, v123
	v_mov_b32_e32 v19, v123
	v_mov_b32_e32 v18, v123
	v_mov_b32_e32 v17, v123
	v_mov_b32_e32 v16, v123
	v_mov_b32_e32 v7, v123
	v_mov_b32_e32 v6, v123
	v_mov_b32_e32 v5, v123
	v_mov_b32_e32 v4, v123
	v_mov_b32_e32 v3, v123
	v_mov_b32_e32 v2, v123
	v_mov_b32_e32 v1, v123
	v_mov_b32_e32 v0, v123
	s_branch .LBB0_773
.Lkzero_844:
	v_mov_b32_e32 v91, 0
	v_mov_b32_e32 v90, v91
	v_mov_b32_e32 v89, v91
	v_mov_b32_e32 v88, v91
	v_mov_b32_e32 v99, v91
	v_mov_b32_e32 v98, v91
	v_mov_b32_e32 v97, v91
	v_mov_b32_e32 v96, v91
	v_mov_b32_e32 v79, v91
	v_mov_b32_e32 v78, v91
	v_mov_b32_e32 v77, v91
	v_mov_b32_e32 v76, v91
	v_mov_b32_e32 v87, v91
	v_mov_b32_e32 v86, v91
	v_mov_b32_e32 v85, v91
	v_mov_b32_e32 v84, v91
	v_mov_b32_e32 v67, v91
	v_mov_b32_e32 v66, v91
	v_mov_b32_e32 v65, v91
	v_mov_b32_e32 v64, v91
	v_mov_b32_e32 v75, v91
	v_mov_b32_e32 v74, v91
	v_mov_b32_e32 v73, v91
	v_mov_b32_e32 v72, v91
	v_mov_b32_e32 v55, v91
	v_mov_b32_e32 v54, v91
	v_mov_b32_e32 v53, v91
	v_mov_b32_e32 v52, v91
	v_mov_b32_e32 v63, v91
	v_mov_b32_e32 v62, v91
	v_mov_b32_e32 v61, v91
	v_mov_b32_e32 v60, v91
	v_mov_b32_e32 v95, v91
	v_mov_b32_e32 v94, v91
	v_mov_b32_e32 v93, v91
	v_mov_b32_e32 v92, v91
	v_mov_b32_e32 v83, v91
	v_mov_b32_e32 v82, v91
	v_mov_b32_e32 v81, v91
	v_mov_b32_e32 v80, v91
	v_mov_b32_e32 v71, v91
	v_mov_b32_e32 v70, v91
	v_mov_b32_e32 v69, v91
	v_mov_b32_e32 v68, v91
	v_mov_b32_e32 v59, v91
	v_mov_b32_e32 v58, v91
	v_mov_b32_e32 v57, v91
	v_mov_b32_e32 v56, v91
	v_mov_b32_e32 v47, v91
	v_mov_b32_e32 v46, v91
	v_mov_b32_e32 v45, v91
	v_mov_b32_e32 v44, v91
	v_mov_b32_e32 v51, v91
	v_mov_b32_e32 v50, v91
	v_mov_b32_e32 v49, v91
	v_mov_b32_e32 v48, v91
	v_mov_b32_e32 v31, v91
	v_mov_b32_e32 v30, v91
	v_mov_b32_e32 v29, v91
	v_mov_b32_e32 v28, v91
	v_mov_b32_e32 v39, v91
	v_mov_b32_e32 v38, v91
	v_mov_b32_e32 v37, v91
	v_mov_b32_e32 v36, v91
	v_mov_b32_e32 v15, v91
	v_mov_b32_e32 v14, v91
	v_mov_b32_e32 v13, v91
	v_mov_b32_e32 v12, v91
	v_mov_b32_e32 v23, v91
	v_mov_b32_e32 v22, v91
	v_mov_b32_e32 v21, v91
	v_mov_b32_e32 v20, v91
	v_mov_b32_e32 v3, v91
	v_mov_b32_e32 v2, v91
	v_mov_b32_e32 v1, v91
	v_mov_b32_e32 v0, v91
	v_mov_b32_e32 v11, v91
	v_mov_b32_e32 v10, v91
	v_mov_b32_e32 v9, v91
	v_mov_b32_e32 v8, v91
	v_mov_b32_e32 v43, v91
	v_mov_b32_e32 v42, v91
	v_mov_b32_e32 v41, v91
	v_mov_b32_e32 v40, v91
	v_mov_b32_e32 v35, v91
	v_mov_b32_e32 v34, v91
	v_mov_b32_e32 v33, v91
	v_mov_b32_e32 v32, v91
	v_mov_b32_e32 v19, v91
	v_mov_b32_e32 v18, v91
	v_mov_b32_e32 v17, v91
	v_mov_b32_e32 v16, v91
	v_mov_b32_e32 v7, v91
	v_mov_b32_e32 v6, v91
	v_mov_b32_e32 v5, v91
	v_mov_b32_e32 v4, v91
	s_branch .LBB0_846
